# v15: load-segment head/tail/foot reorder (ds_reads first after barrier, scalar updates in MFMA shadow) + 8-byte phase of MFMA runs, on v12
# baseline (speedup 1.0000x reference)
; #define PG8_STAGE(bufoff, gbase, voff) do { _Pragma("unroll") for (int _i = 0; _i < 2; ++_i) \
;         __builtin_amdgcn_global_load_lds((const unsigned*)((const char*)(gbase) + (voff)[_i]), (PG8_LAS unsigned*)(lds + (bufoff) + ldsw + _i * 8192), 16, 0, 0); } while (0)
; #define PG8_LDA(dst, b, h) do { _Pragma("unroll") for (int m = 0; m < 4; ++m) _Pragma("unroll") for (int k = 0; k < 2; ++k) dst[m][k] = *(const PG8_LAS bf16x8*)(lds + PG8_SA(b, h) + aoff + m * 2048 + k * 1024); } while (0)
; #define PG8_LDB(dst, b, h) do { _Pragma("unroll") for (int n = 0; n < 2; ++n) _Pragma("unroll") for (int k = 0; k < 2; ++k) dst[n][k] = *(const PG8_LAS bf16x8*)(lds + PG8_SB(b, h) + boff + n * 2048 + k * 1024); } while (0)
; #define PG8_WAIT_V(n) asm volatile("s_waitcnt vmcnt(" #n ")" ::: "memory")
; #define PG8_WAIT_L(n) asm volatile("s_waitcnt lgkmcnt(" #n ")" ::: "memory")
; #define PG8_BAR __builtin_amdgcn_s_barrier()
; template <class Epi, class Sched, bool ALIGN_EPI = false, bool SP2 = false>
; __device__ __forceinline__ void gemm_phase(PG8_LAS unsigned char* lds, const Gemm g, const Sched& S, const Epi& E) {
;     ...
;         const bool has_next = S.next(ui + 1, nxt);
;         const char* nA = has_next ? (const char*)g.A + (size_t)nxt.pm * tstep + (size_t)nxt.kt0 * kstep : cA; const char* nB = has_next ? (const char*)g.Bt + (size_t)nxt.pn * tstep + (size_t)nxt.kt0 * kstep : cB;
;         const int nt = cur.nt;
;         for (int t = 0; t < nt; t += 2) {
;             const bool last = (t == nt - 2);
;             const char* a1 = cA + (size_t)(t + 1) * kstep;
;             const char* a2 = last ? nA : cA + (size_t)(t + 2) * kstep; const char* b2 = last ? nB : cB + (size_t)(t + 2) * kstep;
;             const char* a3 = a2 + kstep; const char* b3 = b2 + kstep;
;             if (last && has_next) S.a_ready(nxt);
;             if constexpr (SP2) {
;             PG8_LDB(B0, 0, 0); PG8_LDB(B1, 0, 1); PG8_SCHED; PG8_LDA(At, 0, 0); PG8_STAGE(PG8_SA(1, 1), a1 + hstep, voffA);
;             PG8_WAIT_V(8); PG8_WAIT_L(0); PG8_BAR; PG8_MMA(0, 0, At, B0); PG8_MMA(0, 1, At, B1); PG8_BAR; PG8_SCHED;
;             PG8_LDA(At, 0, 1); PG8_STAGE(PG8_SB(0, 0), b2, voffB); PG8_STAGE(PG8_SB(0, 1), b2 + hstep, voffB); PG8_STAGE(PG8_SA(0, 0), a2, voffA);
;             PG8_WAIT_V(8); PG8_WAIT_L(0); PG8_BAR; PG8_MMA(1, 0, At, B0); PG8_MMA(1, 1, At, B1); PG8_BAR; PG8_SCHED;
.LBB0_816:
	ds_read_b128 v[142:145], v198
	ds_read_b128 v[146:149], v198 offset:1024
	ds_read_b128 v[154:157], v198 offset:2048
	ds_read_b128 v[158:161], v198 offset:3072
	ds_read_b128 v[162:165], v198 offset:16384
	ds_read_b128 v[166:169], v198 offset:17408
	ds_read_b128 v[170:173], v198 offset:18432
	ds_read_b128 v[174:177], v198 offset:19456
	s_add_i32 m0, s9, 0xc000
	ds_read_b128 v[178:181], v153
	ds_read_b128 v[182:185], v153 offset:1024
	ds_read_b128 v[186:189], v153 offset:2048
	ds_read_b128 v[190:193], v153 offset:3072
	ds_read_b128 v[194:197], v153 offset:4096
	ds_read_b128 v[214:217], v153 offset:5120
	ds_read_b128 v[218:221], v153 offset:6144
	ds_read_b128 v[234:237], v153 offset:7168
	s_setprio 0
	s_add_u32 s0, s50, 0xfff00080
	s_addc_u32 s1, s51, -1
	s_add_i32 s61, 0, 0x10000
	s_cmp_eq_u32 s60, 60
	s_cselect_b32 s27, s47, s1
	s_cselect_b32 s26, s46, s0
	s_cselect_b32 s1, s49, s45
	s_cselect_b32 s0, s48, s43
	s_add_i32 s64, 0, 0x14000
	global_load_lds_dwordx4 v138, s[50:51]
	s_add_i32 m0, s9, 0xe000
	s_nop 0
	global_load_lds_dwordx4 v140, s[50:51]
	s_nop 0
	s_setprio 1
	s_waitcnt vmcnt(8)
	s_waitcnt lgkmcnt(0)
	s_barrier
	v_mfma_f32_16x16x32_bf16 v[128:131], v[142:145], v[178:181], v[128:131]
	v_mfma_f32_16x16x32_bf16 v[128:131], v[146:149], v[182:185], v[128:131]
	v_mfma_f32_16x16x32_bf16 v[124:127], v[154:157], v[178:181], v[124:127]
	v_mfma_f32_16x16x32_bf16 v[124:127], v[158:161], v[182:185], v[124:127]
	v_mfma_f32_16x16x32_bf16 v[108:111], v[154:157], v[186:189], v[108:111]
	v_mfma_f32_16x16x32_bf16 v[108:111], v[158:161], v[190:193], v[108:111]
	v_mfma_f32_16x16x32_bf16 v[116:119], v[142:145], v[186:189], v[116:119]
	v_mfma_f32_16x16x32_bf16 v[116:119], v[146:149], v[190:193], v[116:119]
	v_mfma_f32_16x16x32_bf16 v[100:103], v[142:145], v[194:197], v[100:103]
	v_mfma_f32_16x16x32_bf16 v[100:103], v[146:149], v[214:217], v[100:103]
	v_mfma_f32_16x16x32_bf16 v[92:95], v[154:157], v[194:197], v[92:95]
	v_mfma_f32_16x16x32_bf16 v[92:95], v[158:161], v[214:217], v[92:95]
	v_mfma_f32_16x16x32_bf16 v[76:79], v[154:157], v[218:221], v[76:79]
	v_mfma_f32_16x16x32_bf16 v[76:79], v[158:161], v[234:237], v[76:79]
	v_mfma_f32_16x16x32_bf16 v[84:87], v[142:145], v[218:221], v[84:87]
	v_mfma_f32_16x16x32_bf16 v[84:87], v[146:149], v[234:237], v[84:87]
	s_setprio 0
	s_setprio 1
	v_mfma_f32_16x16x32_bf16 v[120:123], v[162:165], v[178:181], v[120:123]
	v_mfma_f32_16x16x32_bf16 v[120:123], v[166:169], v[182:185], v[120:123]
	v_mfma_f32_16x16x32_bf16 v[112:115], v[170:173], v[178:181], v[112:115]
	v_mfma_f32_16x16x32_bf16 v[112:115], v[174:177], v[182:185], v[112:115]
	v_mfma_f32_16x16x32_bf16 v[96:99], v[170:173], v[186:189], v[96:99]
	v_mfma_f32_16x16x32_bf16 v[96:99], v[174:177], v[190:193], v[96:99]
	v_mfma_f32_16x16x32_bf16 v[104:107], v[162:165], v[186:189], v[104:107]
	v_mfma_f32_16x16x32_bf16 v[104:107], v[166:169], v[190:193], v[104:107]
	v_mfma_f32_16x16x32_bf16 v[88:91], v[162:165], v[194:197], v[88:91]
	v_mfma_f32_16x16x32_bf16 v[88:91], v[166:169], v[214:217], v[88:91]
	v_mfma_f32_16x16x32_bf16 v[80:83], v[170:173], v[194:197], v[80:83]
	v_mfma_f32_16x16x32_bf16 v[80:83], v[174:177], v[214:217], v[80:83]
	v_mfma_f32_16x16x32_bf16 v[68:71], v[170:173], v[218:221], v[68:71]
	v_mfma_f32_16x16x32_bf16 v[68:71], v[174:177], v[234:237], v[68:71]
	v_mfma_f32_16x16x32_bf16 v[72:75], v[162:165], v[218:221], v[72:75]
	v_mfma_f32_16x16x32_bf16 v[72:75], v[166:169], v[234:237], v[72:75]
	s_barrier
	ds_read_b128 v[178:181], v153 offset:16384
	ds_read_b128 v[182:185], v153 offset:17408
	ds_read_b128 v[186:189], v153 offset:18432
	ds_read_b128 v[190:193], v153 offset:19456
	ds_read_b128 v[194:197], v153 offset:20480
	ds_read_b128 v[214:217], v153 offset:21504
	ds_read_b128 v[218:221], v153 offset:22528
	ds_read_b128 v[234:237], v153 offset:23552
	s_setprio 0
	s_add_i32 s61, s61, s8
	s_mov_b32 m0, s61
	s_nop 0
	global_load_lds_dwordx4 v2, s[0:1]
	s_add_i32 m0, s61, 0x2000
	s_add_u32 s62, s0, 0x100000
	s_addc_u32 s63, s1, 0
	s_add_i32 s61, s64, s8
	global_load_lds_dwordx4 v132, s[0:1]
	s_mov_b32 m0, s61
	s_nop 0
	global_load_lds_dwordx4 v2, s[62:63]
	s_add_i32 m0, s61, 0x2000
	s_nop 0
	global_load_lds_dwordx4 v132, s[62:63]
	s_mov_b32 m0, s9
	s_nop 0
	global_load_lds_dwordx4 v136, s[26:27]
	s_mov_b32 m0, s10
	s_nop 0
	global_load_lds_dwordx4 v134, s[26:27]
	s_nop 0
	s_add_u32 s100, s26, 0x80
	s_addc_u32 s101, s27, 0
	s_setprio 1
	s_waitcnt vmcnt(8)
	s_waitcnt lgkmcnt(0)
	s_barrier
	v_mfma_f32_16x16x32_bf16 v[64:67], v[142:145], v[178:181], v[64:67]
	v_mfma_f32_16x16x32_bf16 v[64:67], v[146:149], v[182:185], v[64:67]
	v_mfma_f32_16x16x32_bf16 v[60:63], v[154:157], v[178:181], v[60:63]
	v_mfma_f32_16x16x32_bf16 v[60:63], v[158:161], v[182:185], v[60:63]
	v_mfma_f32_16x16x32_bf16 v[44:47], v[154:157], v[186:189], v[44:47]
	v_mfma_f32_16x16x32_bf16 v[44:47], v[158:161], v[190:193], v[44:47]
	v_mfma_f32_16x16x32_bf16 v[52:55], v[142:145], v[186:189], v[52:55]
	v_mfma_f32_16x16x32_bf16 v[52:55], v[146:149], v[190:193], v[52:55]
	v_mfma_f32_16x16x32_bf16 v[36:39], v[142:145], v[194:197], v[36:39]
	v_mfma_f32_16x16x32_bf16 v[36:39], v[146:149], v[214:217], v[36:39]
	v_mfma_f32_16x16x32_bf16 v[28:31], v[154:157], v[194:197], v[28:31]
	v_mfma_f32_16x16x32_bf16 v[28:31], v[158:161], v[214:217], v[28:31]
	v_mfma_f32_16x16x32_bf16 v[12:15], v[154:157], v[218:221], v[12:15]
	v_mfma_f32_16x16x32_bf16 v[12:15], v[158:161], v[234:237], v[12:15]
	v_mfma_f32_16x16x32_bf16 v[16:19], v[142:145], v[218:221], v[16:19]
	v_mfma_f32_16x16x32_bf16 v[16:19], v[146:149], v[234:237], v[16:19]
	s_setprio 0
	s_setprio 1
	v_mfma_f32_16x16x32_bf16 v[56:59], v[162:165], v[178:181], v[56:59]
	v_mfma_f32_16x16x32_bf16 v[56:59], v[166:169], v[182:185], v[56:59]
	v_mfma_f32_16x16x32_bf16 v[48:51], v[170:173], v[178:181], v[48:51]
	v_mfma_f32_16x16x32_bf16 v[48:51], v[174:177], v[182:185], v[48:51]
	v_mfma_f32_16x16x32_bf16 v[32:35], v[170:173], v[186:189], v[32:35]
	v_mfma_f32_16x16x32_bf16 v[32:35], v[174:177], v[190:193], v[32:35]
	v_mfma_f32_16x16x32_bf16 v[40:43], v[162:165], v[186:189], v[40:43]
	v_mfma_f32_16x16x32_bf16 v[40:43], v[166:169], v[190:193], v[40:43]
	v_mfma_f32_16x16x32_bf16 v[24:27], v[162:165], v[194:197], v[24:27]
	v_mfma_f32_16x16x32_bf16 v[24:27], v[166:169], v[214:217], v[24:27]
	v_mfma_f32_16x16x32_bf16 v[20:23], v[170:173], v[194:197], v[20:23]
	v_mfma_f32_16x16x32_bf16 v[20:23], v[174:177], v[214:217], v[20:23]
	v_mfma_f32_16x16x32_bf16 v[4:7], v[170:173], v[218:221], v[4:7]
	v_mfma_f32_16x16x32_bf16 v[4:7], v[174:177], v[234:237], v[4:7]
	v_mfma_f32_16x16x32_bf16 v[8:11], v[162:165], v[218:221], v[8:11]
	v_mfma_f32_16x16x32_bf16 v[8:11], v[166:169], v[234:237], v[8:11]
	s_barrier
; #define PG8_STAGE(bufoff, gbase, voff) do { _Pragma("unroll") for (int _i = 0; _i < 2; ++_i) \
;         __builtin_amdgcn_global_load_lds((const unsigned*)((const char*)(gbase) + (voff)[_i]), (PG8_LAS unsigned*)(lds + (bufoff) + ldsw + _i * 8192), 16, 0, 0); } while (0)
; #define PG8_LDA(dst, b, h) do { _Pragma("unroll") for (int m = 0; m < 4; ++m) _Pragma("unroll") for (int k = 0; k < 2; ++k) dst[m][k] = *(const PG8_LAS bf16x8*)(lds + PG8_SA(b, h) + aoff + m * 2048 + k * 1024); } while (0)
; #define PG8_LDB(dst, b, h) do { _Pragma("unroll") for (int n = 0; n < 2; ++n) _Pragma("unroll") for (int k = 0; k < 2; ++k) dst[n][k] = *(const PG8_LAS bf16x8*)(lds + PG8_SB(b, h) + boff + n * 2048 + k * 1024); } while (0)
; #define PG8_MMA(ai, bj, At, Bt) do { __builtin_amdgcn_s_setprio(1); _Pragma("unroll") for (int m = 0; m < 4; ++m) _Pragma("unroll") for (int n = 0; n < 2; ++n) _Pragma("unroll") for (int k = 0; k < 2; ++k) \
;         acc[ai][bj][m][n] = __builtin_amdgcn_mfma_f32_16x16x32_bf16(Bt[n][k], At[m][k], acc[ai][bj][m][n], 0, 0, 0); __builtin_amdgcn_s_setprio(0); } while (0)
; #define PG8_WAIT_V(n) asm volatile("s_waitcnt vmcnt(" #n ")" ::: "memory")
; #define PG8_WAIT_L(n) asm volatile("s_waitcnt lgkmcnt(" #n ")" ::: "memory")
; #define PG8_BAR __builtin_amdgcn_s_barrier()
; #define PG8_SCHED __builtin_amdgcn_sched_barrier(0)
; template <class Epi, class Sched, bool ALIGN_EPI = false, bool SP2 = false>
; __device__ __forceinline__ void gemm_phase(PG8_LAS unsigned char* lds, const Gemm g, const Sched& S, const Epi& E) {
;     ...
;             PG8_LDB(B0, 1, 0); PG8_LDB(B1, 1, 1); PG8_SCHED; PG8_LDA(At, 1, 0); PG8_STAGE(PG8_SA(0, 1), a2 + hstep, voffA);
;             PG8_WAIT_V(8); PG8_WAIT_L(0); PG8_BAR; PG8_MMA(0, 0, At, B0); PG8_MMA(0, 1, At, B1); PG8_BAR; PG8_SCHED;
;             PG8_LDA(At, 1, 1); PG8_STAGE(PG8_SB(1, 0), b3, voffB); PG8_STAGE(PG8_SB(1, 1), b3 + hstep, voffB); PG8_STAGE(PG8_SA(1, 0), a3, voffA);
;             PG8_WAIT_V(8); PG8_WAIT_L(0); PG8_BAR; PG8_MMA(1, 0, At, B0); PG8_MMA(1, 1, At, B1); PG8_BAR; PG8_SCHED;
	ds_read_b128 v[142:145], v198 offset:32768
	ds_read_b128 v[146:149], v198 offset:33792
	ds_read_b128 v[154:157], v198 offset:34816
	ds_read_b128 v[158:161], v198 offset:35840
	ds_read_b128 v[162:165], v198 offset:49152
	ds_read_b128 v[166:169], v198 offset:50176
	ds_read_b128 v[170:173], v198 offset:51200
	ds_read_b128 v[174:177], v198 offset:52224
	s_add_u32 s26, s26, 0x100000
	s_addc_u32 s27, s27, 0
	s_mov_b32 m0, s11
	ds_read_b128 v[178:181], v153 offset:32768
	ds_read_b128 v[182:185], v153 offset:33792
	ds_read_b128 v[186:189], v153 offset:34816
	ds_read_b128 v[190:193], v153 offset:35840
	ds_read_b128 v[194:197], v153 offset:36864
	ds_read_b128 v[214:217], v153 offset:37888
	ds_read_b128 v[218:221], v153 offset:38912
	ds_read_b128 v[234:237], v153 offset:39936
	s_setprio 0
	s_add_i32 s61, 0, 0x18000
	s_add_i32 s62, 0, 0x1c000
	global_load_lds_dwordx4 v136, s[26:27]
	s_mov_b32 m0, s52
	s_nop 0
	global_load_lds_dwordx4 v134, s[26:27]
	s_setprio 1
	s_waitcnt vmcnt(8)
	s_waitcnt lgkmcnt(0)
	s_barrier
	v_mfma_f32_16x16x32_bf16 v[128:131], v[142:145], v[178:181], v[128:131]
	v_mfma_f32_16x16x32_bf16 v[128:131], v[146:149], v[182:185], v[128:131]
	v_mfma_f32_16x16x32_bf16 v[124:127], v[154:157], v[178:181], v[124:127]
	v_mfma_f32_16x16x32_bf16 v[124:127], v[158:161], v[182:185], v[124:127]
	v_mfma_f32_16x16x32_bf16 v[108:111], v[154:157], v[186:189], v[108:111]
	v_mfma_f32_16x16x32_bf16 v[108:111], v[158:161], v[190:193], v[108:111]
	v_mfma_f32_16x16x32_bf16 v[116:119], v[142:145], v[186:189], v[116:119]
	v_mfma_f32_16x16x32_bf16 v[116:119], v[146:149], v[190:193], v[116:119]
	v_mfma_f32_16x16x32_bf16 v[100:103], v[142:145], v[194:197], v[100:103]
	v_mfma_f32_16x16x32_bf16 v[100:103], v[146:149], v[214:217], v[100:103]
	v_mfma_f32_16x16x32_bf16 v[92:95], v[154:157], v[194:197], v[92:95]
	v_mfma_f32_16x16x32_bf16 v[92:95], v[158:161], v[214:217], v[92:95]
	v_mfma_f32_16x16x32_bf16 v[76:79], v[154:157], v[218:221], v[76:79]
	v_mfma_f32_16x16x32_bf16 v[76:79], v[158:161], v[234:237], v[76:79]
	v_mfma_f32_16x16x32_bf16 v[84:87], v[142:145], v[218:221], v[84:87]
	v_mfma_f32_16x16x32_bf16 v[84:87], v[146:149], v[234:237], v[84:87]
	s_setprio 0
	s_setprio 1
	v_mfma_f32_16x16x32_bf16 v[120:123], v[162:165], v[178:181], v[120:123]
	v_mfma_f32_16x16x32_bf16 v[120:123], v[166:169], v[182:185], v[120:123]
	v_mfma_f32_16x16x32_bf16 v[112:115], v[170:173], v[178:181], v[112:115]
	v_mfma_f32_16x16x32_bf16 v[112:115], v[174:177], v[182:185], v[112:115]
	v_mfma_f32_16x16x32_bf16 v[96:99], v[170:173], v[186:189], v[96:99]
	v_mfma_f32_16x16x32_bf16 v[96:99], v[174:177], v[190:193], v[96:99]
	v_mfma_f32_16x16x32_bf16 v[104:107], v[162:165], v[186:189], v[104:107]
	v_mfma_f32_16x16x32_bf16 v[104:107], v[166:169], v[190:193], v[104:107]
	v_mfma_f32_16x16x32_bf16 v[88:91], v[162:165], v[194:197], v[88:91]
	v_mfma_f32_16x16x32_bf16 v[88:91], v[166:169], v[214:217], v[88:91]
	v_mfma_f32_16x16x32_bf16 v[80:83], v[170:173], v[194:197], v[80:83]
	v_mfma_f32_16x16x32_bf16 v[80:83], v[174:177], v[214:217], v[80:83]
	v_mfma_f32_16x16x32_bf16 v[68:71], v[170:173], v[218:221], v[68:71]
	v_mfma_f32_16x16x32_bf16 v[68:71], v[174:177], v[234:237], v[68:71]
	v_mfma_f32_16x16x32_bf16 v[72:75], v[162:165], v[218:221], v[72:75]
	v_mfma_f32_16x16x32_bf16 v[72:75], v[166:169], v[234:237], v[72:75]
	s_barrier
	ds_read_b128 v[178:181], v153 offset:49152
	ds_read_b128 v[182:185], v153 offset:50176
	ds_read_b128 v[186:189], v153 offset:51200
	ds_read_b128 v[190:193], v153 offset:52224
	ds_read_b128 v[194:197], v153 offset:53248
	ds_read_b128 v[214:217], v153 offset:54272
	ds_read_b128 v[218:221], v153 offset:55296
	ds_read_b128 v[234:237], v153 offset:56320
	s_setprio 0
	s_add_i32 s26, s61, s8
	s_mov_b32 m0, s26
	s_add_u32 s0, s0, 0x80
	s_addc_u32 s1, s1, 0
	global_load_lds_dwordx4 v2, s[0:1]
	s_add_i32 m0, s26, 0x2000
	s_add_i32 s26, s62, s8
	global_load_lds_dwordx4 v132, s[0:1]
	s_add_u32 s0, s0, 0x100000
	s_addc_u32 s1, s1, 0
	s_mov_b32 m0, s26
	s_nop 0
	global_load_lds_dwordx4 v2, s[0:1]
	s_add_i32 m0, s26, 0x2000
	s_nop 0
	global_load_lds_dwordx4 v132, s[0:1]
	s_mov_b32 m0, s54
	s_nop 0
	global_load_lds_dwordx4 v136, s[100:101]
	s_mov_b32 m0, s55
	s_nop 0
	global_load_lds_dwordx4 v134, s[100:101]
	s_setprio 1
	s_waitcnt vmcnt(8)
	s_waitcnt lgkmcnt(0)
	s_barrier
	v_mfma_f32_16x16x32_bf16 v[64:67], v[142:145], v[178:181], v[64:67]
	v_mfma_f32_16x16x32_bf16 v[64:67], v[146:149], v[182:185], v[64:67]
	v_mfma_f32_16x16x32_bf16 v[60:63], v[154:157], v[178:181], v[60:63]
	v_mfma_f32_16x16x32_bf16 v[60:63], v[158:161], v[182:185], v[60:63]
	v_mfma_f32_16x16x32_bf16 v[44:47], v[154:157], v[186:189], v[44:47]
	v_mfma_f32_16x16x32_bf16 v[44:47], v[158:161], v[190:193], v[44:47]
	v_mfma_f32_16x16x32_bf16 v[52:55], v[142:145], v[186:189], v[52:55]
	v_mfma_f32_16x16x32_bf16 v[52:55], v[146:149], v[190:193], v[52:55]
	v_mfma_f32_16x16x32_bf16 v[36:39], v[142:145], v[194:197], v[36:39]
	v_mfma_f32_16x16x32_bf16 v[36:39], v[146:149], v[214:217], v[36:39]
	v_mfma_f32_16x16x32_bf16 v[28:31], v[154:157], v[194:197], v[28:31]
	v_mfma_f32_16x16x32_bf16 v[28:31], v[158:161], v[214:217], v[28:31]
	v_mfma_f32_16x16x32_bf16 v[12:15], v[154:157], v[218:221], v[12:15]
	v_mfma_f32_16x16x32_bf16 v[12:15], v[158:161], v[234:237], v[12:15]
	v_mfma_f32_16x16x32_bf16 v[16:19], v[142:145], v[218:221], v[16:19]
	v_mfma_f32_16x16x32_bf16 v[16:19], v[146:149], v[234:237], v[16:19]
	s_setprio 0
	s_setprio 1
	s_add_i32 s60, s60, 2
	s_add_u32 s50, s50, 0x100
	s_addc_u32 s51, s51, 0
	s_add_u32 s43, s43, 0x100
	s_addc_u32 s45, s45, 0
	s_nop 0
	v_mfma_f32_16x16x32_bf16 v[56:59], v[162:165], v[178:181], v[56:59]
	v_mfma_f32_16x16x32_bf16 v[56:59], v[166:169], v[182:185], v[56:59]
	v_mfma_f32_16x16x32_bf16 v[48:51], v[170:173], v[178:181], v[48:51]
	v_mfma_f32_16x16x32_bf16 v[48:51], v[174:177], v[182:185], v[48:51]
	v_mfma_f32_16x16x32_bf16 v[32:35], v[170:173], v[186:189], v[32:35]
	v_mfma_f32_16x16x32_bf16 v[32:35], v[174:177], v[190:193], v[32:35]
	v_mfma_f32_16x16x32_bf16 v[40:43], v[162:165], v[186:189], v[40:43]
	v_mfma_f32_16x16x32_bf16 v[40:43], v[166:169], v[190:193], v[40:43]
	v_mfma_f32_16x16x32_bf16 v[24:27], v[162:165], v[194:197], v[24:27]
	v_mfma_f32_16x16x32_bf16 v[24:27], v[166:169], v[214:217], v[24:27]
	v_mfma_f32_16x16x32_bf16 v[20:23], v[170:173], v[194:197], v[20:23]
	v_mfma_f32_16x16x32_bf16 v[20:23], v[174:177], v[214:217], v[20:23]
	v_mfma_f32_16x16x32_bf16 v[4:7], v[170:173], v[218:221], v[4:7]
	v_mfma_f32_16x16x32_bf16 v[4:7], v[174:177], v[234:237], v[4:7]
	v_mfma_f32_16x16x32_bf16 v[8:11], v[162:165], v[218:221], v[8:11]
	v_mfma_f32_16x16x32_bf16 v[8:11], v[166:169], v[234:237], v[8:11]
	s_barrier
	s_cmp_gt_u32 s60, 61
	s_cbranch_scc0 .LBB0_816
	s_setprio 0
	s_and_b64 vcc, exec, s[40:41]
	s_cbranch_vccz .LBB0_819
	s_barrier

; #define PG8_STAGE(bufoff, gbase, voff) do { _Pragma("unroll") for (int _i = 0; _i < 2; ++_i) \
;         __builtin_amdgcn_global_load_lds((const unsigned*)((const char*)(gbase) + (voff)[_i]), (PG8_LAS unsigned*)(lds + (bufoff) + ldsw + _i * 8192), 16, 0, 0); } while (0)
; #define PG8_LDA(dst, b, h) do { _Pragma("unroll") for (int m = 0; m < 4; ++m) _Pragma("unroll") for (int k = 0; k < 2; ++k) dst[m][k] = *(const PG8_LAS bf16x8*)(lds + PG8_SA(b, h) + aoff + m * 2048 + k * 1024); } while (0)
; #define PG8_LDB(dst, b, h) do { _Pragma("unroll") for (int n = 0; n < 2; ++n) _Pragma("unroll") for (int k = 0; k < 2; ++k) dst[n][k] = *(const PG8_LAS bf16x8*)(lds + PG8_SB(b, h) + boff + n * 2048 + k * 1024); } while (0)
; #define PG8_WAIT_V(n) asm volatile("s_waitcnt vmcnt(" #n ")" ::: "memory")
; #define PG8_WAIT_L(n) asm volatile("s_waitcnt lgkmcnt(" #n ")" ::: "memory")
; #define PG8_BAR __builtin_amdgcn_s_barrier()
; template <class Epi, class Sched, bool ALIGN_EPI = false, bool SP2 = false>
; __device__ __forceinline__ void gemm_phase(PG8_LAS unsigned char* lds, const Gemm g, const Sched& S, const Epi& E) {
;     ...
;         const bool has_next = S.next(ui + 1, nxt);
;         const char* nA = has_next ? (const char*)g.A + (size_t)nxt.pm * tstep + (size_t)nxt.kt0 * kstep : cA; const char* nB = has_next ? (const char*)g.Bt + (size_t)nxt.pn * tstep + (size_t)nxt.kt0 * kstep : cB;
;         const int nt = cur.nt;
;         for (int t = 0; t < nt; t += 2) {
;             const bool last = (t == nt - 2);
;             const char* a1 = cA + (size_t)(t + 1) * kstep;
;             const char* a2 = last ? nA : cA + (size_t)(t + 2) * kstep; const char* b2 = last ? nB : cB + (size_t)(t + 2) * kstep;
;             const char* a3 = a2 + kstep; const char* b3 = b2 + kstep;
;             if (last && has_next) S.a_ready(nxt);
;             if constexpr (SP2) {
;             PG8_LDB(B0, 0, 0); PG8_LDB(B1, 0, 1); PG8_SCHED; PG8_LDA(At, 0, 0); PG8_STAGE(PG8_SA(1, 1), a1 + hstep, voffA);
;             PG8_WAIT_V(8); PG8_WAIT_L(0); PG8_BAR; PG8_MMA(0, 0, At, B0); PG8_MMA(0, 1, At, B1); PG8_BAR; PG8_SCHED;
;             PG8_LDA(At, 0, 1); PG8_STAGE(PG8_SB(0, 0), b2, voffB); PG8_STAGE(PG8_SB(0, 1), b2 + hstep, voffB); PG8_STAGE(PG8_SA(0, 0), a2, voffA);
;             PG8_WAIT_V(8); PG8_WAIT_L(0); PG8_BAR; PG8_MMA(1, 0, At, B0); PG8_MMA(1, 1, At, B1); PG8_BAR; PG8_SCHED;
.LBB0_1032:
	ds_read_b128 v[146:149], v198
	ds_read_b128 v[150:153], v198 offset:1024
	ds_read_b128 v[154:157], v198 offset:2048
	ds_read_b128 v[158:161], v198 offset:3072
	ds_read_b128 v[162:165], v198 offset:16384
	ds_read_b128 v[166:169], v198 offset:17408
	ds_read_b128 v[170:173], v198 offset:18432
	ds_read_b128 v[174:177], v198 offset:19456
	s_add_i32 m0, s37, 0xc000
	ds_read_b128 v[178:181], v145
	ds_read_b128 v[182:185], v145 offset:1024
	ds_read_b128 v[186:189], v145 offset:2048
	ds_read_b128 v[190:193], v145 offset:3072
	ds_read_b128 v[194:197], v145 offset:4096
	ds_read_b128 v[214:217], v145 offset:5120
	ds_read_b128 v[218:221], v145 offset:6144
	ds_read_b128 v[234:237], v145 offset:7168
	s_setprio 0
	s_add_u32 s0, s50, 0xfffc0080
	s_addc_u32 s1, s51, -1
	s_add_i32 s53, 0, 0x10000
	s_cmp_eq_u32 s52, 12
	s_cselect_b32 s27, s47, s1
	s_cselect_b32 s26, s46, s0
	s_cselect_b32 s1, s49, s45
	s_cselect_b32 s0, s48, s43
	s_add_i32 s64, 0, 0x14000
	global_load_lds_dwordx4 v138, s[50:51]
	s_add_i32 m0, s37, 0xe000
	s_nop 0
	global_load_lds_dwordx4 v140, s[50:51]
	s_setprio 1
	s_waitcnt vmcnt(8)
	s_waitcnt lgkmcnt(0)
	s_barrier
	v_mfma_f32_16x16x32_bf16 v[128:131], v[146:149], v[178:181], v[128:131]
	v_mfma_f32_16x16x32_bf16 v[128:131], v[150:153], v[182:185], v[128:131]
	v_mfma_f32_16x16x32_bf16 v[124:127], v[154:157], v[178:181], v[124:127]
	v_mfma_f32_16x16x32_bf16 v[124:127], v[158:161], v[182:185], v[124:127]
	v_mfma_f32_16x16x32_bf16 v[116:119], v[154:157], v[186:189], v[116:119]
	v_mfma_f32_16x16x32_bf16 v[116:119], v[158:161], v[190:193], v[116:119]
	v_mfma_f32_16x16x32_bf16 v[120:123], v[146:149], v[186:189], v[120:123]
	v_mfma_f32_16x16x32_bf16 v[120:123], v[150:153], v[190:193], v[120:123]
	v_mfma_f32_16x16x32_bf16 v[104:107], v[146:149], v[194:197], v[104:107]
	v_mfma_f32_16x16x32_bf16 v[104:107], v[150:153], v[214:217], v[104:107]
	v_mfma_f32_16x16x32_bf16 v[100:103], v[154:157], v[194:197], v[100:103]
	v_mfma_f32_16x16x32_bf16 v[100:103], v[158:161], v[214:217], v[100:103]
	v_mfma_f32_16x16x32_bf16 v[84:87], v[154:157], v[218:221], v[84:87]
	v_mfma_f32_16x16x32_bf16 v[84:87], v[158:161], v[234:237], v[84:87]
	v_mfma_f32_16x16x32_bf16 v[88:91], v[146:149], v[218:221], v[88:91]
	v_mfma_f32_16x16x32_bf16 v[88:91], v[150:153], v[234:237], v[88:91]
	s_setprio 0
	s_setprio 1
	v_mfma_f32_16x16x32_bf16 v[112:115], v[162:165], v[178:181], v[112:115]
	v_mfma_f32_16x16x32_bf16 v[112:115], v[166:169], v[182:185], v[112:115]
	v_mfma_f32_16x16x32_bf16 v[108:111], v[170:173], v[178:181], v[108:111]
	v_mfma_f32_16x16x32_bf16 v[108:111], v[174:177], v[182:185], v[108:111]
	v_mfma_f32_16x16x32_bf16 v[92:95], v[170:173], v[186:189], v[92:95]
	v_mfma_f32_16x16x32_bf16 v[92:95], v[174:177], v[190:193], v[92:95]
	v_mfma_f32_16x16x32_bf16 v[96:99], v[162:165], v[186:189], v[96:99]
	v_mfma_f32_16x16x32_bf16 v[96:99], v[166:169], v[190:193], v[96:99]
	v_mfma_f32_16x16x32_bf16 v[80:83], v[162:165], v[194:197], v[80:83]
	v_mfma_f32_16x16x32_bf16 v[80:83], v[166:169], v[214:217], v[80:83]
	v_mfma_f32_16x16x32_bf16 v[76:79], v[170:173], v[194:197], v[76:79]
	v_mfma_f32_16x16x32_bf16 v[76:79], v[174:177], v[214:217], v[76:79]
	v_mfma_f32_16x16x32_bf16 v[68:71], v[170:173], v[218:221], v[68:71]
	v_mfma_f32_16x16x32_bf16 v[68:71], v[174:177], v[234:237], v[68:71]
	v_mfma_f32_16x16x32_bf16 v[72:75], v[162:165], v[218:221], v[72:75]
	v_mfma_f32_16x16x32_bf16 v[72:75], v[166:169], v[234:237], v[72:75]
	s_barrier
	ds_read_b128 v[178:181], v145 offset:16384
	ds_read_b128 v[182:185], v145 offset:17408
	ds_read_b128 v[186:189], v145 offset:18432
	ds_read_b128 v[190:193], v145 offset:19456
	ds_read_b128 v[194:197], v145 offset:20480
	ds_read_b128 v[214:217], v145 offset:21504
	ds_read_b128 v[218:221], v145 offset:22528
	ds_read_b128 v[234:237], v145 offset:23552
	s_setprio 0
	s_add_i32 s53, s53, s10
	s_mov_b32 m0, s53
	s_nop 0
	global_load_lds_dwordx4 v2, s[0:1]
	s_add_i32 m0, s53, 0x2000
	s_add_u32 s62, s0, 0x40000
	s_addc_u32 s63, s1, 0
	s_add_i32 s53, s64, s10
	global_load_lds_dwordx4 v132, s[0:1]
	s_mov_b32 m0, s53
	s_nop 0
	global_load_lds_dwordx4 v2, s[62:63]
	s_add_i32 m0, s53, 0x2000
	s_nop 0
	global_load_lds_dwordx4 v132, s[62:63]
	s_mov_b32 m0, s37
	s_nop 0
	global_load_lds_dwordx4 v136, s[26:27]
	s_mov_b32 m0, s54
	s_nop 0
	global_load_lds_dwordx4 v134, s[26:27]
	s_nop 0
	s_add_u32 s100, s26, 0x80
	s_addc_u32 s101, s27, 0
	s_setprio 1
	s_waitcnt vmcnt(8)
	s_waitcnt lgkmcnt(0)
	s_barrier
	v_mfma_f32_16x16x32_bf16 v[64:67], v[146:149], v[178:181], v[64:67]
	v_mfma_f32_16x16x32_bf16 v[64:67], v[150:153], v[182:185], v[64:67]
	v_mfma_f32_16x16x32_bf16 v[60:63], v[154:157], v[178:181], v[60:63]
	v_mfma_f32_16x16x32_bf16 v[60:63], v[158:161], v[182:185], v[60:63]
	v_mfma_f32_16x16x32_bf16 v[52:55], v[154:157], v[186:189], v[52:55]
	v_mfma_f32_16x16x32_bf16 v[52:55], v[158:161], v[190:193], v[52:55]
	v_mfma_f32_16x16x32_bf16 v[56:59], v[146:149], v[186:189], v[56:59]
	v_mfma_f32_16x16x32_bf16 v[56:59], v[150:153], v[190:193], v[56:59]
	v_mfma_f32_16x16x32_bf16 v[40:43], v[146:149], v[194:197], v[40:43]
	v_mfma_f32_16x16x32_bf16 v[40:43], v[150:153], v[214:217], v[40:43]
	v_mfma_f32_16x16x32_bf16 v[36:39], v[154:157], v[194:197], v[36:39]
	v_mfma_f32_16x16x32_bf16 v[36:39], v[158:161], v[214:217], v[36:39]
	v_mfma_f32_16x16x32_bf16 v[20:23], v[154:157], v[218:221], v[20:23]
	v_mfma_f32_16x16x32_bf16 v[20:23], v[158:161], v[234:237], v[20:23]
	v_mfma_f32_16x16x32_bf16 v[24:27], v[146:149], v[218:221], v[24:27]
	v_mfma_f32_16x16x32_bf16 v[24:27], v[150:153], v[234:237], v[24:27]
	s_setprio 0
	s_setprio 1
	v_mfma_f32_16x16x32_bf16 v[48:51], v[162:165], v[178:181], v[48:51]
	v_mfma_f32_16x16x32_bf16 v[48:51], v[166:169], v[182:185], v[48:51]
	v_mfma_f32_16x16x32_bf16 v[44:47], v[170:173], v[178:181], v[44:47]
	v_mfma_f32_16x16x32_bf16 v[44:47], v[174:177], v[182:185], v[44:47]
	v_mfma_f32_16x16x32_bf16 v[28:31], v[170:173], v[186:189], v[28:31]
	v_mfma_f32_16x16x32_bf16 v[28:31], v[174:177], v[190:193], v[28:31]
	v_mfma_f32_16x16x32_bf16 v[32:35], v[162:165], v[186:189], v[32:35]
	v_mfma_f32_16x16x32_bf16 v[32:35], v[166:169], v[190:193], v[32:35]
	v_mfma_f32_16x16x32_bf16 v[16:19], v[162:165], v[194:197], v[16:19]
	v_mfma_f32_16x16x32_bf16 v[16:19], v[166:169], v[214:217], v[16:19]
	v_mfma_f32_16x16x32_bf16 v[12:15], v[170:173], v[194:197], v[12:15]
	v_mfma_f32_16x16x32_bf16 v[12:15], v[174:177], v[214:217], v[12:15]
	v_mfma_f32_16x16x32_bf16 v[4:7], v[170:173], v[218:221], v[4:7]
	v_mfma_f32_16x16x32_bf16 v[4:7], v[174:177], v[234:237], v[4:7]
	v_mfma_f32_16x16x32_bf16 v[8:11], v[162:165], v[218:221], v[8:11]
	v_mfma_f32_16x16x32_bf16 v[8:11], v[166:169], v[234:237], v[8:11]
	s_barrier
; #define PG8_STAGE(bufoff, gbase, voff) do { _Pragma("unroll") for (int _i = 0; _i < 2; ++_i) \
;         __builtin_amdgcn_global_load_lds((const unsigned*)((const char*)(gbase) + (voff)[_i]), (PG8_LAS unsigned*)(lds + (bufoff) + ldsw + _i * 8192), 16, 0, 0); } while (0)
; #define PG8_LDA(dst, b, h) do { _Pragma("unroll") for (int m = 0; m < 4; ++m) _Pragma("unroll") for (int k = 0; k < 2; ++k) dst[m][k] = *(const PG8_LAS bf16x8*)(lds + PG8_SA(b, h) + aoff + m * 2048 + k * 1024); } while (0)
; #define PG8_LDB(dst, b, h) do { _Pragma("unroll") for (int n = 0; n < 2; ++n) _Pragma("unroll") for (int k = 0; k < 2; ++k) dst[n][k] = *(const PG8_LAS bf16x8*)(lds + PG8_SB(b, h) + boff + n * 2048 + k * 1024); } while (0)
; #define PG8_MMA(ai, bj, At, Bt) do { __builtin_amdgcn_s_setprio(1); _Pragma("unroll") for (int m = 0; m < 4; ++m) _Pragma("unroll") for (int n = 0; n < 2; ++n) _Pragma("unroll") for (int k = 0; k < 2; ++k) \
;         acc[ai][bj][m][n] = __builtin_amdgcn_mfma_f32_16x16x32_bf16(Bt[n][k], At[m][k], acc[ai][bj][m][n], 0, 0, 0); __builtin_amdgcn_s_setprio(0); } while (0)
; #define PG8_WAIT_V(n) asm volatile("s_waitcnt vmcnt(" #n ")" ::: "memory")
; #define PG8_WAIT_L(n) asm volatile("s_waitcnt lgkmcnt(" #n ")" ::: "memory")
; #define PG8_BAR __builtin_amdgcn_s_barrier()
; #define PG8_SCHED __builtin_amdgcn_sched_barrier(0)
; template <class Epi, class Sched, bool ALIGN_EPI = false, bool SP2 = false>
; __device__ __forceinline__ void gemm_phase(PG8_LAS unsigned char* lds, const Gemm g, const Sched& S, const Epi& E) {
;     ...
;             PG8_LDB(B0, 1, 0); PG8_LDB(B1, 1, 1); PG8_SCHED; PG8_LDA(At, 1, 0); PG8_STAGE(PG8_SA(0, 1), a2 + hstep, voffA);
;             PG8_WAIT_V(8); PG8_WAIT_L(0); PG8_BAR; PG8_MMA(0, 0, At, B0); PG8_MMA(0, 1, At, B1); PG8_BAR; PG8_SCHED;
;             PG8_LDA(At, 1, 1); PG8_STAGE(PG8_SB(1, 0), b3, voffB); PG8_STAGE(PG8_SB(1, 1), b3 + hstep, voffB); PG8_STAGE(PG8_SA(1, 0), a3, voffA);
;             PG8_WAIT_V(8); PG8_WAIT_L(0); PG8_BAR; PG8_MMA(1, 0, At, B0); PG8_MMA(1, 1, At, B1); PG8_BAR; PG8_SCHED;
	ds_read_b128 v[146:149], v198 offset:32768
	ds_read_b128 v[150:153], v198 offset:33792
	ds_read_b128 v[154:157], v198 offset:34816
	ds_read_b128 v[158:161], v198 offset:35840
	ds_read_b128 v[162:165], v198 offset:49152
	ds_read_b128 v[166:169], v198 offset:50176
	ds_read_b128 v[170:173], v198 offset:51200
	ds_read_b128 v[174:177], v198 offset:52224
	s_add_u32 s26, s26, 0x40000
	s_addc_u32 s27, s27, 0
	s_mov_b32 m0, s55
	ds_read_b128 v[178:181], v145 offset:32768
	ds_read_b128 v[182:185], v145 offset:33792
	ds_read_b128 v[186:189], v145 offset:34816
	ds_read_b128 v[190:193], v145 offset:35840
	ds_read_b128 v[194:197], v145 offset:36864
	ds_read_b128 v[214:217], v145 offset:37888
	ds_read_b128 v[218:221], v145 offset:38912
	ds_read_b128 v[234:237], v145 offset:39936
	s_setprio 0
	s_add_i32 s53, 0, 0x18000
	s_add_i32 s62, 0, 0x1c000
	global_load_lds_dwordx4 v136, s[26:27]
	s_mov_b32 m0, s56
	s_nop 0
	global_load_lds_dwordx4 v134, s[26:27]
	s_setprio 1
	s_waitcnt vmcnt(8)
	s_waitcnt lgkmcnt(0)
	s_barrier
	v_mfma_f32_16x16x32_bf16 v[128:131], v[146:149], v[178:181], v[128:131]
	v_mfma_f32_16x16x32_bf16 v[128:131], v[150:153], v[182:185], v[128:131]
	v_mfma_f32_16x16x32_bf16 v[124:127], v[154:157], v[178:181], v[124:127]
	v_mfma_f32_16x16x32_bf16 v[124:127], v[158:161], v[182:185], v[124:127]
	v_mfma_f32_16x16x32_bf16 v[116:119], v[154:157], v[186:189], v[116:119]
	v_mfma_f32_16x16x32_bf16 v[116:119], v[158:161], v[190:193], v[116:119]
	v_mfma_f32_16x16x32_bf16 v[120:123], v[146:149], v[186:189], v[120:123]
	v_mfma_f32_16x16x32_bf16 v[120:123], v[150:153], v[190:193], v[120:123]
	v_mfma_f32_16x16x32_bf16 v[104:107], v[146:149], v[194:197], v[104:107]
	v_mfma_f32_16x16x32_bf16 v[104:107], v[150:153], v[214:217], v[104:107]
	v_mfma_f32_16x16x32_bf16 v[100:103], v[154:157], v[194:197], v[100:103]
	v_mfma_f32_16x16x32_bf16 v[100:103], v[158:161], v[214:217], v[100:103]
	v_mfma_f32_16x16x32_bf16 v[84:87], v[154:157], v[218:221], v[84:87]
	v_mfma_f32_16x16x32_bf16 v[84:87], v[158:161], v[234:237], v[84:87]
	v_mfma_f32_16x16x32_bf16 v[88:91], v[146:149], v[218:221], v[88:91]
	v_mfma_f32_16x16x32_bf16 v[88:91], v[150:153], v[234:237], v[88:91]
	s_setprio 0
	s_setprio 1
	v_mfma_f32_16x16x32_bf16 v[112:115], v[162:165], v[178:181], v[112:115]
	v_mfma_f32_16x16x32_bf16 v[112:115], v[166:169], v[182:185], v[112:115]
	v_mfma_f32_16x16x32_bf16 v[108:111], v[170:173], v[178:181], v[108:111]
	v_mfma_f32_16x16x32_bf16 v[108:111], v[174:177], v[182:185], v[108:111]
	v_mfma_f32_16x16x32_bf16 v[92:95], v[170:173], v[186:189], v[92:95]
	v_mfma_f32_16x16x32_bf16 v[92:95], v[174:177], v[190:193], v[92:95]
	v_mfma_f32_16x16x32_bf16 v[96:99], v[162:165], v[186:189], v[96:99]
	v_mfma_f32_16x16x32_bf16 v[96:99], v[166:169], v[190:193], v[96:99]
	v_mfma_f32_16x16x32_bf16 v[80:83], v[162:165], v[194:197], v[80:83]
	v_mfma_f32_16x16x32_bf16 v[80:83], v[166:169], v[214:217], v[80:83]
	v_mfma_f32_16x16x32_bf16 v[76:79], v[170:173], v[194:197], v[76:79]
	v_mfma_f32_16x16x32_bf16 v[76:79], v[174:177], v[214:217], v[76:79]
	v_mfma_f32_16x16x32_bf16 v[68:71], v[170:173], v[218:221], v[68:71]
	v_mfma_f32_16x16x32_bf16 v[68:71], v[174:177], v[234:237], v[68:71]
	v_mfma_f32_16x16x32_bf16 v[72:75], v[162:165], v[218:221], v[72:75]
	v_mfma_f32_16x16x32_bf16 v[72:75], v[166:169], v[234:237], v[72:75]
	s_barrier
	ds_read_b128 v[178:181], v145 offset:49152
	ds_read_b128 v[182:185], v145 offset:50176
	ds_read_b128 v[186:189], v145 offset:51200
	ds_read_b128 v[190:193], v145 offset:52224
	ds_read_b128 v[194:197], v145 offset:53248
	ds_read_b128 v[214:217], v145 offset:54272
	ds_read_b128 v[218:221], v145 offset:55296
	ds_read_b128 v[234:237], v145 offset:56320
	s_setprio 0
	s_add_i32 s26, s53, s10
	s_mov_b32 m0, s26
	s_add_u32 s0, s0, 0x80
	s_addc_u32 s1, s1, 0
	global_load_lds_dwordx4 v2, s[0:1]
	s_add_i32 m0, s26, 0x2000
	s_add_i32 s26, s62, s10
	global_load_lds_dwordx4 v132, s[0:1]
	s_add_u32 s0, s0, 0x40000
	s_addc_u32 s1, s1, 0
	s_mov_b32 m0, s26
	s_nop 0
	global_load_lds_dwordx4 v2, s[0:1]
	s_add_i32 m0, s26, 0x2000
	s_nop 0
	global_load_lds_dwordx4 v132, s[0:1]
	s_mov_b32 m0, s57
	s_nop 0
	global_load_lds_dwordx4 v136, s[100:101]
	s_mov_b32 m0, s58
	s_nop 0
	global_load_lds_dwordx4 v134, s[100:101]
	s_setprio 1
	s_waitcnt vmcnt(8)
	s_waitcnt lgkmcnt(0)
	s_barrier
	v_mfma_f32_16x16x32_bf16 v[64:67], v[146:149], v[178:181], v[64:67]
	v_mfma_f32_16x16x32_bf16 v[64:67], v[150:153], v[182:185], v[64:67]
	v_mfma_f32_16x16x32_bf16 v[60:63], v[154:157], v[178:181], v[60:63]
	v_mfma_f32_16x16x32_bf16 v[60:63], v[158:161], v[182:185], v[60:63]
	v_mfma_f32_16x16x32_bf16 v[52:55], v[154:157], v[186:189], v[52:55]
	v_mfma_f32_16x16x32_bf16 v[52:55], v[158:161], v[190:193], v[52:55]
	v_mfma_f32_16x16x32_bf16 v[56:59], v[146:149], v[186:189], v[56:59]
	v_mfma_f32_16x16x32_bf16 v[56:59], v[150:153], v[190:193], v[56:59]
	v_mfma_f32_16x16x32_bf16 v[40:43], v[146:149], v[194:197], v[40:43]
	v_mfma_f32_16x16x32_bf16 v[40:43], v[150:153], v[214:217], v[40:43]
	v_mfma_f32_16x16x32_bf16 v[36:39], v[154:157], v[194:197], v[36:39]
	v_mfma_f32_16x16x32_bf16 v[36:39], v[158:161], v[214:217], v[36:39]
	v_mfma_f32_16x16x32_bf16 v[20:23], v[154:157], v[218:221], v[20:23]
	v_mfma_f32_16x16x32_bf16 v[20:23], v[158:161], v[234:237], v[20:23]
	v_mfma_f32_16x16x32_bf16 v[24:27], v[146:149], v[218:221], v[24:27]
	v_mfma_f32_16x16x32_bf16 v[24:27], v[150:153], v[234:237], v[24:27]
	s_setprio 0
	s_setprio 1
	s_add_i32 s52, s52, 2
	s_add_u32 s50, s50, 0x100
	s_addc_u32 s51, s51, 0
	s_add_u32 s43, s43, 0x100
	s_addc_u32 s45, s45, 0
	s_nop 0
	v_mfma_f32_16x16x32_bf16 v[48:51], v[162:165], v[178:181], v[48:51]
	v_mfma_f32_16x16x32_bf16 v[48:51], v[166:169], v[182:185], v[48:51]
	v_mfma_f32_16x16x32_bf16 v[44:47], v[170:173], v[178:181], v[44:47]
	v_mfma_f32_16x16x32_bf16 v[44:47], v[174:177], v[182:185], v[44:47]
	v_mfma_f32_16x16x32_bf16 v[28:31], v[170:173], v[186:189], v[28:31]
	v_mfma_f32_16x16x32_bf16 v[28:31], v[174:177], v[190:193], v[28:31]
	v_mfma_f32_16x16x32_bf16 v[32:35], v[162:165], v[186:189], v[32:35]
	v_mfma_f32_16x16x32_bf16 v[32:35], v[166:169], v[190:193], v[32:35]
	v_mfma_f32_16x16x32_bf16 v[16:19], v[162:165], v[194:197], v[16:19]
	v_mfma_f32_16x16x32_bf16 v[16:19], v[166:169], v[214:217], v[16:19]
	v_mfma_f32_16x16x32_bf16 v[12:15], v[170:173], v[194:197], v[12:15]
	v_mfma_f32_16x16x32_bf16 v[12:15], v[174:177], v[214:217], v[12:15]
	v_mfma_f32_16x16x32_bf16 v[4:7], v[170:173], v[218:221], v[4:7]
	v_mfma_f32_16x16x32_bf16 v[4:7], v[174:177], v[234:237], v[4:7]
	v_mfma_f32_16x16x32_bf16 v[8:11], v[162:165], v[218:221], v[8:11]
	v_mfma_f32_16x16x32_bf16 v[8:11], v[166:169], v[234:237], v[8:11]
	s_barrier
	s_cmp_gt_u32 s52, 13
	s_cbranch_scc0 .LBB0_1032
	s_setprio 0
	s_and_b64 vcc, exec, s[40:41]
	s_cbranch_vccz .LBB0_1035
	s_barrier

; #define PG8_STAGE(bufoff, gbase, voff) do { _Pragma("unroll") for (int _i = 0; _i < 2; ++_i) \
;         __builtin_amdgcn_global_load_lds((const unsigned*)((const char*)(gbase) + (voff)[_i]), (PG8_LAS unsigned*)(lds + (bufoff) + ldsw + _i * 8192), 16, 0, 0); } while (0)
; #define PG8_LDA(dst, b, h) do { _Pragma("unroll") for (int m = 0; m < 4; ++m) _Pragma("unroll") for (int k = 0; k < 2; ++k) dst[m][k] = *(const PG8_LAS bf16x8*)(lds + PG8_SA(b, h) + aoff + m * 2048 + k * 1024); } while (0)
; #define PG8_LDB(dst, b, h) do { _Pragma("unroll") for (int n = 0; n < 2; ++n) _Pragma("unroll") for (int k = 0; k < 2; ++k) dst[n][k] = *(const PG8_LAS bf16x8*)(lds + PG8_SB(b, h) + boff + n * 2048 + k * 1024); } while (0)
; #define PG8_WAIT_V(n) asm volatile("s_waitcnt vmcnt(" #n ")" ::: "memory")
; #define PG8_WAIT_L(n) asm volatile("s_waitcnt lgkmcnt(" #n ")" ::: "memory")
; #define PG8_BAR __builtin_amdgcn_s_barrier()
; template <class Epi, class Sched, bool ALIGN_EPI = false, bool SP2 = false>
; __device__ __forceinline__ void gemm_phase(PG8_LAS unsigned char* lds, const Gemm g, const Sched& S, const Epi& E) {
;     ...
;         const bool has_next = S.next(ui + 1, nxt);
;         const char* nA = has_next ? (const char*)g.A + (size_t)nxt.pm * tstep + (size_t)nxt.kt0 * kstep : cA; const char* nB = has_next ? (const char*)g.Bt + (size_t)nxt.pn * tstep + (size_t)nxt.kt0 * kstep : cB;
;         const int nt = cur.nt;
;         for (int t = 0; t < nt; t += 2) {
;             const bool last = (t == nt - 2);
;             const char* a1 = cA + (size_t)(t + 1) * kstep;
;             const char* a2 = last ? nA : cA + (size_t)(t + 2) * kstep; const char* b2 = last ? nB : cB + (size_t)(t + 2) * kstep;
;             const char* a3 = a2 + kstep; const char* b3 = b2 + kstep;
;             if (last && has_next) S.a_ready(nxt);
;             if constexpr (SP2) {
;             PG8_LDB(B0, 0, 0); PG8_LDB(B1, 0, 1); PG8_SCHED; PG8_LDA(At, 0, 0); PG8_STAGE(PG8_SA(1, 1), a1 + hstep, voffA);
;             PG8_WAIT_V(8); PG8_WAIT_L(0); PG8_BAR; PG8_MMA(0, 0, At, B0); PG8_MMA(0, 1, At, B1); PG8_BAR; PG8_SCHED;
;             PG8_LDA(At, 0, 1); PG8_STAGE(PG8_SB(0, 0), b2, voffB); PG8_STAGE(PG8_SB(0, 1), b2 + hstep, voffB); PG8_STAGE(PG8_SA(0, 0), a2, voffA);
;             PG8_WAIT_V(8); PG8_WAIT_L(0); PG8_BAR; PG8_MMA(1, 0, At, B0); PG8_MMA(1, 1, At, B1); PG8_BAR; PG8_SCHED;
.LBB0_1051:
	ds_read_b128 v[84:87], v154
	ds_read_b128 v[88:91], v154 offset:1024
	ds_read_b128 v[162:165], v154 offset:2048
	ds_read_b128 v[166:169], v154 offset:3072
	ds_read_b128 v[170:173], v154 offset:16384
	ds_read_b128 v[174:177], v154 offset:17408
	ds_read_b128 v[178:181], v154 offset:18432
	ds_read_b128 v[182:185], v154 offset:19456
	s_add_i32 m0, s10, 0xc000
	ds_read_b128 v[186:189], v160
	ds_read_b128 v[190:193], v160 offset:1024
	ds_read_b128 v[194:197], v160 offset:2048
	ds_read_b128 v[214:217], v160 offset:3072
	ds_read_b128 v[218:221], v160 offset:4096
	ds_read_b128 v[234:237], v160 offset:5120
	ds_read_b128 v[238:241], v160 offset:6144
	ds_read_b128 v[242:245], v160 offset:7168
	s_setprio 0
	s_add_u32 s0, s52, 0xfffe0080
	s_addc_u32 s1, s53, -1
	s_add_i32 s63, 0, 0x10000
	s_cmp_eq_u32 s62, 4
	s_cselect_b32 s27, s45, s1
	s_cselect_b32 s26, s58, s0
	s_cselect_b32 s1, s43, s61
	s_cselect_b32 s0, s59, s60
	s_add_i32 s66, 0, 0x14000
	global_load_lds_dwordx4 v150, s[52:53]
	s_add_i32 m0, s10, 0xe000
	s_nop 0
	global_load_lds_dwordx4 v152, s[52:53]
	s_setprio 1
	s_waitcnt vmcnt(8)
	s_waitcnt lgkmcnt(0)
	s_barrier
	v_mfma_f32_16x16x32_bf16 v[136:139], v[84:87], v[186:189], v[136:139]
	v_mfma_f32_16x16x32_bf16 v[136:139], v[88:91], v[190:193], v[136:139]
	v_mfma_f32_16x16x32_bf16 v[132:135], v[162:165], v[186:189], v[132:135]
	v_mfma_f32_16x16x32_bf16 v[132:135], v[166:169], v[190:193], v[132:135]
	v_mfma_f32_16x16x32_bf16 v[120:123], v[162:165], v[194:197], v[120:123]
	v_mfma_f32_16x16x32_bf16 v[120:123], v[166:169], v[214:217], v[120:123]
	v_mfma_f32_16x16x32_bf16 v[128:131], v[84:87], v[194:197], v[128:131]
	v_mfma_f32_16x16x32_bf16 v[128:131], v[88:91], v[214:217], v[128:131]
	v_mfma_f32_16x16x32_bf16 v[104:107], v[84:87], v[218:221], v[104:107]
	v_mfma_f32_16x16x32_bf16 v[104:107], v[88:91], v[234:237], v[104:107]
	v_mfma_f32_16x16x32_bf16 v[100:103], v[162:165], v[218:221], v[100:103]
	v_mfma_f32_16x16x32_bf16 v[100:103], v[166:169], v[234:237], v[100:103]
	v_mfma_f32_16x16x32_bf16 v[76:79], v[162:165], v[238:241], v[76:79]
	v_mfma_f32_16x16x32_bf16 v[76:79], v[166:169], v[242:245], v[76:79]
	v_mfma_f32_16x16x32_bf16 v[80:83], v[84:87], v[238:241], v[80:83]
	v_mfma_f32_16x16x32_bf16 v[80:83], v[88:91], v[242:245], v[80:83]
	s_setprio 0
	s_setprio 1
	v_mfma_f32_16x16x32_bf16 v[124:127], v[170:173], v[186:189], v[124:127]
	v_mfma_f32_16x16x32_bf16 v[124:127], v[174:177], v[190:193], v[124:127]
	v_mfma_f32_16x16x32_bf16 v[116:119], v[178:181], v[186:189], v[116:119]
	v_mfma_f32_16x16x32_bf16 v[116:119], v[182:185], v[190:193], v[116:119]
	v_mfma_f32_16x16x32_bf16 v[108:111], v[178:181], v[194:197], v[108:111]
	v_mfma_f32_16x16x32_bf16 v[108:111], v[182:185], v[214:217], v[108:111]
	v_mfma_f32_16x16x32_bf16 v[112:115], v[170:173], v[194:197], v[112:115]
	v_mfma_f32_16x16x32_bf16 v[112:115], v[174:177], v[214:217], v[112:115]
	v_mfma_f32_16x16x32_bf16 v[96:99], v[170:173], v[218:221], v[96:99]
	v_mfma_f32_16x16x32_bf16 v[96:99], v[174:177], v[234:237], v[96:99]
	v_mfma_f32_16x16x32_bf16 v[92:95], v[178:181], v[218:221], v[92:95]
	v_mfma_f32_16x16x32_bf16 v[92:95], v[182:185], v[234:237], v[92:95]
	v_mfma_f32_16x16x32_bf16 v[68:71], v[178:181], v[238:241], v[68:71]
	v_mfma_f32_16x16x32_bf16 v[68:71], v[182:185], v[242:245], v[68:71]
	v_mfma_f32_16x16x32_bf16 v[72:75], v[170:173], v[238:241], v[72:75]
	v_mfma_f32_16x16x32_bf16 v[72:75], v[174:177], v[242:245], v[72:75]
	s_barrier
	ds_read_b128 v[186:189], v160 offset:16384
	ds_read_b128 v[190:193], v160 offset:17408
	ds_read_b128 v[194:197], v160 offset:18432
	ds_read_b128 v[214:217], v160 offset:19456
	ds_read_b128 v[218:221], v160 offset:20480
	ds_read_b128 v[234:237], v160 offset:21504
	ds_read_b128 v[238:241], v160 offset:22528
	ds_read_b128 v[242:245], v160 offset:23552
	s_setprio 0
	s_add_i32 s63, s63, s9
	s_mov_b32 m0, s63
	s_nop 0
	global_load_lds_dwordx4 v2, s[0:1]
	s_add_i32 m0, s63, 0x2000
	s_add_u32 s64, s0, 0x20000
	s_addc_u32 s65, s1, 0
	s_add_i32 s63, s66, s9
	global_load_lds_dwordx4 v144, s[0:1]
	s_mov_b32 m0, s63
	s_nop 0
	global_load_lds_dwordx4 v2, s[64:65]
	s_add_i32 m0, s63, 0x2000
	s_nop 0
	global_load_lds_dwordx4 v144, s[64:65]
	s_mov_b32 m0, s10
	s_nop 0
	global_load_lds_dwordx4 v140, s[26:27]
	s_mov_b32 m0, s11
	s_nop 0
	global_load_lds_dwordx4 v142, s[26:27]
	s_nop 0
	s_add_u32 s100, s26, 0x80
	s_addc_u32 s101, s27, 0
	s_setprio 1
	s_waitcnt vmcnt(8)
	s_waitcnt lgkmcnt(0)
	s_barrier
	v_mfma_f32_16x16x32_bf16 v[64:67], v[84:87], v[186:189], v[64:67]
	v_mfma_f32_16x16x32_bf16 v[64:67], v[88:91], v[190:193], v[64:67]
	v_mfma_f32_16x16x32_bf16 v[60:63], v[162:165], v[186:189], v[60:63]
	v_mfma_f32_16x16x32_bf16 v[60:63], v[166:169], v[190:193], v[60:63]
	v_mfma_f32_16x16x32_bf16 v[44:47], v[162:165], v[194:197], v[44:47]
	v_mfma_f32_16x16x32_bf16 v[44:47], v[166:169], v[214:217], v[44:47]
	v_mfma_f32_16x16x32_bf16 v[48:51], v[84:87], v[194:197], v[48:51]
	v_mfma_f32_16x16x32_bf16 v[48:51], v[88:91], v[214:217], v[48:51]
	v_mfma_f32_16x16x32_bf16 v[32:35], v[84:87], v[218:221], v[32:35]
	v_mfma_f32_16x16x32_bf16 v[32:35], v[88:91], v[234:237], v[32:35]
	v_mfma_f32_16x16x32_bf16 v[28:31], v[162:165], v[218:221], v[28:31]
	v_mfma_f32_16x16x32_bf16 v[28:31], v[166:169], v[234:237], v[28:31]
	v_mfma_f32_16x16x32_bf16 v[12:15], v[162:165], v[238:241], v[12:15]
	v_mfma_f32_16x16x32_bf16 v[12:15], v[166:169], v[242:245], v[12:15]
	v_mfma_f32_16x16x32_bf16 v[16:19], v[84:87], v[238:241], v[16:19]
	v_mfma_f32_16x16x32_bf16 v[16:19], v[88:91], v[242:245], v[16:19]
	s_setprio 0
	s_setprio 1
	v_mfma_f32_16x16x32_bf16 v[56:59], v[170:173], v[186:189], v[56:59]
	v_mfma_f32_16x16x32_bf16 v[56:59], v[174:177], v[190:193], v[56:59]
	v_mfma_f32_16x16x32_bf16 v[52:55], v[178:181], v[186:189], v[52:55]
	v_mfma_f32_16x16x32_bf16 v[52:55], v[182:185], v[190:193], v[52:55]
	v_mfma_f32_16x16x32_bf16 v[36:39], v[178:181], v[194:197], v[36:39]
	v_mfma_f32_16x16x32_bf16 v[36:39], v[182:185], v[214:217], v[36:39]
	v_mfma_f32_16x16x32_bf16 v[40:43], v[170:173], v[194:197], v[40:43]
	v_mfma_f32_16x16x32_bf16 v[40:43], v[174:177], v[214:217], v[40:43]
	v_mfma_f32_16x16x32_bf16 v[24:27], v[170:173], v[218:221], v[24:27]
	v_mfma_f32_16x16x32_bf16 v[24:27], v[174:177], v[234:237], v[24:27]
	v_mfma_f32_16x16x32_bf16 v[20:23], v[178:181], v[218:221], v[20:23]
	v_mfma_f32_16x16x32_bf16 v[20:23], v[182:185], v[234:237], v[20:23]
	v_mfma_f32_16x16x32_bf16 v[4:7], v[178:181], v[238:241], v[4:7]
	v_mfma_f32_16x16x32_bf16 v[4:7], v[182:185], v[242:245], v[4:7]
	v_mfma_f32_16x16x32_bf16 v[8:11], v[170:173], v[238:241], v[8:11]
	v_mfma_f32_16x16x32_bf16 v[8:11], v[174:177], v[242:245], v[8:11]
	s_barrier
; #define PG8_STAGE(bufoff, gbase, voff) do { _Pragma("unroll") for (int _i = 0; _i < 2; ++_i) \
;         __builtin_amdgcn_global_load_lds((const unsigned*)((const char*)(gbase) + (voff)[_i]), (PG8_LAS unsigned*)(lds + (bufoff) + ldsw + _i * 8192), 16, 0, 0); } while (0)
; #define PG8_LDA(dst, b, h) do { _Pragma("unroll") for (int m = 0; m < 4; ++m) _Pragma("unroll") for (int k = 0; k < 2; ++k) dst[m][k] = *(const PG8_LAS bf16x8*)(lds + PG8_SA(b, h) + aoff + m * 2048 + k * 1024); } while (0)
; #define PG8_LDB(dst, b, h) do { _Pragma("unroll") for (int n = 0; n < 2; ++n) _Pragma("unroll") for (int k = 0; k < 2; ++k) dst[n][k] = *(const PG8_LAS bf16x8*)(lds + PG8_SB(b, h) + boff + n * 2048 + k * 1024); } while (0)
; #define PG8_MMA(ai, bj, At, Bt) do { __builtin_amdgcn_s_setprio(1); _Pragma("unroll") for (int m = 0; m < 4; ++m) _Pragma("unroll") for (int n = 0; n < 2; ++n) _Pragma("unroll") for (int k = 0; k < 2; ++k) \
;         acc[ai][bj][m][n] = __builtin_amdgcn_mfma_f32_16x16x32_bf16(Bt[n][k], At[m][k], acc[ai][bj][m][n], 0, 0, 0); __builtin_amdgcn_s_setprio(0); } while (0)
; #define PG8_WAIT_V(n) asm volatile("s_waitcnt vmcnt(" #n ")" ::: "memory")
; #define PG8_WAIT_L(n) asm volatile("s_waitcnt lgkmcnt(" #n ")" ::: "memory")
; #define PG8_BAR __builtin_amdgcn_s_barrier()
; #define PG8_SCHED __builtin_amdgcn_sched_barrier(0)
; template <class Epi, class Sched, bool ALIGN_EPI = false, bool SP2 = false>
; __device__ __forceinline__ void gemm_phase(PG8_LAS unsigned char* lds, const Gemm g, const Sched& S, const Epi& E) {
;     ...
;             PG8_LDB(B0, 1, 0); PG8_LDB(B1, 1, 1); PG8_SCHED; PG8_LDA(At, 1, 0); PG8_STAGE(PG8_SA(0, 1), a2 + hstep, voffA);
;             PG8_WAIT_V(8); PG8_WAIT_L(0); PG8_BAR; PG8_MMA(0, 0, At, B0); PG8_MMA(0, 1, At, B1); PG8_BAR; PG8_SCHED;
;             PG8_LDA(At, 1, 1); PG8_STAGE(PG8_SB(1, 0), b3, voffB); PG8_STAGE(PG8_SB(1, 1), b3 + hstep, voffB); PG8_STAGE(PG8_SA(1, 0), a3, voffA);
;             PG8_WAIT_V(8); PG8_WAIT_L(0); PG8_BAR; PG8_MMA(1, 0, At, B0); PG8_MMA(1, 1, At, B1); PG8_BAR; PG8_SCHED;
	ds_read_b128 v[84:87], v154 offset:32768
	ds_read_b128 v[88:91], v154 offset:33792
	ds_read_b128 v[162:165], v154 offset:34816
	ds_read_b128 v[166:169], v154 offset:35840
	ds_read_b128 v[170:173], v154 offset:49152
	ds_read_b128 v[174:177], v154 offset:50176
	ds_read_b128 v[178:181], v154 offset:51200
	ds_read_b128 v[182:185], v154 offset:52224
	s_add_u32 s26, s26, 0x20000
	s_addc_u32 s27, s27, 0
	s_mov_b32 m0, s25
	ds_read_b128 v[186:189], v160 offset:32768
	ds_read_b128 v[190:193], v160 offset:33792
	ds_read_b128 v[194:197], v160 offset:34816
	ds_read_b128 v[214:217], v160 offset:35840
	ds_read_b128 v[218:221], v160 offset:36864
	ds_read_b128 v[234:237], v160 offset:37888
	ds_read_b128 v[238:241], v160 offset:38912
	ds_read_b128 v[242:245], v160 offset:39936
	s_setprio 0
	s_add_i32 s63, 0, 0x18000
	s_add_i32 s64, 0, 0x1c000
	global_load_lds_dwordx4 v140, s[26:27]
	s_mov_b32 m0, s51
	s_nop 0
	global_load_lds_dwordx4 v142, s[26:27]
	s_setprio 1
	s_waitcnt vmcnt(8)
	s_waitcnt lgkmcnt(0)
	s_barrier
	v_mfma_f32_16x16x32_bf16 v[136:139], v[84:87], v[186:189], v[136:139]
	v_mfma_f32_16x16x32_bf16 v[136:139], v[88:91], v[190:193], v[136:139]
	v_mfma_f32_16x16x32_bf16 v[132:135], v[162:165], v[186:189], v[132:135]
	v_mfma_f32_16x16x32_bf16 v[132:135], v[166:169], v[190:193], v[132:135]
	v_mfma_f32_16x16x32_bf16 v[120:123], v[162:165], v[194:197], v[120:123]
	v_mfma_f32_16x16x32_bf16 v[120:123], v[166:169], v[214:217], v[120:123]
	v_mfma_f32_16x16x32_bf16 v[128:131], v[84:87], v[194:197], v[128:131]
	v_mfma_f32_16x16x32_bf16 v[128:131], v[88:91], v[214:217], v[128:131]
	v_mfma_f32_16x16x32_bf16 v[104:107], v[84:87], v[218:221], v[104:107]
	v_mfma_f32_16x16x32_bf16 v[104:107], v[88:91], v[234:237], v[104:107]
	v_mfma_f32_16x16x32_bf16 v[100:103], v[162:165], v[218:221], v[100:103]
	v_mfma_f32_16x16x32_bf16 v[100:103], v[166:169], v[234:237], v[100:103]
	v_mfma_f32_16x16x32_bf16 v[76:79], v[162:165], v[238:241], v[76:79]
	v_mfma_f32_16x16x32_bf16 v[76:79], v[166:169], v[242:245], v[76:79]
	v_mfma_f32_16x16x32_bf16 v[80:83], v[84:87], v[238:241], v[80:83]
	v_mfma_f32_16x16x32_bf16 v[80:83], v[88:91], v[242:245], v[80:83]
	s_setprio 0
	s_setprio 1
	v_mfma_f32_16x16x32_bf16 v[124:127], v[170:173], v[186:189], v[124:127]
	v_mfma_f32_16x16x32_bf16 v[124:127], v[174:177], v[190:193], v[124:127]
	v_mfma_f32_16x16x32_bf16 v[116:119], v[178:181], v[186:189], v[116:119]
	v_mfma_f32_16x16x32_bf16 v[116:119], v[182:185], v[190:193], v[116:119]
	v_mfma_f32_16x16x32_bf16 v[108:111], v[178:181], v[194:197], v[108:111]
	v_mfma_f32_16x16x32_bf16 v[108:111], v[182:185], v[214:217], v[108:111]
	v_mfma_f32_16x16x32_bf16 v[112:115], v[170:173], v[194:197], v[112:115]
	v_mfma_f32_16x16x32_bf16 v[112:115], v[174:177], v[214:217], v[112:115]
	v_mfma_f32_16x16x32_bf16 v[96:99], v[170:173], v[218:221], v[96:99]
	v_mfma_f32_16x16x32_bf16 v[96:99], v[174:177], v[234:237], v[96:99]
	v_mfma_f32_16x16x32_bf16 v[92:95], v[178:181], v[218:221], v[92:95]
	v_mfma_f32_16x16x32_bf16 v[92:95], v[182:185], v[234:237], v[92:95]
	v_mfma_f32_16x16x32_bf16 v[68:71], v[178:181], v[238:241], v[68:71]
	v_mfma_f32_16x16x32_bf16 v[68:71], v[182:185], v[242:245], v[68:71]
	v_mfma_f32_16x16x32_bf16 v[72:75], v[170:173], v[238:241], v[72:75]
	v_mfma_f32_16x16x32_bf16 v[72:75], v[174:177], v[242:245], v[72:75]
	s_barrier
	ds_read_b128 v[186:189], v160 offset:49152
	ds_read_b128 v[190:193], v160 offset:50176
	ds_read_b128 v[194:197], v160 offset:51200
	ds_read_b128 v[214:217], v160 offset:52224
	ds_read_b128 v[218:221], v160 offset:53248
	ds_read_b128 v[234:237], v160 offset:54272
	ds_read_b128 v[238:241], v160 offset:55296
	ds_read_b128 v[242:245], v160 offset:56320
	s_setprio 0
	s_add_i32 s26, s63, s9
	s_mov_b32 m0, s26
	s_add_u32 s0, s0, 0x80
	s_addc_u32 s1, s1, 0
	global_load_lds_dwordx4 v2, s[0:1]
	s_add_i32 m0, s26, 0x2000
	s_add_i32 s26, s64, s9
	global_load_lds_dwordx4 v144, s[0:1]
	s_add_u32 s0, s0, 0x20000
	s_addc_u32 s1, s1, 0
	s_mov_b32 m0, s26
	s_nop 0
	global_load_lds_dwordx4 v2, s[0:1]
	s_add_i32 m0, s26, 0x2000
	s_nop 0
	global_load_lds_dwordx4 v144, s[0:1]
	s_mov_b32 m0, s54
	s_nop 0
	global_load_lds_dwordx4 v140, s[100:101]
	s_mov_b32 m0, s55
	s_nop 0
	global_load_lds_dwordx4 v142, s[100:101]
	s_setprio 1
	s_waitcnt vmcnt(8)
	s_waitcnt lgkmcnt(0)
	s_barrier
	v_mfma_f32_16x16x32_bf16 v[64:67], v[84:87], v[186:189], v[64:67]
	v_mfma_f32_16x16x32_bf16 v[64:67], v[88:91], v[190:193], v[64:67]
	v_mfma_f32_16x16x32_bf16 v[60:63], v[162:165], v[186:189], v[60:63]
	v_mfma_f32_16x16x32_bf16 v[60:63], v[166:169], v[190:193], v[60:63]
	v_mfma_f32_16x16x32_bf16 v[44:47], v[162:165], v[194:197], v[44:47]
	v_mfma_f32_16x16x32_bf16 v[44:47], v[166:169], v[214:217], v[44:47]
	v_mfma_f32_16x16x32_bf16 v[48:51], v[84:87], v[194:197], v[48:51]
	v_mfma_f32_16x16x32_bf16 v[48:51], v[88:91], v[214:217], v[48:51]
	v_mfma_f32_16x16x32_bf16 v[32:35], v[84:87], v[218:221], v[32:35]
	v_mfma_f32_16x16x32_bf16 v[32:35], v[88:91], v[234:237], v[32:35]
	v_mfma_f32_16x16x32_bf16 v[28:31], v[162:165], v[218:221], v[28:31]
	v_mfma_f32_16x16x32_bf16 v[28:31], v[166:169], v[234:237], v[28:31]
	v_mfma_f32_16x16x32_bf16 v[12:15], v[162:165], v[238:241], v[12:15]
	v_mfma_f32_16x16x32_bf16 v[12:15], v[166:169], v[242:245], v[12:15]
	v_mfma_f32_16x16x32_bf16 v[16:19], v[84:87], v[238:241], v[16:19]
	v_mfma_f32_16x16x32_bf16 v[16:19], v[88:91], v[242:245], v[16:19]
	s_setprio 0
	s_setprio 1
	s_add_i32 s62, s62, 2
	s_add_u32 s52, s52, 0x100
	s_addc_u32 s53, s53, 0
	s_add_u32 s60, s60, 0x100
	s_addc_u32 s61, s61, 0
	s_nop 0
	v_mfma_f32_16x16x32_bf16 v[56:59], v[170:173], v[186:189], v[56:59]
	v_mfma_f32_16x16x32_bf16 v[56:59], v[174:177], v[190:193], v[56:59]
	v_mfma_f32_16x16x32_bf16 v[52:55], v[178:181], v[186:189], v[52:55]
	v_mfma_f32_16x16x32_bf16 v[52:55], v[182:185], v[190:193], v[52:55]
	v_mfma_f32_16x16x32_bf16 v[36:39], v[178:181], v[194:197], v[36:39]
	v_mfma_f32_16x16x32_bf16 v[36:39], v[182:185], v[214:217], v[36:39]
	v_mfma_f32_16x16x32_bf16 v[40:43], v[170:173], v[194:197], v[40:43]
	v_mfma_f32_16x16x32_bf16 v[40:43], v[174:177], v[214:217], v[40:43]
	v_mfma_f32_16x16x32_bf16 v[24:27], v[170:173], v[218:221], v[24:27]
	v_mfma_f32_16x16x32_bf16 v[24:27], v[174:177], v[234:237], v[24:27]
	v_mfma_f32_16x16x32_bf16 v[20:23], v[178:181], v[218:221], v[20:23]
	v_mfma_f32_16x16x32_bf16 v[20:23], v[182:185], v[234:237], v[20:23]
	v_mfma_f32_16x16x32_bf16 v[4:7], v[178:181], v[238:241], v[4:7]
	v_mfma_f32_16x16x32_bf16 v[4:7], v[182:185], v[242:245], v[4:7]
	v_mfma_f32_16x16x32_bf16 v[8:11], v[170:173], v[238:241], v[8:11]
	v_mfma_f32_16x16x32_bf16 v[8:11], v[174:177], v[242:245], v[8:11]
	s_barrier
	s_cmp_gt_u32 s62, 5
	s_cbranch_scc0 .LBB0_1051
	s_setprio 0
	s_and_b64 vcc, exec, s[36:37]
	s_cbranch_vccz .LBB0_1054
	s_barrier

; #define PG8_STAGE(bufoff, gbase, voff) do { _Pragma("unroll") for (int _i = 0; _i < 2; ++_i) \
;         __builtin_amdgcn_global_load_lds((const unsigned*)((const char*)(gbase) + (voff)[_i]), (PG8_LAS unsigned*)(lds + (bufoff) + ldsw + _i * 8192), 16, 0, 0); } while (0)
; #define PG8_LDA(dst, b, h) do { _Pragma("unroll") for (int m = 0; m < 4; ++m) _Pragma("unroll") for (int k = 0; k < 2; ++k) dst[m][k] = *(const PG8_LAS bf16x8*)(lds + PG8_SA(b, h) + aoff + m * 2048 + k * 1024); } while (0)
; #define PG8_LDB(dst, b, h) do { _Pragma("unroll") for (int n = 0; n < 2; ++n) _Pragma("unroll") for (int k = 0; k < 2; ++k) dst[n][k] = *(const PG8_LAS bf16x8*)(lds + PG8_SB(b, h) + boff + n * 2048 + k * 1024); } while (0)
; #define PG8_WAIT_V(n) asm volatile("s_waitcnt vmcnt(" #n ")" ::: "memory")
; #define PG8_WAIT_L(n) asm volatile("s_waitcnt lgkmcnt(" #n ")" ::: "memory")
; #define PG8_BAR __builtin_amdgcn_s_barrier()
; template <class Epi, class Sched, bool ALIGN_EPI = false, bool SP2 = false>
; __device__ __forceinline__ void gemm_phase(PG8_LAS unsigned char* lds, const Gemm g, const Sched& S, const Epi& E) {
;     ...
;         const bool has_next = S.next(ui + 1, nxt);
;         const char* nA = has_next ? (const char*)g.A + (size_t)nxt.pm * tstep + (size_t)nxt.kt0 * kstep : cA; const char* nB = has_next ? (const char*)g.Bt + (size_t)nxt.pn * tstep + (size_t)nxt.kt0 * kstep : cB;
;         const int nt = cur.nt;
;         for (int t = 0; t < nt; t += 2) {
;             const bool last = (t == nt - 2);
;             const char* a1 = cA + (size_t)(t + 1) * kstep;
;             const char* a2 = last ? nA : cA + (size_t)(t + 2) * kstep; const char* b2 = last ? nB : cB + (size_t)(t + 2) * kstep;
;             const char* a3 = a2 + kstep; const char* b3 = b2 + kstep;
;             if (last && has_next) S.a_ready(nxt);
;             if constexpr (SP2) {
;             PG8_LDB(B0, 0, 0); PG8_LDB(B1, 0, 1); PG8_SCHED; PG8_LDA(At, 0, 0); PG8_STAGE(PG8_SA(1, 1), a1 + hstep, voffA);
;             PG8_WAIT_V(8); PG8_WAIT_L(0); PG8_BAR; PG8_MMA(0, 0, At, B0); PG8_MMA(0, 1, At, B1); PG8_BAR; PG8_SCHED;
;             PG8_LDA(At, 0, 1); PG8_STAGE(PG8_SB(0, 0), b2, voffB); PG8_STAGE(PG8_SB(0, 1), b2 + hstep, voffB); PG8_STAGE(PG8_SA(0, 0), a2, voffA);
;             PG8_WAIT_V(8); PG8_WAIT_L(0); PG8_BAR; PG8_MMA(1, 0, At, B0); PG8_MMA(1, 1, At, B1); PG8_BAR; PG8_SCHED;
.LBB0_1624:
	ds_read_b128 v[142:145], v210
	ds_read_b128 v[150:153], v210 offset:1024
	ds_read_b128 v[154:157], v210 offset:2048
	ds_read_b128 v[158:161], v210 offset:3072
	ds_read_b128 v[162:165], v210 offset:16384
	ds_read_b128 v[166:169], v210 offset:17408
	ds_read_b128 v[170:173], v210 offset:18432
	ds_read_b128 v[174:177], v210 offset:19456
	s_add_i32 m0, s10, 0xc000
	ds_read_b128 v[178:181], v149
	ds_read_b128 v[182:185], v149 offset:1024
	ds_read_b128 v[186:189], v149 offset:2048
	ds_read_b128 v[190:193], v149 offset:3072
	ds_read_b128 v[194:197], v149 offset:4096
	ds_read_b128 v[198:201], v149 offset:5120
	ds_read_b128 v[202:205], v149 offset:6144
	ds_read_b128 v[206:209], v149 offset:7168
	s_setprio 0
	s_add_u32 s0, s56, 0xfff00080
	s_addc_u32 s1, s57, -1
	s_add_i32 s63, 0, 0x10000
	s_cmp_eq_u32 s62, 60
	s_cselect_b32 s27, s51, s1
	s_cselect_b32 s26, s50, s0
	s_cselect_b32 s1, s53, s49
	s_cselect_b32 s0, s52, s47
	s_add_i32 s66, 0, 0x14000
	global_load_lds_dwordx4 v138, s[56:57]
	s_add_i32 m0, s10, 0xe000
	s_nop 0
	global_load_lds_dwordx4 v140, s[56:57]
	s_nop 0
	s_setprio 1
	s_waitcnt vmcnt(8)
	s_waitcnt lgkmcnt(0)
	s_barrier
	v_mfma_f32_16x16x32_bf16 v[128:131], v[142:145], v[178:181], v[128:131]
	v_mfma_f32_16x16x32_bf16 v[128:131], v[150:153], v[182:185], v[128:131]
	v_mfma_f32_16x16x32_bf16 v[124:127], v[154:157], v[178:181], v[124:127]
	v_mfma_f32_16x16x32_bf16 v[124:127], v[158:161], v[182:185], v[124:127]
	v_mfma_f32_16x16x32_bf16 v[108:111], v[154:157], v[186:189], v[108:111]
	v_mfma_f32_16x16x32_bf16 v[108:111], v[158:161], v[190:193], v[108:111]
	v_mfma_f32_16x16x32_bf16 v[112:115], v[142:145], v[186:189], v[112:115]
	v_mfma_f32_16x16x32_bf16 v[112:115], v[150:153], v[190:193], v[112:115]
	v_mfma_f32_16x16x32_bf16 v[96:99], v[142:145], v[194:197], v[96:99]
	v_mfma_f32_16x16x32_bf16 v[96:99], v[150:153], v[198:201], v[96:99]
	v_mfma_f32_16x16x32_bf16 v[92:95], v[154:157], v[194:197], v[92:95]
	v_mfma_f32_16x16x32_bf16 v[92:95], v[158:161], v[198:201], v[92:95]
	v_mfma_f32_16x16x32_bf16 v[76:79], v[154:157], v[202:205], v[76:79]
	v_mfma_f32_16x16x32_bf16 v[76:79], v[158:161], v[206:209], v[76:79]
	v_mfma_f32_16x16x32_bf16 v[80:83], v[142:145], v[202:205], v[80:83]
	v_mfma_f32_16x16x32_bf16 v[80:83], v[150:153], v[206:209], v[80:83]
	s_setprio 0
	s_setprio 1
	v_mfma_f32_16x16x32_bf16 v[120:123], v[162:165], v[178:181], v[120:123]
	v_mfma_f32_16x16x32_bf16 v[120:123], v[166:169], v[182:185], v[120:123]
	v_mfma_f32_16x16x32_bf16 v[116:119], v[170:173], v[178:181], v[116:119]
	v_mfma_f32_16x16x32_bf16 v[116:119], v[174:177], v[182:185], v[116:119]
	v_mfma_f32_16x16x32_bf16 v[100:103], v[170:173], v[186:189], v[100:103]
	v_mfma_f32_16x16x32_bf16 v[100:103], v[174:177], v[190:193], v[100:103]
	v_mfma_f32_16x16x32_bf16 v[104:107], v[162:165], v[186:189], v[104:107]
	v_mfma_f32_16x16x32_bf16 v[104:107], v[166:169], v[190:193], v[104:107]
	v_mfma_f32_16x16x32_bf16 v[88:91], v[162:165], v[194:197], v[88:91]
	v_mfma_f32_16x16x32_bf16 v[88:91], v[166:169], v[198:201], v[88:91]
	v_mfma_f32_16x16x32_bf16 v[84:87], v[170:173], v[194:197], v[84:87]
	v_mfma_f32_16x16x32_bf16 v[84:87], v[174:177], v[198:201], v[84:87]
	v_mfma_f32_16x16x32_bf16 v[68:71], v[170:173], v[202:205], v[68:71]
	v_mfma_f32_16x16x32_bf16 v[68:71], v[174:177], v[206:209], v[68:71]
	v_mfma_f32_16x16x32_bf16 v[72:75], v[162:165], v[202:205], v[72:75]
	v_mfma_f32_16x16x32_bf16 v[72:75], v[166:169], v[206:209], v[72:75]
	s_barrier
	ds_read_b128 v[178:181], v149 offset:16384
	ds_read_b128 v[182:185], v149 offset:17408
	ds_read_b128 v[186:189], v149 offset:18432
	ds_read_b128 v[190:193], v149 offset:19456
	ds_read_b128 v[194:197], v149 offset:20480
	ds_read_b128 v[198:201], v149 offset:21504
	ds_read_b128 v[202:205], v149 offset:22528
	ds_read_b128 v[206:209], v149 offset:23552
	s_setprio 0
	s_add_i32 s63, s63, s9
	s_mov_b32 m0, s63
	s_nop 0
	global_load_lds_dwordx4 v2, s[0:1]
	s_add_i32 m0, s63, 0x2000
	s_add_u32 s64, s0, 0x100000
	s_addc_u32 s65, s1, 0
	s_add_i32 s63, s66, s9
	global_load_lds_dwordx4 v136, s[0:1]
	s_mov_b32 m0, s63
	s_nop 0
	global_load_lds_dwordx4 v2, s[64:65]
	s_add_i32 m0, s63, 0x2000
	s_nop 0
	global_load_lds_dwordx4 v136, s[64:65]
	s_mov_b32 m0, s10
	s_nop 0
	global_load_lds_dwordx4 v132, s[26:27]
	s_mov_b32 m0, s11
	s_nop 0
	global_load_lds_dwordx4 v134, s[26:27]
	s_nop 0
	s_add_u32 s100, s26, 0x80
	s_addc_u32 s101, s27, 0
	s_setprio 1
	s_waitcnt vmcnt(8)
	s_waitcnt lgkmcnt(0)
	s_barrier
	v_mfma_f32_16x16x32_bf16 v[64:67], v[142:145], v[178:181], v[64:67]
	v_mfma_f32_16x16x32_bf16 v[64:67], v[150:153], v[182:185], v[64:67]
	v_mfma_f32_16x16x32_bf16 v[60:63], v[154:157], v[178:181], v[60:63]
	v_mfma_f32_16x16x32_bf16 v[60:63], v[158:161], v[182:185], v[60:63]
	v_mfma_f32_16x16x32_bf16 v[44:47], v[154:157], v[186:189], v[44:47]
	v_mfma_f32_16x16x32_bf16 v[44:47], v[158:161], v[190:193], v[44:47]
	v_mfma_f32_16x16x32_bf16 v[48:51], v[142:145], v[186:189], v[48:51]
	v_mfma_f32_16x16x32_bf16 v[48:51], v[150:153], v[190:193], v[48:51]
	v_mfma_f32_16x16x32_bf16 v[32:35], v[142:145], v[194:197], v[32:35]
	v_mfma_f32_16x16x32_bf16 v[32:35], v[150:153], v[198:201], v[32:35]
	v_mfma_f32_16x16x32_bf16 v[28:31], v[154:157], v[194:197], v[28:31]
	v_mfma_f32_16x16x32_bf16 v[28:31], v[158:161], v[198:201], v[28:31]
	v_mfma_f32_16x16x32_bf16 v[12:15], v[154:157], v[202:205], v[12:15]
	v_mfma_f32_16x16x32_bf16 v[12:15], v[158:161], v[206:209], v[12:15]
	v_mfma_f32_16x16x32_bf16 v[16:19], v[142:145], v[202:205], v[16:19]
	v_mfma_f32_16x16x32_bf16 v[16:19], v[150:153], v[206:209], v[16:19]
	s_setprio 0
	s_setprio 1
	v_mfma_f32_16x16x32_bf16 v[56:59], v[162:165], v[178:181], v[56:59]
	v_mfma_f32_16x16x32_bf16 v[56:59], v[166:169], v[182:185], v[56:59]
	v_mfma_f32_16x16x32_bf16 v[52:55], v[170:173], v[178:181], v[52:55]
	v_mfma_f32_16x16x32_bf16 v[52:55], v[174:177], v[182:185], v[52:55]
	v_mfma_f32_16x16x32_bf16 v[36:39], v[170:173], v[186:189], v[36:39]
	v_mfma_f32_16x16x32_bf16 v[36:39], v[174:177], v[190:193], v[36:39]
	v_mfma_f32_16x16x32_bf16 v[40:43], v[162:165], v[186:189], v[40:43]
	v_mfma_f32_16x16x32_bf16 v[40:43], v[166:169], v[190:193], v[40:43]
	v_mfma_f32_16x16x32_bf16 v[24:27], v[162:165], v[194:197], v[24:27]
	v_mfma_f32_16x16x32_bf16 v[24:27], v[166:169], v[198:201], v[24:27]
	v_mfma_f32_16x16x32_bf16 v[20:23], v[170:173], v[194:197], v[20:23]
	v_mfma_f32_16x16x32_bf16 v[20:23], v[174:177], v[198:201], v[20:23]
	v_mfma_f32_16x16x32_bf16 v[4:7], v[170:173], v[202:205], v[4:7]
	v_mfma_f32_16x16x32_bf16 v[4:7], v[174:177], v[206:209], v[4:7]
	v_mfma_f32_16x16x32_bf16 v[8:11], v[162:165], v[202:205], v[8:11]
	v_mfma_f32_16x16x32_bf16 v[8:11], v[166:169], v[206:209], v[8:11]
	s_barrier
; #define PG8_STAGE(bufoff, gbase, voff) do { _Pragma("unroll") for (int _i = 0; _i < 2; ++_i) \
;         __builtin_amdgcn_global_load_lds((const unsigned*)((const char*)(gbase) + (voff)[_i]), (PG8_LAS unsigned*)(lds + (bufoff) + ldsw + _i * 8192), 16, 0, 0); } while (0)
; #define PG8_LDA(dst, b, h) do { _Pragma("unroll") for (int m = 0; m < 4; ++m) _Pragma("unroll") for (int k = 0; k < 2; ++k) dst[m][k] = *(const PG8_LAS bf16x8*)(lds + PG8_SA(b, h) + aoff + m * 2048 + k * 1024); } while (0)
; #define PG8_LDB(dst, b, h) do { _Pragma("unroll") for (int n = 0; n < 2; ++n) _Pragma("unroll") for (int k = 0; k < 2; ++k) dst[n][k] = *(const PG8_LAS bf16x8*)(lds + PG8_SB(b, h) + boff + n * 2048 + k * 1024); } while (0)
; #define PG8_MMA(ai, bj, At, Bt) do { __builtin_amdgcn_s_setprio(1); _Pragma("unroll") for (int m = 0; m < 4; ++m) _Pragma("unroll") for (int n = 0; n < 2; ++n) _Pragma("unroll") for (int k = 0; k < 2; ++k) \
;         acc[ai][bj][m][n] = __builtin_amdgcn_mfma_f32_16x16x32_bf16(Bt[n][k], At[m][k], acc[ai][bj][m][n], 0, 0, 0); __builtin_amdgcn_s_setprio(0); } while (0)
; #define PG8_WAIT_V(n) asm volatile("s_waitcnt vmcnt(" #n ")" ::: "memory")
; #define PG8_WAIT_L(n) asm volatile("s_waitcnt lgkmcnt(" #n ")" ::: "memory")
; #define PG8_BAR __builtin_amdgcn_s_barrier()
; #define PG8_SCHED __builtin_amdgcn_sched_barrier(0)
; template <class Epi, class Sched, bool ALIGN_EPI = false, bool SP2 = false>
; __device__ __forceinline__ void gemm_phase(PG8_LAS unsigned char* lds, const Gemm g, const Sched& S, const Epi& E) {
;     ...
;             PG8_LDB(B0, 1, 0); PG8_LDB(B1, 1, 1); PG8_SCHED; PG8_LDA(At, 1, 0); PG8_STAGE(PG8_SA(0, 1), a2 + hstep, voffA);
;             PG8_WAIT_V(8); PG8_WAIT_L(0); PG8_BAR; PG8_MMA(0, 0, At, B0); PG8_MMA(0, 1, At, B1); PG8_BAR; PG8_SCHED;
;             PG8_LDA(At, 1, 1); PG8_STAGE(PG8_SB(1, 0), b3, voffB); PG8_STAGE(PG8_SB(1, 1), b3 + hstep, voffB); PG8_STAGE(PG8_SA(1, 0), a3, voffA);
;             PG8_WAIT_V(8); PG8_WAIT_L(0); PG8_BAR; PG8_MMA(1, 0, At, B0); PG8_MMA(1, 1, At, B1); PG8_BAR; PG8_SCHED;
	ds_read_b128 v[142:145], v210 offset:32768
	ds_read_b128 v[150:153], v210 offset:33792
	ds_read_b128 v[154:157], v210 offset:34816
	ds_read_b128 v[158:161], v210 offset:35840
	ds_read_b128 v[162:165], v210 offset:49152
	ds_read_b128 v[166:169], v210 offset:50176
	ds_read_b128 v[170:173], v210 offset:51200
	ds_read_b128 v[174:177], v210 offset:52224
	s_add_u32 s26, s26, 0x100000
	s_addc_u32 s27, s27, 0
	s_mov_b32 m0, s25
	ds_read_b128 v[178:181], v149 offset:32768
	ds_read_b128 v[182:185], v149 offset:33792
	ds_read_b128 v[186:189], v149 offset:34816
	ds_read_b128 v[190:193], v149 offset:35840
	ds_read_b128 v[194:197], v149 offset:36864
	ds_read_b128 v[198:201], v149 offset:37888
	ds_read_b128 v[202:205], v149 offset:38912
	ds_read_b128 v[206:209], v149 offset:39936
	s_setprio 0
	s_add_i32 s63, 0, 0x18000
	s_add_i32 s64, 0, 0x1c000
	global_load_lds_dwordx4 v132, s[26:27]
	s_mov_b32 m0, s55
	s_nop 0
	global_load_lds_dwordx4 v134, s[26:27]
	s_setprio 1
	s_waitcnt vmcnt(8)
	s_waitcnt lgkmcnt(0)
	s_barrier
	v_mfma_f32_16x16x32_bf16 v[128:131], v[142:145], v[178:181], v[128:131]
	v_mfma_f32_16x16x32_bf16 v[128:131], v[150:153], v[182:185], v[128:131]
	v_mfma_f32_16x16x32_bf16 v[124:127], v[154:157], v[178:181], v[124:127]
	v_mfma_f32_16x16x32_bf16 v[124:127], v[158:161], v[182:185], v[124:127]
	v_mfma_f32_16x16x32_bf16 v[108:111], v[154:157], v[186:189], v[108:111]
	v_mfma_f32_16x16x32_bf16 v[108:111], v[158:161], v[190:193], v[108:111]
	v_mfma_f32_16x16x32_bf16 v[112:115], v[142:145], v[186:189], v[112:115]
	v_mfma_f32_16x16x32_bf16 v[112:115], v[150:153], v[190:193], v[112:115]
	v_mfma_f32_16x16x32_bf16 v[96:99], v[142:145], v[194:197], v[96:99]
	v_mfma_f32_16x16x32_bf16 v[96:99], v[150:153], v[198:201], v[96:99]
	v_mfma_f32_16x16x32_bf16 v[92:95], v[154:157], v[194:197], v[92:95]
	v_mfma_f32_16x16x32_bf16 v[92:95], v[158:161], v[198:201], v[92:95]
	v_mfma_f32_16x16x32_bf16 v[76:79], v[154:157], v[202:205], v[76:79]
	v_mfma_f32_16x16x32_bf16 v[76:79], v[158:161], v[206:209], v[76:79]
	v_mfma_f32_16x16x32_bf16 v[80:83], v[142:145], v[202:205], v[80:83]
	v_mfma_f32_16x16x32_bf16 v[80:83], v[150:153], v[206:209], v[80:83]
	s_setprio 0
	s_setprio 1
	v_mfma_f32_16x16x32_bf16 v[120:123], v[162:165], v[178:181], v[120:123]
	v_mfma_f32_16x16x32_bf16 v[120:123], v[166:169], v[182:185], v[120:123]
	v_mfma_f32_16x16x32_bf16 v[116:119], v[170:173], v[178:181], v[116:119]
	v_mfma_f32_16x16x32_bf16 v[116:119], v[174:177], v[182:185], v[116:119]
	v_mfma_f32_16x16x32_bf16 v[100:103], v[170:173], v[186:189], v[100:103]
	v_mfma_f32_16x16x32_bf16 v[100:103], v[174:177], v[190:193], v[100:103]
	v_mfma_f32_16x16x32_bf16 v[104:107], v[162:165], v[186:189], v[104:107]
	v_mfma_f32_16x16x32_bf16 v[104:107], v[166:169], v[190:193], v[104:107]
	v_mfma_f32_16x16x32_bf16 v[88:91], v[162:165], v[194:197], v[88:91]
	v_mfma_f32_16x16x32_bf16 v[88:91], v[166:169], v[198:201], v[88:91]
	v_mfma_f32_16x16x32_bf16 v[84:87], v[170:173], v[194:197], v[84:87]
	v_mfma_f32_16x16x32_bf16 v[84:87], v[174:177], v[198:201], v[84:87]
	v_mfma_f32_16x16x32_bf16 v[68:71], v[170:173], v[202:205], v[68:71]
	v_mfma_f32_16x16x32_bf16 v[68:71], v[174:177], v[206:209], v[68:71]
	v_mfma_f32_16x16x32_bf16 v[72:75], v[162:165], v[202:205], v[72:75]
	v_mfma_f32_16x16x32_bf16 v[72:75], v[166:169], v[206:209], v[72:75]
	s_barrier
	ds_read_b128 v[178:181], v149 offset:49152
	ds_read_b128 v[182:185], v149 offset:50176
	ds_read_b128 v[186:189], v149 offset:51200
	ds_read_b128 v[190:193], v149 offset:52224
	ds_read_b128 v[194:197], v149 offset:53248
	ds_read_b128 v[198:201], v149 offset:54272
	ds_read_b128 v[202:205], v149 offset:55296
	ds_read_b128 v[206:209], v149 offset:56320
	s_setprio 0
	s_add_i32 s26, s63, s9
	s_mov_b32 m0, s26
	s_add_u32 s0, s0, 0x80
	s_addc_u32 s1, s1, 0
	global_load_lds_dwordx4 v2, s[0:1]
	s_add_i32 m0, s26, 0x2000
	s_add_i32 s26, s64, s9
	global_load_lds_dwordx4 v136, s[0:1]
	s_add_u32 s0, s0, 0x100000
	s_addc_u32 s1, s1, 0
	s_mov_b32 m0, s26
	s_nop 0
	global_load_lds_dwordx4 v2, s[0:1]
	s_add_i32 m0, s26, 0x2000
	s_nop 0
	global_load_lds_dwordx4 v136, s[0:1]
	s_mov_b32 m0, s58
	s_nop 0
	global_load_lds_dwordx4 v132, s[100:101]
	s_mov_b32 m0, s59
	s_nop 0
	global_load_lds_dwordx4 v134, s[100:101]
	s_setprio 1
	s_waitcnt vmcnt(8)
	s_waitcnt lgkmcnt(0)
	s_barrier
	v_mfma_f32_16x16x32_bf16 v[64:67], v[142:145], v[178:181], v[64:67]
	v_mfma_f32_16x16x32_bf16 v[64:67], v[150:153], v[182:185], v[64:67]
	v_mfma_f32_16x16x32_bf16 v[60:63], v[154:157], v[178:181], v[60:63]
	v_mfma_f32_16x16x32_bf16 v[60:63], v[158:161], v[182:185], v[60:63]
	v_mfma_f32_16x16x32_bf16 v[44:47], v[154:157], v[186:189], v[44:47]
	v_mfma_f32_16x16x32_bf16 v[44:47], v[158:161], v[190:193], v[44:47]
	v_mfma_f32_16x16x32_bf16 v[48:51], v[142:145], v[186:189], v[48:51]
	v_mfma_f32_16x16x32_bf16 v[48:51], v[150:153], v[190:193], v[48:51]
	v_mfma_f32_16x16x32_bf16 v[32:35], v[142:145], v[194:197], v[32:35]
	v_mfma_f32_16x16x32_bf16 v[32:35], v[150:153], v[198:201], v[32:35]
	v_mfma_f32_16x16x32_bf16 v[28:31], v[154:157], v[194:197], v[28:31]
	v_mfma_f32_16x16x32_bf16 v[28:31], v[158:161], v[198:201], v[28:31]
	v_mfma_f32_16x16x32_bf16 v[12:15], v[154:157], v[202:205], v[12:15]
	v_mfma_f32_16x16x32_bf16 v[12:15], v[158:161], v[206:209], v[12:15]
	v_mfma_f32_16x16x32_bf16 v[16:19], v[142:145], v[202:205], v[16:19]
	v_mfma_f32_16x16x32_bf16 v[16:19], v[150:153], v[206:209], v[16:19]
	s_setprio 0
	s_setprio 1
	s_add_i32 s62, s62, 2
	s_add_u32 s56, s56, 0x100
	s_addc_u32 s57, s57, 0
	s_add_u32 s47, s47, 0x100
	s_addc_u32 s49, s49, 0
	s_nop 0
	v_mfma_f32_16x16x32_bf16 v[56:59], v[162:165], v[178:181], v[56:59]
	v_mfma_f32_16x16x32_bf16 v[56:59], v[166:169], v[182:185], v[56:59]
	v_mfma_f32_16x16x32_bf16 v[52:55], v[170:173], v[178:181], v[52:55]
	v_mfma_f32_16x16x32_bf16 v[52:55], v[174:177], v[182:185], v[52:55]
	v_mfma_f32_16x16x32_bf16 v[36:39], v[170:173], v[186:189], v[36:39]
	v_mfma_f32_16x16x32_bf16 v[36:39], v[174:177], v[190:193], v[36:39]
	v_mfma_f32_16x16x32_bf16 v[40:43], v[162:165], v[186:189], v[40:43]
	v_mfma_f32_16x16x32_bf16 v[40:43], v[166:169], v[190:193], v[40:43]
	v_mfma_f32_16x16x32_bf16 v[24:27], v[162:165], v[194:197], v[24:27]
	v_mfma_f32_16x16x32_bf16 v[24:27], v[166:169], v[198:201], v[24:27]
	v_mfma_f32_16x16x32_bf16 v[20:23], v[170:173], v[194:197], v[20:23]
	v_mfma_f32_16x16x32_bf16 v[20:23], v[174:177], v[198:201], v[20:23]
	v_mfma_f32_16x16x32_bf16 v[4:7], v[170:173], v[202:205], v[4:7]
	v_mfma_f32_16x16x32_bf16 v[4:7], v[174:177], v[206:209], v[4:7]
	v_mfma_f32_16x16x32_bf16 v[8:11], v[162:165], v[202:205], v[8:11]
	v_mfma_f32_16x16x32_bf16 v[8:11], v[166:169], v[206:209], v[8:11]
	s_barrier
	s_cmp_gt_u32 s62, 61
	s_cbranch_scc0 .LBB0_1624
	s_setprio 0
	s_and_b64 vcc, exec, s[44:45]
	s_cbranch_vccz .LBB0_1627
	s_barrier

; #define PG8_STAGE(bufoff, gbase, voff) do { _Pragma("unroll") for (int _i = 0; _i < 2; ++_i) \
;         __builtin_amdgcn_global_load_lds((const unsigned*)((const char*)(gbase) + (voff)[_i]), (PG8_LAS unsigned*)(lds + (bufoff) + ldsw + _i * 8192), 16, 0, 0); } while (0)
; #define PG8_LDA(dst, b, h) do { _Pragma("unroll") for (int m = 0; m < 4; ++m) _Pragma("unroll") for (int k = 0; k < 2; ++k) dst[m][k] = *(const PG8_LAS bf16x8*)(lds + PG8_SA(b, h) + aoff + m * 2048 + k * 1024); } while (0)
; #define PG8_LDB(dst, b, h) do { _Pragma("unroll") for (int n = 0; n < 2; ++n) _Pragma("unroll") for (int k = 0; k < 2; ++k) dst[n][k] = *(const PG8_LAS bf16x8*)(lds + PG8_SB(b, h) + boff + n * 2048 + k * 1024); } while (0)
; #define PG8_WAIT_V(n) asm volatile("s_waitcnt vmcnt(" #n ")" ::: "memory")
; #define PG8_WAIT_L(n) asm volatile("s_waitcnt lgkmcnt(" #n ")" ::: "memory")
; #define PG8_BAR __builtin_amdgcn_s_barrier()
; template <class Epi, class Sched, bool ALIGN_EPI = false, bool SP2 = false>
; __device__ __forceinline__ void gemm_phase(PG8_LAS unsigned char* lds, const Gemm g, const Sched& S, const Epi& E) {
;     ...
;         const bool has_next = S.next(ui + 1, nxt);
;         const char* nA = has_next ? (const char*)g.A + (size_t)nxt.pm * tstep + (size_t)nxt.kt0 * kstep : cA; const char* nB = has_next ? (const char*)g.Bt + (size_t)nxt.pn * tstep + (size_t)nxt.kt0 * kstep : cB;
;         const int nt = cur.nt;
;         for (int t = 0; t < nt; t += 2) {
;             const bool last = (t == nt - 2);
;             const char* a1 = cA + (size_t)(t + 1) * kstep;
;             const char* a2 = last ? nA : cA + (size_t)(t + 2) * kstep; const char* b2 = last ? nB : cB + (size_t)(t + 2) * kstep;
;             const char* a3 = a2 + kstep; const char* b3 = b2 + kstep;
;             if (last && has_next) S.a_ready(nxt);
;             if constexpr (SP2) {
;             PG8_LDB(B0, 0, 0); PG8_LDB(B1, 0, 1); PG8_SCHED; PG8_LDA(At, 0, 0); PG8_STAGE(PG8_SA(1, 1), a1 + hstep, voffA);
;             PG8_WAIT_V(8); PG8_WAIT_L(0); PG8_BAR; PG8_MMA(0, 0, At, B0); PG8_MMA(0, 1, At, B1); PG8_BAR; PG8_SCHED;
;             PG8_LDA(At, 0, 1); PG8_STAGE(PG8_SB(0, 0), b2, voffB); PG8_STAGE(PG8_SB(0, 1), b2 + hstep, voffB); PG8_STAGE(PG8_SA(0, 0), a2, voffA);
;             PG8_WAIT_V(8); PG8_WAIT_L(0); PG8_BAR; PG8_MMA(1, 0, At, B0); PG8_MMA(1, 1, At, B1); PG8_BAR; PG8_SCHED;
.LBB0_2089:
	ds_read_b128 v[142:145], v210
	ds_read_b128 v[146:149], v210 offset:1024
	ds_read_b128 v[154:157], v210 offset:2048
	ds_read_b128 v[158:161], v210 offset:3072
	ds_read_b128 v[162:165], v210 offset:16384
	ds_read_b128 v[166:169], v210 offset:17408
	ds_read_b128 v[170:173], v210 offset:18432
	ds_read_b128 v[174:177], v210 offset:19456
	s_add_i32 m0, s10, 0xc000
	ds_read_b128 v[178:181], v153
	ds_read_b128 v[182:185], v153 offset:1024
	ds_read_b128 v[186:189], v153 offset:2048
	ds_read_b128 v[190:193], v153 offset:3072
	ds_read_b128 v[194:197], v153 offset:4096
	ds_read_b128 v[198:201], v153 offset:5120
	ds_read_b128 v[202:205], v153 offset:6144
	ds_read_b128 v[206:209], v153 offset:7168
	s_setprio 0
	s_add_u32 s0, s50, 0xfff00080
	s_addc_u32 s1, s51, -1
	s_add_i32 s61, 0, 0x10000
	s_cmp_eq_u32 s60, 60
	s_cselect_b32 s27, s47, s1
	s_cselect_b32 s26, s46, s0
	s_cselect_b32 s1, s49, s45
	s_cselect_b32 s0, s48, s43
	s_add_i32 s64, 0, 0x14000
	global_load_lds_dwordx4 v138, s[50:51]
	s_add_i32 m0, s10, 0xe000
	s_nop 0
	global_load_lds_dwordx4 v140, s[50:51]
	s_setprio 1
	s_waitcnt vmcnt(8)
	s_waitcnt lgkmcnt(0)
	s_barrier
	v_mfma_f32_16x16x32_bf16 v[128:131], v[142:145], v[178:181], v[128:131]
	v_mfma_f32_16x16x32_bf16 v[128:131], v[146:149], v[182:185], v[128:131]
	v_mfma_f32_16x16x32_bf16 v[124:127], v[154:157], v[178:181], v[124:127]
	v_mfma_f32_16x16x32_bf16 v[124:127], v[158:161], v[182:185], v[124:127]
	v_mfma_f32_16x16x32_bf16 v[108:111], v[154:157], v[186:189], v[108:111]
	v_mfma_f32_16x16x32_bf16 v[108:111], v[158:161], v[190:193], v[108:111]
	v_mfma_f32_16x16x32_bf16 v[112:115], v[142:145], v[186:189], v[112:115]
	v_mfma_f32_16x16x32_bf16 v[112:115], v[146:149], v[190:193], v[112:115]
	v_mfma_f32_16x16x32_bf16 v[96:99], v[142:145], v[194:197], v[96:99]
	v_mfma_f32_16x16x32_bf16 v[96:99], v[146:149], v[198:201], v[96:99]
	v_mfma_f32_16x16x32_bf16 v[92:95], v[154:157], v[194:197], v[92:95]
	v_mfma_f32_16x16x32_bf16 v[92:95], v[158:161], v[198:201], v[92:95]
	v_mfma_f32_16x16x32_bf16 v[76:79], v[154:157], v[202:205], v[76:79]
	v_mfma_f32_16x16x32_bf16 v[76:79], v[158:161], v[206:209], v[76:79]
	v_mfma_f32_16x16x32_bf16 v[80:83], v[142:145], v[202:205], v[80:83]
	v_mfma_f32_16x16x32_bf16 v[80:83], v[146:149], v[206:209], v[80:83]
	s_setprio 0
	s_setprio 1
	v_mfma_f32_16x16x32_bf16 v[120:123], v[162:165], v[178:181], v[120:123]
	v_mfma_f32_16x16x32_bf16 v[120:123], v[166:169], v[182:185], v[120:123]
	v_mfma_f32_16x16x32_bf16 v[116:119], v[170:173], v[178:181], v[116:119]
	v_mfma_f32_16x16x32_bf16 v[116:119], v[174:177], v[182:185], v[116:119]
	v_mfma_f32_16x16x32_bf16 v[100:103], v[170:173], v[186:189], v[100:103]
	v_mfma_f32_16x16x32_bf16 v[100:103], v[174:177], v[190:193], v[100:103]
	v_mfma_f32_16x16x32_bf16 v[104:107], v[162:165], v[186:189], v[104:107]
	v_mfma_f32_16x16x32_bf16 v[104:107], v[166:169], v[190:193], v[104:107]
	v_mfma_f32_16x16x32_bf16 v[88:91], v[162:165], v[194:197], v[88:91]
	v_mfma_f32_16x16x32_bf16 v[88:91], v[166:169], v[198:201], v[88:91]
	v_mfma_f32_16x16x32_bf16 v[84:87], v[170:173], v[194:197], v[84:87]
	v_mfma_f32_16x16x32_bf16 v[84:87], v[174:177], v[198:201], v[84:87]
	v_mfma_f32_16x16x32_bf16 v[68:71], v[170:173], v[202:205], v[68:71]
	v_mfma_f32_16x16x32_bf16 v[68:71], v[174:177], v[206:209], v[68:71]
	v_mfma_f32_16x16x32_bf16 v[72:75], v[162:165], v[202:205], v[72:75]
	v_mfma_f32_16x16x32_bf16 v[72:75], v[166:169], v[206:209], v[72:75]
	s_barrier
	ds_read_b128 v[178:181], v153 offset:16384
	ds_read_b128 v[182:185], v153 offset:17408
	ds_read_b128 v[186:189], v153 offset:18432
	ds_read_b128 v[190:193], v153 offset:19456
	ds_read_b128 v[194:197], v153 offset:20480
	ds_read_b128 v[198:201], v153 offset:21504
	ds_read_b128 v[202:205], v153 offset:22528
	ds_read_b128 v[206:209], v153 offset:23552
	s_setprio 0
	s_add_i32 s61, s61, s9
	s_mov_b32 m0, s61
	s_nop 0
	global_load_lds_dwordx4 v2, s[0:1]
	s_add_i32 m0, s61, 0x2000
	s_add_u32 s62, s0, 0x100000
	s_addc_u32 s63, s1, 0
	s_add_i32 s61, s64, s9
	global_load_lds_dwordx4 v132, s[0:1]
	s_mov_b32 m0, s61
	s_nop 0
	global_load_lds_dwordx4 v2, s[62:63]
	s_add_i32 m0, s61, 0x2000
	s_nop 0
	global_load_lds_dwordx4 v132, s[62:63]
	s_mov_b32 m0, s10
	s_nop 0
	global_load_lds_dwordx4 v136, s[26:27]
	s_mov_b32 m0, s11
	s_nop 0
	global_load_lds_dwordx4 v134, s[26:27]
	s_nop 0
	s_add_u32 s100, s26, 0x80
	s_addc_u32 s101, s27, 0
	s_setprio 1
	s_waitcnt vmcnt(8)
	s_waitcnt lgkmcnt(0)
	s_barrier
	v_mfma_f32_16x16x32_bf16 v[64:67], v[142:145], v[178:181], v[64:67]
	v_mfma_f32_16x16x32_bf16 v[64:67], v[146:149], v[182:185], v[64:67]
	v_mfma_f32_16x16x32_bf16 v[60:63], v[154:157], v[178:181], v[60:63]
	v_mfma_f32_16x16x32_bf16 v[60:63], v[158:161], v[182:185], v[60:63]
	v_mfma_f32_16x16x32_bf16 v[44:47], v[154:157], v[186:189], v[44:47]
	v_mfma_f32_16x16x32_bf16 v[44:47], v[158:161], v[190:193], v[44:47]
	v_mfma_f32_16x16x32_bf16 v[48:51], v[142:145], v[186:189], v[48:51]
	v_mfma_f32_16x16x32_bf16 v[48:51], v[146:149], v[190:193], v[48:51]
	v_mfma_f32_16x16x32_bf16 v[32:35], v[142:145], v[194:197], v[32:35]
	v_mfma_f32_16x16x32_bf16 v[32:35], v[146:149], v[198:201], v[32:35]
	v_mfma_f32_16x16x32_bf16 v[28:31], v[154:157], v[194:197], v[28:31]
	v_mfma_f32_16x16x32_bf16 v[28:31], v[158:161], v[198:201], v[28:31]
	v_mfma_f32_16x16x32_bf16 v[12:15], v[154:157], v[202:205], v[12:15]
	v_mfma_f32_16x16x32_bf16 v[12:15], v[158:161], v[206:209], v[12:15]
	v_mfma_f32_16x16x32_bf16 v[16:19], v[142:145], v[202:205], v[16:19]
	v_mfma_f32_16x16x32_bf16 v[16:19], v[146:149], v[206:209], v[16:19]
	s_setprio 0
	s_setprio 1
	v_mfma_f32_16x16x32_bf16 v[56:59], v[162:165], v[178:181], v[56:59]
	v_mfma_f32_16x16x32_bf16 v[56:59], v[166:169], v[182:185], v[56:59]
	v_mfma_f32_16x16x32_bf16 v[52:55], v[170:173], v[178:181], v[52:55]
	v_mfma_f32_16x16x32_bf16 v[52:55], v[174:177], v[182:185], v[52:55]
	v_mfma_f32_16x16x32_bf16 v[36:39], v[170:173], v[186:189], v[36:39]
	v_mfma_f32_16x16x32_bf16 v[36:39], v[174:177], v[190:193], v[36:39]
	v_mfma_f32_16x16x32_bf16 v[40:43], v[162:165], v[186:189], v[40:43]
	v_mfma_f32_16x16x32_bf16 v[40:43], v[166:169], v[190:193], v[40:43]
	v_mfma_f32_16x16x32_bf16 v[24:27], v[162:165], v[194:197], v[24:27]
	v_mfma_f32_16x16x32_bf16 v[24:27], v[166:169], v[198:201], v[24:27]
	v_mfma_f32_16x16x32_bf16 v[20:23], v[170:173], v[194:197], v[20:23]
	v_mfma_f32_16x16x32_bf16 v[20:23], v[174:177], v[198:201], v[20:23]
	v_mfma_f32_16x16x32_bf16 v[4:7], v[170:173], v[202:205], v[4:7]
	v_mfma_f32_16x16x32_bf16 v[4:7], v[174:177], v[206:209], v[4:7]
	v_mfma_f32_16x16x32_bf16 v[8:11], v[162:165], v[202:205], v[8:11]
	v_mfma_f32_16x16x32_bf16 v[8:11], v[166:169], v[206:209], v[8:11]
	s_barrier
; #define PG8_STAGE(bufoff, gbase, voff) do { _Pragma("unroll") for (int _i = 0; _i < 2; ++_i) \
;         __builtin_amdgcn_global_load_lds((const unsigned*)((const char*)(gbase) + (voff)[_i]), (PG8_LAS unsigned*)(lds + (bufoff) + ldsw + _i * 8192), 16, 0, 0); } while (0)
; #define PG8_LDA(dst, b, h) do { _Pragma("unroll") for (int m = 0; m < 4; ++m) _Pragma("unroll") for (int k = 0; k < 2; ++k) dst[m][k] = *(const PG8_LAS bf16x8*)(lds + PG8_SA(b, h) + aoff + m * 2048 + k * 1024); } while (0)
; #define PG8_LDB(dst, b, h) do { _Pragma("unroll") for (int n = 0; n < 2; ++n) _Pragma("unroll") for (int k = 0; k < 2; ++k) dst[n][k] = *(const PG8_LAS bf16x8*)(lds + PG8_SB(b, h) + boff + n * 2048 + k * 1024); } while (0)
; #define PG8_MMA(ai, bj, At, Bt) do { __builtin_amdgcn_s_setprio(1); _Pragma("unroll") for (int m = 0; m < 4; ++m) _Pragma("unroll") for (int n = 0; n < 2; ++n) _Pragma("unroll") for (int k = 0; k < 2; ++k) \
;         acc[ai][bj][m][n] = __builtin_amdgcn_mfma_f32_16x16x32_bf16(Bt[n][k], At[m][k], acc[ai][bj][m][n], 0, 0, 0); __builtin_amdgcn_s_setprio(0); } while (0)
; #define PG8_WAIT_V(n) asm volatile("s_waitcnt vmcnt(" #n ")" ::: "memory")
; #define PG8_WAIT_L(n) asm volatile("s_waitcnt lgkmcnt(" #n ")" ::: "memory")
; #define PG8_BAR __builtin_amdgcn_s_barrier()
; #define PG8_SCHED __builtin_amdgcn_sched_barrier(0)
; template <class Epi, class Sched, bool ALIGN_EPI = false, bool SP2 = false>
; __device__ __forceinline__ void gemm_phase(PG8_LAS unsigned char* lds, const Gemm g, const Sched& S, const Epi& E) {
;     ...
;             PG8_LDB(B0, 1, 0); PG8_LDB(B1, 1, 1); PG8_SCHED; PG8_LDA(At, 1, 0); PG8_STAGE(PG8_SA(0, 1), a2 + hstep, voffA);
;             PG8_WAIT_V(8); PG8_WAIT_L(0); PG8_BAR; PG8_MMA(0, 0, At, B0); PG8_MMA(0, 1, At, B1); PG8_BAR; PG8_SCHED;
;             PG8_LDA(At, 1, 1); PG8_STAGE(PG8_SB(1, 0), b3, voffB); PG8_STAGE(PG8_SB(1, 1), b3 + hstep, voffB); PG8_STAGE(PG8_SA(1, 0), a3, voffA);
;             PG8_WAIT_V(8); PG8_WAIT_L(0); PG8_BAR; PG8_MMA(1, 0, At, B0); PG8_MMA(1, 1, At, B1); PG8_BAR; PG8_SCHED;
	ds_read_b128 v[142:145], v210 offset:32768
	ds_read_b128 v[146:149], v210 offset:33792
	ds_read_b128 v[154:157], v210 offset:34816
	ds_read_b128 v[158:161], v210 offset:35840
	ds_read_b128 v[162:165], v210 offset:49152
	ds_read_b128 v[166:169], v210 offset:50176
	ds_read_b128 v[170:173], v210 offset:51200
	ds_read_b128 v[174:177], v210 offset:52224
	s_add_u32 s26, s26, 0x100000
	s_addc_u32 s27, s27, 0
	s_mov_b32 m0, s52
	ds_read_b128 v[178:181], v153 offset:32768
	ds_read_b128 v[182:185], v153 offset:33792
	ds_read_b128 v[186:189], v153 offset:34816
	ds_read_b128 v[190:193], v153 offset:35840
	ds_read_b128 v[194:197], v153 offset:36864
	ds_read_b128 v[198:201], v153 offset:37888
	ds_read_b128 v[202:205], v153 offset:38912
	ds_read_b128 v[206:209], v153 offset:39936
	s_setprio 0
	s_add_i32 s61, 0, 0x18000
	s_add_i32 s62, 0, 0x1c000
	global_load_lds_dwordx4 v136, s[26:27]
	s_mov_b32 m0, s53
	s_nop 0
	global_load_lds_dwordx4 v134, s[26:27]
	s_setprio 1
	s_waitcnt vmcnt(8)
	s_waitcnt lgkmcnt(0)
	s_barrier
	v_mfma_f32_16x16x32_bf16 v[128:131], v[142:145], v[178:181], v[128:131]
	v_mfma_f32_16x16x32_bf16 v[128:131], v[146:149], v[182:185], v[128:131]
	v_mfma_f32_16x16x32_bf16 v[124:127], v[154:157], v[178:181], v[124:127]
	v_mfma_f32_16x16x32_bf16 v[124:127], v[158:161], v[182:185], v[124:127]
	v_mfma_f32_16x16x32_bf16 v[108:111], v[154:157], v[186:189], v[108:111]
	v_mfma_f32_16x16x32_bf16 v[108:111], v[158:161], v[190:193], v[108:111]
	v_mfma_f32_16x16x32_bf16 v[112:115], v[142:145], v[186:189], v[112:115]
	v_mfma_f32_16x16x32_bf16 v[112:115], v[146:149], v[190:193], v[112:115]
	v_mfma_f32_16x16x32_bf16 v[96:99], v[142:145], v[194:197], v[96:99]
	v_mfma_f32_16x16x32_bf16 v[96:99], v[146:149], v[198:201], v[96:99]
	v_mfma_f32_16x16x32_bf16 v[92:95], v[154:157], v[194:197], v[92:95]
	v_mfma_f32_16x16x32_bf16 v[92:95], v[158:161], v[198:201], v[92:95]
	v_mfma_f32_16x16x32_bf16 v[76:79], v[154:157], v[202:205], v[76:79]
	v_mfma_f32_16x16x32_bf16 v[76:79], v[158:161], v[206:209], v[76:79]
	v_mfma_f32_16x16x32_bf16 v[80:83], v[142:145], v[202:205], v[80:83]
	v_mfma_f32_16x16x32_bf16 v[80:83], v[146:149], v[206:209], v[80:83]
	s_setprio 0
	s_setprio 1
	v_mfma_f32_16x16x32_bf16 v[120:123], v[162:165], v[178:181], v[120:123]
	v_mfma_f32_16x16x32_bf16 v[120:123], v[166:169], v[182:185], v[120:123]
	v_mfma_f32_16x16x32_bf16 v[116:119], v[170:173], v[178:181], v[116:119]
	v_mfma_f32_16x16x32_bf16 v[116:119], v[174:177], v[182:185], v[116:119]
	v_mfma_f32_16x16x32_bf16 v[100:103], v[170:173], v[186:189], v[100:103]
	v_mfma_f32_16x16x32_bf16 v[100:103], v[174:177], v[190:193], v[100:103]
	v_mfma_f32_16x16x32_bf16 v[104:107], v[162:165], v[186:189], v[104:107]
	v_mfma_f32_16x16x32_bf16 v[104:107], v[166:169], v[190:193], v[104:107]
	v_mfma_f32_16x16x32_bf16 v[88:91], v[162:165], v[194:197], v[88:91]
	v_mfma_f32_16x16x32_bf16 v[88:91], v[166:169], v[198:201], v[88:91]
	v_mfma_f32_16x16x32_bf16 v[84:87], v[170:173], v[194:197], v[84:87]
	v_mfma_f32_16x16x32_bf16 v[84:87], v[174:177], v[198:201], v[84:87]
	v_mfma_f32_16x16x32_bf16 v[68:71], v[170:173], v[202:205], v[68:71]
	v_mfma_f32_16x16x32_bf16 v[68:71], v[174:177], v[206:209], v[68:71]
	v_mfma_f32_16x16x32_bf16 v[72:75], v[162:165], v[202:205], v[72:75]
	v_mfma_f32_16x16x32_bf16 v[72:75], v[166:169], v[206:209], v[72:75]
	s_barrier
	ds_read_b128 v[178:181], v153 offset:49152
	ds_read_b128 v[182:185], v153 offset:50176
	ds_read_b128 v[186:189], v153 offset:51200
	ds_read_b128 v[190:193], v153 offset:52224
	ds_read_b128 v[194:197], v153 offset:53248
	ds_read_b128 v[198:201], v153 offset:54272
	ds_read_b128 v[202:205], v153 offset:55296
	ds_read_b128 v[206:209], v153 offset:56320
	s_setprio 0
	s_add_i32 s26, s61, s9
	s_mov_b32 m0, s26
	s_add_u32 s0, s0, 0x80
	s_addc_u32 s1, s1, 0
	global_load_lds_dwordx4 v2, s[0:1]
	s_add_i32 m0, s26, 0x2000
	s_add_i32 s26, s62, s9
	global_load_lds_dwordx4 v132, s[0:1]
	s_add_u32 s0, s0, 0x100000
	s_addc_u32 s1, s1, 0
	s_mov_b32 m0, s26
	s_nop 0
	global_load_lds_dwordx4 v2, s[0:1]
	s_add_i32 m0, s26, 0x2000
	s_nop 0
	global_load_lds_dwordx4 v132, s[0:1]
	s_mov_b32 m0, s54
	s_nop 0
	global_load_lds_dwordx4 v136, s[100:101]
	s_mov_b32 m0, s55
	s_nop 0
	global_load_lds_dwordx4 v134, s[100:101]
	s_setprio 1
	s_waitcnt vmcnt(8)
	s_waitcnt lgkmcnt(0)
	s_barrier
	v_mfma_f32_16x16x32_bf16 v[64:67], v[142:145], v[178:181], v[64:67]
	v_mfma_f32_16x16x32_bf16 v[64:67], v[146:149], v[182:185], v[64:67]
	v_mfma_f32_16x16x32_bf16 v[60:63], v[154:157], v[178:181], v[60:63]
	v_mfma_f32_16x16x32_bf16 v[60:63], v[158:161], v[182:185], v[60:63]
	v_mfma_f32_16x16x32_bf16 v[44:47], v[154:157], v[186:189], v[44:47]
	v_mfma_f32_16x16x32_bf16 v[44:47], v[158:161], v[190:193], v[44:47]
	v_mfma_f32_16x16x32_bf16 v[48:51], v[142:145], v[186:189], v[48:51]
	v_mfma_f32_16x16x32_bf16 v[48:51], v[146:149], v[190:193], v[48:51]
	v_mfma_f32_16x16x32_bf16 v[32:35], v[142:145], v[194:197], v[32:35]
	v_mfma_f32_16x16x32_bf16 v[32:35], v[146:149], v[198:201], v[32:35]
	v_mfma_f32_16x16x32_bf16 v[28:31], v[154:157], v[194:197], v[28:31]
	v_mfma_f32_16x16x32_bf16 v[28:31], v[158:161], v[198:201], v[28:31]
	v_mfma_f32_16x16x32_bf16 v[12:15], v[154:157], v[202:205], v[12:15]
	v_mfma_f32_16x16x32_bf16 v[12:15], v[158:161], v[206:209], v[12:15]
	v_mfma_f32_16x16x32_bf16 v[16:19], v[142:145], v[202:205], v[16:19]
	v_mfma_f32_16x16x32_bf16 v[16:19], v[146:149], v[206:209], v[16:19]
	s_setprio 0
	s_setprio 1
	s_add_i32 s60, s60, 2
	s_add_u32 s50, s50, 0x100
	s_addc_u32 s51, s51, 0
	s_add_u32 s43, s43, 0x100
	s_addc_u32 s45, s45, 0
	s_nop 0
	v_mfma_f32_16x16x32_bf16 v[56:59], v[162:165], v[178:181], v[56:59]
	v_mfma_f32_16x16x32_bf16 v[56:59], v[166:169], v[182:185], v[56:59]
	v_mfma_f32_16x16x32_bf16 v[52:55], v[170:173], v[178:181], v[52:55]
	v_mfma_f32_16x16x32_bf16 v[52:55], v[174:177], v[182:185], v[52:55]
	v_mfma_f32_16x16x32_bf16 v[36:39], v[170:173], v[186:189], v[36:39]
	v_mfma_f32_16x16x32_bf16 v[36:39], v[174:177], v[190:193], v[36:39]
	v_mfma_f32_16x16x32_bf16 v[40:43], v[162:165], v[186:189], v[40:43]
	v_mfma_f32_16x16x32_bf16 v[40:43], v[166:169], v[190:193], v[40:43]
	v_mfma_f32_16x16x32_bf16 v[24:27], v[162:165], v[194:197], v[24:27]
	v_mfma_f32_16x16x32_bf16 v[24:27], v[166:169], v[198:201], v[24:27]
	v_mfma_f32_16x16x32_bf16 v[20:23], v[170:173], v[194:197], v[20:23]
	v_mfma_f32_16x16x32_bf16 v[20:23], v[174:177], v[198:201], v[20:23]
	v_mfma_f32_16x16x32_bf16 v[4:7], v[170:173], v[202:205], v[4:7]
	v_mfma_f32_16x16x32_bf16 v[4:7], v[174:177], v[206:209], v[4:7]
	v_mfma_f32_16x16x32_bf16 v[8:11], v[162:165], v[202:205], v[8:11]
	v_mfma_f32_16x16x32_bf16 v[8:11], v[166:169], v[206:209], v[8:11]
	s_barrier
	s_cmp_gt_u32 s60, 61
	s_cbranch_scc0 .LBB0_2089
	s_setprio 0
	s_and_b64 vcc, exec, s[40:41]
	s_cbranch_vccz .LBB0_2092
	s_barrier

; #define PG8_STAGE(bufoff, gbase, voff) do { _Pragma("unroll") for (int _i = 0; _i < 2; ++_i) \
;         __builtin_amdgcn_global_load_lds((const unsigned*)((const char*)(gbase) + (voff)[_i]), (PG8_LAS unsigned*)(lds + (bufoff) + ldsw + _i * 8192), 16, 0, 0); } while (0)
; #define PG8_LDA(dst, b, h) do { _Pragma("unroll") for (int m = 0; m < 4; ++m) _Pragma("unroll") for (int k = 0; k < 2; ++k) dst[m][k] = *(const PG8_LAS bf16x8*)(lds + PG8_SA(b, h) + aoff + m * 2048 + k * 1024); } while (0)
; #define PG8_LDB(dst, b, h) do { _Pragma("unroll") for (int n = 0; n < 2; ++n) _Pragma("unroll") for (int k = 0; k < 2; ++k) dst[n][k] = *(const PG8_LAS bf16x8*)(lds + PG8_SB(b, h) + boff + n * 2048 + k * 1024); } while (0)
; #define PG8_WAIT_V(n) asm volatile("s_waitcnt vmcnt(" #n ")" ::: "memory")
; #define PG8_WAIT_L(n) asm volatile("s_waitcnt lgkmcnt(" #n ")" ::: "memory")
; #define PG8_BAR __builtin_amdgcn_s_barrier()
; template <class Epi, class Sched, bool ALIGN_EPI = false, bool SP2 = false>
; __device__ __forceinline__ void gemm_phase(PG8_LAS unsigned char* lds, const Gemm g, const Sched& S, const Epi& E) {
;     ...
;         const bool has_next = S.next(ui + 1, nxt);
;         const char* nA = has_next ? (const char*)g.A + (size_t)nxt.pm * tstep + (size_t)nxt.kt0 * kstep : cA; const char* nB = has_next ? (const char*)g.Bt + (size_t)nxt.pn * tstep + (size_t)nxt.kt0 * kstep : cB;
;         const int nt = cur.nt;
;         for (int t = 0; t < nt; t += 2) {
;             const bool last = (t == nt - 2);
;             const char* a1 = cA + (size_t)(t + 1) * kstep;
;             const char* a2 = last ? nA : cA + (size_t)(t + 2) * kstep; const char* b2 = last ? nB : cB + (size_t)(t + 2) * kstep;
;             const char* a3 = a2 + kstep; const char* b3 = b2 + kstep;
;             if (last && has_next) S.a_ready(nxt);
;             if constexpr (SP2) {
;             PG8_LDB(B0, 0, 0); PG8_LDB(B1, 0, 1); PG8_SCHED; PG8_LDA(At, 0, 0); PG8_STAGE(PG8_SA(1, 1), a1 + hstep, voffA);
;             PG8_WAIT_V(8); PG8_WAIT_L(0); PG8_BAR; PG8_MMA(0, 0, At, B0); PG8_MMA(0, 1, At, B1); PG8_BAR; PG8_SCHED;
;             PG8_LDA(At, 0, 1); PG8_STAGE(PG8_SB(0, 0), b2, voffB); PG8_STAGE(PG8_SB(0, 1), b2 + hstep, voffB); PG8_STAGE(PG8_SA(0, 0), a2, voffA);
;             PG8_WAIT_V(8); PG8_WAIT_L(0); PG8_BAR; PG8_MMA(1, 0, At, B0); PG8_MMA(1, 1, At, B1); PG8_BAR; PG8_SCHED;
.LBB0_2115:
	s_waitcnt vmcnt(0)
	ds_read_b128 v[132:135], v188
	ds_read_b128 v[136:139], v188 offset:1024
	ds_read_b128 v[152:155], v188 offset:2048
	ds_read_b128 v[156:159], v188 offset:3072
	ds_read_b128 v[160:163], v188 offset:16384
	ds_read_b128 v[164:167], v188 offset:17408
	ds_read_b128 v[168:171], v188 offset:18432
	ds_read_b128 v[172:175], v188 offset:19456
	s_add_i32 m0, s11, 0xc000
	ds_read_b128 v[176:179], v194
	ds_read_b128 v[180:183], v194 offset:1024
	ds_read_b128 v[184:187], v194 offset:2048
	ds_read_b128 v[196:199], v194 offset:3072
	ds_read_b128 v[200:203], v194 offset:4096
	ds_read_b128 v[204:207], v194 offset:5120
	ds_read_b128 v[208:211], v194 offset:6144
	ds_read_b128 v[212:215], v194 offset:7168
	s_setprio 0
	s_add_u32 s0, s40, 0xfff00080
	s_addc_u32 s1, s41, -1
	s_add_i32 s77, 0, 0x10000
	s_cmp_eq_u32 s76, 60
	s_cselect_b32 s27, s49, s1
	s_cselect_b32 s26, s57, s0
	s_cselect_b32 s1, s47, s59
	s_cselect_b32 s0, s73, s58
	s_add_i32 s80, 0, 0x14000
	global_load_lds_dwordx4 v148, s[40:41]
	s_add_i32 m0, s11, 0xe000
	s_nop 0
	global_load_lds_dwordx4 v150, s[40:41]
	s_nop 0
	s_setprio 1
	s_waitcnt vmcnt(8)
	s_waitcnt lgkmcnt(0)
	s_barrier
	v_mfma_f32_16x16x32_bf16 v[128:131], v[132:135], v[176:179], v[128:131]
	v_mfma_f32_16x16x32_bf16 v[128:131], v[136:139], v[180:183], v[128:131]
	v_mfma_f32_16x16x32_bf16 v[124:127], v[152:155], v[176:179], v[124:127]
	v_mfma_f32_16x16x32_bf16 v[124:127], v[156:159], v[180:183], v[124:127]
	v_mfma_f32_16x16x32_bf16 v[108:111], v[152:155], v[184:187], v[108:111]
	v_mfma_f32_16x16x32_bf16 v[108:111], v[156:159], v[196:199], v[108:111]
	v_mfma_f32_16x16x32_bf16 v[112:115], v[132:135], v[184:187], v[112:115]
	v_mfma_f32_16x16x32_bf16 v[112:115], v[136:139], v[196:199], v[112:115]
	v_mfma_f32_16x16x32_bf16 v[96:99], v[132:135], v[200:203], v[96:99]
	v_mfma_f32_16x16x32_bf16 v[96:99], v[136:139], v[204:207], v[96:99]
	v_mfma_f32_16x16x32_bf16 v[92:95], v[152:155], v[200:203], v[92:95]
	v_mfma_f32_16x16x32_bf16 v[92:95], v[156:159], v[204:207], v[92:95]
	v_mfma_f32_16x16x32_bf16 v[76:79], v[152:155], v[208:211], v[76:79]
	v_mfma_f32_16x16x32_bf16 v[76:79], v[156:159], v[212:215], v[76:79]
	v_mfma_f32_16x16x32_bf16 v[80:83], v[132:135], v[208:211], v[80:83]
	v_mfma_f32_16x16x32_bf16 v[80:83], v[136:139], v[212:215], v[80:83]
	s_setprio 0
	s_setprio 1
	v_mfma_f32_16x16x32_bf16 v[120:123], v[160:163], v[176:179], v[120:123]
	v_mfma_f32_16x16x32_bf16 v[120:123], v[164:167], v[180:183], v[120:123]
	v_mfma_f32_16x16x32_bf16 v[116:119], v[168:171], v[176:179], v[116:119]
	v_mfma_f32_16x16x32_bf16 v[116:119], v[172:175], v[180:183], v[116:119]
	v_mfma_f32_16x16x32_bf16 v[100:103], v[168:171], v[184:187], v[100:103]
	v_mfma_f32_16x16x32_bf16 v[100:103], v[172:175], v[196:199], v[100:103]
	v_mfma_f32_16x16x32_bf16 v[104:107], v[160:163], v[184:187], v[104:107]
	v_mfma_f32_16x16x32_bf16 v[104:107], v[164:167], v[196:199], v[104:107]
	v_mfma_f32_16x16x32_bf16 v[88:91], v[160:163], v[200:203], v[88:91]
	v_mfma_f32_16x16x32_bf16 v[88:91], v[164:167], v[204:207], v[88:91]
	v_mfma_f32_16x16x32_bf16 v[84:87], v[168:171], v[200:203], v[84:87]
	v_mfma_f32_16x16x32_bf16 v[84:87], v[172:175], v[204:207], v[84:87]
	v_mfma_f32_16x16x32_bf16 v[68:71], v[168:171], v[208:211], v[68:71]
	v_mfma_f32_16x16x32_bf16 v[68:71], v[172:175], v[212:215], v[68:71]
	v_mfma_f32_16x16x32_bf16 v[72:75], v[160:163], v[208:211], v[72:75]
	v_mfma_f32_16x16x32_bf16 v[72:75], v[164:167], v[212:215], v[72:75]
	s_barrier
	ds_read_b128 v[176:179], v194 offset:16384
	ds_read_b128 v[180:183], v194 offset:17408
	ds_read_b128 v[184:187], v194 offset:18432
	ds_read_b128 v[196:199], v194 offset:19456
	ds_read_b128 v[200:203], v194 offset:20480
	ds_read_b128 v[204:207], v194 offset:21504
	ds_read_b128 v[208:211], v194 offset:22528
	ds_read_b128 v[212:215], v194 offset:23552
	s_setprio 0
	s_add_i32 s77, s77, s10
	s_mov_b32 m0, s77
	s_nop 0
	global_load_lds_dwordx4 v2, s[0:1]
	s_add_i32 m0, s77, 0x2000
	s_add_u32 s78, s0, 0x100000
	s_addc_u32 s79, s1, 0
	s_add_i32 s77, s80, s10
	global_load_lds_dwordx4 v144, s[0:1]
	s_mov_b32 m0, s77
	s_nop 0
	global_load_lds_dwordx4 v2, s[78:79]
	s_add_i32 m0, s77, 0x2000
	s_nop 0
	global_load_lds_dwordx4 v144, s[78:79]
	s_mov_b32 m0, s11
	s_nop 0
	global_load_lds_dwordx4 v140, s[26:27]
	s_mov_b32 m0, s55
	s_nop 0
	global_load_lds_dwordx4 v142, s[26:27]
	s_nop 0
	s_add_u32 s100, s26, 0x80
	s_addc_u32 s101, s27, 0
	s_setprio 1
	s_waitcnt vmcnt(8)
	s_waitcnt lgkmcnt(0)
	s_barrier
	v_mfma_f32_16x16x32_bf16 v[64:67], v[132:135], v[176:179], v[64:67]
	v_mfma_f32_16x16x32_bf16 v[64:67], v[136:139], v[180:183], v[64:67]
	v_mfma_f32_16x16x32_bf16 v[60:63], v[152:155], v[176:179], v[60:63]
	v_mfma_f32_16x16x32_bf16 v[60:63], v[156:159], v[180:183], v[60:63]
	v_mfma_f32_16x16x32_bf16 v[44:47], v[152:155], v[184:187], v[44:47]
	v_mfma_f32_16x16x32_bf16 v[44:47], v[156:159], v[196:199], v[44:47]
	v_mfma_f32_16x16x32_bf16 v[48:51], v[132:135], v[184:187], v[48:51]
	v_mfma_f32_16x16x32_bf16 v[48:51], v[136:139], v[196:199], v[48:51]
	v_mfma_f32_16x16x32_bf16 v[32:35], v[132:135], v[200:203], v[32:35]
	v_mfma_f32_16x16x32_bf16 v[32:35], v[136:139], v[204:207], v[32:35]
	v_mfma_f32_16x16x32_bf16 v[28:31], v[152:155], v[200:203], v[28:31]
	v_mfma_f32_16x16x32_bf16 v[28:31], v[156:159], v[204:207], v[28:31]
	v_mfma_f32_16x16x32_bf16 v[12:15], v[152:155], v[208:211], v[12:15]
	v_mfma_f32_16x16x32_bf16 v[12:15], v[156:159], v[212:215], v[12:15]
	v_mfma_f32_16x16x32_bf16 v[16:19], v[132:135], v[208:211], v[16:19]
	v_mfma_f32_16x16x32_bf16 v[16:19], v[136:139], v[212:215], v[16:19]
	s_setprio 0
	s_setprio 1
	v_mfma_f32_16x16x32_bf16 v[56:59], v[160:163], v[176:179], v[56:59]
	v_mfma_f32_16x16x32_bf16 v[56:59], v[164:167], v[180:183], v[56:59]
	v_mfma_f32_16x16x32_bf16 v[52:55], v[168:171], v[176:179], v[52:55]
	v_mfma_f32_16x16x32_bf16 v[52:55], v[172:175], v[180:183], v[52:55]
	v_mfma_f32_16x16x32_bf16 v[36:39], v[168:171], v[184:187], v[36:39]
	v_mfma_f32_16x16x32_bf16 v[36:39], v[172:175], v[196:199], v[36:39]
	v_mfma_f32_16x16x32_bf16 v[40:43], v[160:163], v[184:187], v[40:43]
	v_mfma_f32_16x16x32_bf16 v[40:43], v[164:167], v[196:199], v[40:43]
	v_mfma_f32_16x16x32_bf16 v[24:27], v[160:163], v[200:203], v[24:27]
	v_mfma_f32_16x16x32_bf16 v[24:27], v[164:167], v[204:207], v[24:27]
	v_mfma_f32_16x16x32_bf16 v[20:23], v[168:171], v[200:203], v[20:23]
	v_mfma_f32_16x16x32_bf16 v[20:23], v[172:175], v[204:207], v[20:23]
	v_mfma_f32_16x16x32_bf16 v[4:7], v[168:171], v[208:211], v[4:7]
	v_mfma_f32_16x16x32_bf16 v[4:7], v[172:175], v[212:215], v[4:7]
	v_mfma_f32_16x16x32_bf16 v[8:11], v[160:163], v[208:211], v[8:11]
	v_mfma_f32_16x16x32_bf16 v[8:11], v[164:167], v[212:215], v[8:11]
	s_barrier
; #define PG8_STAGE(bufoff, gbase, voff) do { _Pragma("unroll") for (int _i = 0; _i < 2; ++_i) \
;         __builtin_amdgcn_global_load_lds((const unsigned*)((const char*)(gbase) + (voff)[_i]), (PG8_LAS unsigned*)(lds + (bufoff) + ldsw + _i * 8192), 16, 0, 0); } while (0)
; #define PG8_LDA(dst, b, h) do { _Pragma("unroll") for (int m = 0; m < 4; ++m) _Pragma("unroll") for (int k = 0; k < 2; ++k) dst[m][k] = *(const PG8_LAS bf16x8*)(lds + PG8_SA(b, h) + aoff + m * 2048 + k * 1024); } while (0)
; #define PG8_LDB(dst, b, h) do { _Pragma("unroll") for (int n = 0; n < 2; ++n) _Pragma("unroll") for (int k = 0; k < 2; ++k) dst[n][k] = *(const PG8_LAS bf16x8*)(lds + PG8_SB(b, h) + boff + n * 2048 + k * 1024); } while (0)
; #define PG8_MMA(ai, bj, At, Bt) do { __builtin_amdgcn_s_setprio(1); _Pragma("unroll") for (int m = 0; m < 4; ++m) _Pragma("unroll") for (int n = 0; n < 2; ++n) _Pragma("unroll") for (int k = 0; k < 2; ++k) \
;         acc[ai][bj][m][n] = __builtin_amdgcn_mfma_f32_16x16x32_bf16(Bt[n][k], At[m][k], acc[ai][bj][m][n], 0, 0, 0); __builtin_amdgcn_s_setprio(0); } while (0)
; #define PG8_WAIT_V(n) asm volatile("s_waitcnt vmcnt(" #n ")" ::: "memory")
; #define PG8_WAIT_L(n) asm volatile("s_waitcnt lgkmcnt(" #n ")" ::: "memory")
; #define PG8_BAR __builtin_amdgcn_s_barrier()
; #define PG8_SCHED __builtin_amdgcn_sched_barrier(0)
; template <class Epi, class Sched, bool ALIGN_EPI = false, bool SP2 = false>
; __device__ __forceinline__ void gemm_phase(PG8_LAS unsigned char* lds, const Gemm g, const Sched& S, const Epi& E) {
;     ...
;             PG8_LDB(B0, 1, 0); PG8_LDB(B1, 1, 1); PG8_SCHED; PG8_LDA(At, 1, 0); PG8_STAGE(PG8_SA(0, 1), a2 + hstep, voffA);
;             PG8_WAIT_V(8); PG8_WAIT_L(0); PG8_BAR; PG8_MMA(0, 0, At, B0); PG8_MMA(0, 1, At, B1); PG8_BAR; PG8_SCHED;
;             PG8_LDA(At, 1, 1); PG8_STAGE(PG8_SB(1, 0), b3, voffB); PG8_STAGE(PG8_SB(1, 1), b3 + hstep, voffB); PG8_STAGE(PG8_SA(1, 0), a3, voffA);
;             PG8_WAIT_V(8); PG8_WAIT_L(0); PG8_BAR; PG8_MMA(1, 0, At, B0); PG8_MMA(1, 1, At, B1); PG8_BAR; PG8_SCHED;
	ds_read_b128 v[132:135], v188 offset:32768
	ds_read_b128 v[136:139], v188 offset:33792
	ds_read_b128 v[152:155], v188 offset:34816
	ds_read_b128 v[156:159], v188 offset:35840
	ds_read_b128 v[160:163], v188 offset:49152
	ds_read_b128 v[164:167], v188 offset:50176
	ds_read_b128 v[168:171], v188 offset:51200
	ds_read_b128 v[172:175], v188 offset:52224
	s_add_u32 s26, s26, 0x100000
	s_addc_u32 s27, s27, 0
	s_mov_b32 m0, s60
	ds_read_b128 v[176:179], v194 offset:32768
	ds_read_b128 v[180:183], v194 offset:33792
	ds_read_b128 v[184:187], v194 offset:34816
	ds_read_b128 v[196:199], v194 offset:35840
	ds_read_b128 v[200:203], v194 offset:36864
	ds_read_b128 v[204:207], v194 offset:37888
	ds_read_b128 v[208:211], v194 offset:38912
	ds_read_b128 v[212:215], v194 offset:39936
	s_setprio 0
	s_add_i32 s77, 0, 0x18000
	s_add_i32 s78, 0, 0x1c000
	global_load_lds_dwordx4 v140, s[26:27]
	s_mov_b32 m0, s61
	s_nop 0
	global_load_lds_dwordx4 v142, s[26:27]
	s_setprio 1
	s_waitcnt vmcnt(8)
	s_waitcnt lgkmcnt(0)
	s_barrier
	v_mfma_f32_16x16x32_bf16 v[128:131], v[132:135], v[176:179], v[128:131]
	v_mfma_f32_16x16x32_bf16 v[128:131], v[136:139], v[180:183], v[128:131]
	v_mfma_f32_16x16x32_bf16 v[124:127], v[152:155], v[176:179], v[124:127]
	v_mfma_f32_16x16x32_bf16 v[124:127], v[156:159], v[180:183], v[124:127]
	v_mfma_f32_16x16x32_bf16 v[108:111], v[152:155], v[184:187], v[108:111]
	v_mfma_f32_16x16x32_bf16 v[108:111], v[156:159], v[196:199], v[108:111]
	v_mfma_f32_16x16x32_bf16 v[112:115], v[132:135], v[184:187], v[112:115]
	v_mfma_f32_16x16x32_bf16 v[112:115], v[136:139], v[196:199], v[112:115]
	v_mfma_f32_16x16x32_bf16 v[96:99], v[132:135], v[200:203], v[96:99]
	v_mfma_f32_16x16x32_bf16 v[96:99], v[136:139], v[204:207], v[96:99]
	v_mfma_f32_16x16x32_bf16 v[92:95], v[152:155], v[200:203], v[92:95]
	v_mfma_f32_16x16x32_bf16 v[92:95], v[156:159], v[204:207], v[92:95]
	v_mfma_f32_16x16x32_bf16 v[76:79], v[152:155], v[208:211], v[76:79]
	v_mfma_f32_16x16x32_bf16 v[76:79], v[156:159], v[212:215], v[76:79]
	v_mfma_f32_16x16x32_bf16 v[80:83], v[132:135], v[208:211], v[80:83]
	v_mfma_f32_16x16x32_bf16 v[80:83], v[136:139], v[212:215], v[80:83]
	s_setprio 0
	s_setprio 1
	v_mfma_f32_16x16x32_bf16 v[120:123], v[160:163], v[176:179], v[120:123]
	v_mfma_f32_16x16x32_bf16 v[120:123], v[164:167], v[180:183], v[120:123]
	v_mfma_f32_16x16x32_bf16 v[116:119], v[168:171], v[176:179], v[116:119]
	v_mfma_f32_16x16x32_bf16 v[116:119], v[172:175], v[180:183], v[116:119]
	v_mfma_f32_16x16x32_bf16 v[100:103], v[168:171], v[184:187], v[100:103]
	v_mfma_f32_16x16x32_bf16 v[100:103], v[172:175], v[196:199], v[100:103]
	v_mfma_f32_16x16x32_bf16 v[104:107], v[160:163], v[184:187], v[104:107]
	v_mfma_f32_16x16x32_bf16 v[104:107], v[164:167], v[196:199], v[104:107]
	v_mfma_f32_16x16x32_bf16 v[88:91], v[160:163], v[200:203], v[88:91]
	v_mfma_f32_16x16x32_bf16 v[88:91], v[164:167], v[204:207], v[88:91]
	v_mfma_f32_16x16x32_bf16 v[84:87], v[168:171], v[200:203], v[84:87]
	v_mfma_f32_16x16x32_bf16 v[84:87], v[172:175], v[204:207], v[84:87]
	v_mfma_f32_16x16x32_bf16 v[68:71], v[168:171], v[208:211], v[68:71]
	v_mfma_f32_16x16x32_bf16 v[68:71], v[172:175], v[212:215], v[68:71]
	v_mfma_f32_16x16x32_bf16 v[72:75], v[160:163], v[208:211], v[72:75]
	v_mfma_f32_16x16x32_bf16 v[72:75], v[164:167], v[212:215], v[72:75]
	s_barrier
	ds_read_b128 v[176:179], v194 offset:49152
	ds_read_b128 v[180:183], v194 offset:50176
	ds_read_b128 v[184:187], v194 offset:51200
	ds_read_b128 v[196:199], v194 offset:52224
	ds_read_b128 v[200:203], v194 offset:53248
	ds_read_b128 v[204:207], v194 offset:54272
	ds_read_b128 v[208:211], v194 offset:55296
	ds_read_b128 v[212:215], v194 offset:56320
	s_setprio 0
	s_add_i32 s26, s77, s10
	s_mov_b32 m0, s26
	s_add_u32 s0, s0, 0x80
	s_addc_u32 s1, s1, 0
	global_load_lds_dwordx4 v2, s[0:1]
	s_add_i32 m0, s26, 0x2000
	s_add_i32 s26, s78, s10
	global_load_lds_dwordx4 v144, s[0:1]
	s_add_u32 s0, s0, 0x100000
	s_addc_u32 s1, s1, 0
	s_mov_b32 m0, s26
	s_nop 0
	global_load_lds_dwordx4 v2, s[0:1]
	s_add_i32 m0, s26, 0x2000
	s_nop 0
	global_load_lds_dwordx4 v144, s[0:1]
	s_mov_b32 m0, s62
	s_nop 0
	global_load_lds_dwordx4 v140, s[100:101]
	s_mov_b32 m0, s63
	s_nop 0
	global_load_lds_dwordx4 v142, s[100:101]
	s_setprio 1
	s_waitcnt vmcnt(8)
	s_waitcnt lgkmcnt(0)
	s_barrier
	v_mfma_f32_16x16x32_bf16 v[64:67], v[132:135], v[176:179], v[64:67]
	v_mfma_f32_16x16x32_bf16 v[64:67], v[136:139], v[180:183], v[64:67]
	v_mfma_f32_16x16x32_bf16 v[60:63], v[152:155], v[176:179], v[60:63]
	v_mfma_f32_16x16x32_bf16 v[60:63], v[156:159], v[180:183], v[60:63]
	v_mfma_f32_16x16x32_bf16 v[44:47], v[152:155], v[184:187], v[44:47]
	v_mfma_f32_16x16x32_bf16 v[44:47], v[156:159], v[196:199], v[44:47]
	v_mfma_f32_16x16x32_bf16 v[48:51], v[132:135], v[184:187], v[48:51]
	v_mfma_f32_16x16x32_bf16 v[48:51], v[136:139], v[196:199], v[48:51]
	v_mfma_f32_16x16x32_bf16 v[32:35], v[132:135], v[200:203], v[32:35]
	v_mfma_f32_16x16x32_bf16 v[32:35], v[136:139], v[204:207], v[32:35]
	v_mfma_f32_16x16x32_bf16 v[28:31], v[152:155], v[200:203], v[28:31]
	v_mfma_f32_16x16x32_bf16 v[28:31], v[156:159], v[204:207], v[28:31]
	v_mfma_f32_16x16x32_bf16 v[12:15], v[152:155], v[208:211], v[12:15]
	v_mfma_f32_16x16x32_bf16 v[12:15], v[156:159], v[212:215], v[12:15]
	v_mfma_f32_16x16x32_bf16 v[16:19], v[132:135], v[208:211], v[16:19]
	v_mfma_f32_16x16x32_bf16 v[16:19], v[136:139], v[212:215], v[16:19]
	s_setprio 0
	s_setprio 1
	s_add_i32 s76, s76, 2
	s_add_u32 s40, s40, 0x100
	s_addc_u32 s41, s41, 0
	s_add_u32 s58, s58, 0x100
	s_addc_u32 s59, s59, 0
	s_nop 0
	v_mfma_f32_16x16x32_bf16 v[56:59], v[160:163], v[176:179], v[56:59]
	v_mfma_f32_16x16x32_bf16 v[56:59], v[164:167], v[180:183], v[56:59]
	v_mfma_f32_16x16x32_bf16 v[52:55], v[168:171], v[176:179], v[52:55]
	v_mfma_f32_16x16x32_bf16 v[52:55], v[172:175], v[180:183], v[52:55]
	v_mfma_f32_16x16x32_bf16 v[36:39], v[168:171], v[184:187], v[36:39]
	v_mfma_f32_16x16x32_bf16 v[36:39], v[172:175], v[196:199], v[36:39]
	v_mfma_f32_16x16x32_bf16 v[40:43], v[160:163], v[184:187], v[40:43]
	v_mfma_f32_16x16x32_bf16 v[40:43], v[164:167], v[196:199], v[40:43]
	v_mfma_f32_16x16x32_bf16 v[24:27], v[160:163], v[200:203], v[24:27]
	v_mfma_f32_16x16x32_bf16 v[24:27], v[164:167], v[204:207], v[24:27]
	v_mfma_f32_16x16x32_bf16 v[20:23], v[168:171], v[200:203], v[20:23]
	v_mfma_f32_16x16x32_bf16 v[20:23], v[172:175], v[204:207], v[20:23]
	v_mfma_f32_16x16x32_bf16 v[4:7], v[168:171], v[208:211], v[4:7]
	v_mfma_f32_16x16x32_bf16 v[4:7], v[172:175], v[212:215], v[4:7]
	v_mfma_f32_16x16x32_bf16 v[8:11], v[160:163], v[208:211], v[8:11]
	v_mfma_f32_16x16x32_bf16 v[8:11], v[164:167], v[212:215], v[8:11]
	s_barrier
	s_cmp_gt_u32 s76, 61
	s_cbranch_scc0 .LBB0_2115
	s_setprio 0
	s_and_b64 vcc, exec, s[36:37]
	s_cbranch_vccz .LBB0_2118
	s_barrier

; #define PG8_STAGE(bufoff, gbase, voff) do { _Pragma("unroll") for (int _i = 0; _i < 2; ++_i) \
;         __builtin_amdgcn_global_load_lds((const unsigned*)((const char*)(gbase) + (voff)[_i]), (PG8_LAS unsigned*)(lds + (bufoff) + ldsw + _i * 8192), 16, 0, 0); } while (0)
; #define PG8_LDA(dst, b, h) do { _Pragma("unroll") for (int m = 0; m < 4; ++m) _Pragma("unroll") for (int k = 0; k < 2; ++k) dst[m][k] = *(const PG8_LAS bf16x8*)(lds + PG8_SA(b, h) + aoff + m * 2048 + k * 1024); } while (0)
; #define PG8_LDB(dst, b, h) do { _Pragma("unroll") for (int n = 0; n < 2; ++n) _Pragma("unroll") for (int k = 0; k < 2; ++k) dst[n][k] = *(const PG8_LAS bf16x8*)(lds + PG8_SB(b, h) + boff + n * 2048 + k * 1024); } while (0)
; #define PG8_MMA(ai, bj, At, Bt) do { __builtin_amdgcn_s_setprio(1); _Pragma("unroll") for (int m = 0; m < 4; ++m) _Pragma("unroll") for (int n = 0; n < 2; ++n) _Pragma("unroll") for (int k = 0; k < 2; ++k) \
;         acc[ai][bj][m][n] = __builtin_amdgcn_mfma_f32_16x16x32_bf16(Bt[n][k], At[m][k], acc[ai][bj][m][n], 0, 0, 0); __builtin_amdgcn_s_setprio(0); } while (0)
; #define PG8_WAIT_V(n) asm volatile("s_waitcnt vmcnt(" #n ")" ::: "memory")
; #define PG8_BAR __builtin_amdgcn_s_barrier()
; template <class Epi, class Sched, bool ALIGN_EPI = false, bool SP2 = false>
; __device__ __forceinline__ void gemm_phase(PG8_LAS unsigned char* lds, const Gemm g, const Sched& S, const Epi& E) {
;     ...
;         for (int t = 0; t < nt; t += 2) {
;             const bool last = (t == nt - 2);
;             const char* a1 = cA + (size_t)(t + 1) * kstep;
;             const char* a2 = last ? nA : cA + (size_t)(t + 2) * kstep; const char* b2 = last ? nB : cB + (size_t)(t + 2) * kstep;
;             const char* a3 = a2 + kstep; const char* b3 = b2 + kstep;
;             if (last && has_next) S.a_ready(nxt);
;             if constexpr (SP2) {
;             PG8_LDB(B0, 0, 0); PG8_LDB(B1, 0, 1); PG8_SCHED; PG8_LDA(At, 0, 0); PG8_STAGE(PG8_SA(1, 1), a1 + hstep, voffA);
;             PG8_WAIT_V(8); PG8_WAIT_L(0); PG8_BAR; PG8_MMA(0, 0, At, B0); PG8_MMA(0, 1, At, B1); PG8_BAR; PG8_SCHED;
;             PG8_LDA(At, 0, 1); PG8_STAGE(PG8_SB(0, 0), b2, voffB); PG8_STAGE(PG8_SB(0, 1), b2 + hstep, voffB); PG8_STAGE(PG8_SA(0, 0), a2, voffA);
;             PG8_WAIT_V(8); PG8_WAIT_L(0); PG8_BAR; PG8_MMA(1, 0, At, B0); PG8_MMA(1, 1, At, B1); PG8_BAR; PG8_SCHED;
.LBB0_2692:
	ds_read_b128 v[142:145], v210
	ds_read_b128 v[150:153], v210 offset:1024
	ds_read_b128 v[154:157], v210 offset:2048
	ds_read_b128 v[158:161], v210 offset:3072
	ds_read_b128 v[162:165], v210 offset:16384
	ds_read_b128 v[166:169], v210 offset:17408
	ds_read_b128 v[170:173], v210 offset:18432
	ds_read_b128 v[174:177], v210 offset:19456
	s_add_i32 m0, s10, 0xc000
	ds_read_b128 v[178:181], v149
	ds_read_b128 v[182:185], v149 offset:1024
	ds_read_b128 v[186:189], v149 offset:2048
	ds_read_b128 v[190:193], v149 offset:3072
	ds_read_b128 v[194:197], v149 offset:4096
	ds_read_b128 v[198:201], v149 offset:5120
	ds_read_b128 v[202:205], v149 offset:6144
	ds_read_b128 v[206:209], v149 offset:7168
	s_setprio 0
	s_add_u32 s0, s56, 0xfffe0080
	s_addc_u32 s1, s57, -1
	s_add_i32 s63, 0, 0x10000
	s_cmp_eq_u32 s62, 4
	s_cselect_b32 s27, s51, s1
	s_cselect_b32 s26, s50, s0
	s_cselect_b32 s1, s53, s49
	s_cselect_b32 s0, s52, s47
	s_add_i32 s66, 0, 0x14000
	global_load_lds_dwordx4 v138, s[56:57]
	s_add_i32 m0, s10, 0xe000
	s_nop 0
	global_load_lds_dwordx4 v140, s[56:57]
	s_setprio 1
	s_waitcnt vmcnt(8)
	s_waitcnt lgkmcnt(0)
	s_barrier
	v_mfma_f32_16x16x32_bf16 v[128:131], v[142:145], v[178:181], v[128:131]
	v_mfma_f32_16x16x32_bf16 v[128:131], v[150:153], v[182:185], v[128:131]
	v_mfma_f32_16x16x32_bf16 v[124:127], v[154:157], v[178:181], v[124:127]
	v_mfma_f32_16x16x32_bf16 v[124:127], v[158:161], v[182:185], v[124:127]
	v_mfma_f32_16x16x32_bf16 v[108:111], v[154:157], v[186:189], v[108:111]
	v_mfma_f32_16x16x32_bf16 v[108:111], v[158:161], v[190:193], v[108:111]
	v_mfma_f32_16x16x32_bf16 v[112:115], v[142:145], v[186:189], v[112:115]
	v_mfma_f32_16x16x32_bf16 v[112:115], v[150:153], v[190:193], v[112:115]
	v_mfma_f32_16x16x32_bf16 v[96:99], v[142:145], v[194:197], v[96:99]
	v_mfma_f32_16x16x32_bf16 v[96:99], v[150:153], v[198:201], v[96:99]
	v_mfma_f32_16x16x32_bf16 v[92:95], v[154:157], v[194:197], v[92:95]
	v_mfma_f32_16x16x32_bf16 v[92:95], v[158:161], v[198:201], v[92:95]
	v_mfma_f32_16x16x32_bf16 v[76:79], v[154:157], v[202:205], v[76:79]
	v_mfma_f32_16x16x32_bf16 v[76:79], v[158:161], v[206:209], v[76:79]
	v_mfma_f32_16x16x32_bf16 v[80:83], v[142:145], v[202:205], v[80:83]
	v_mfma_f32_16x16x32_bf16 v[80:83], v[150:153], v[206:209], v[80:83]
	s_setprio 0
	s_setprio 1
	v_mfma_f32_16x16x32_bf16 v[120:123], v[162:165], v[178:181], v[120:123]
	v_mfma_f32_16x16x32_bf16 v[120:123], v[166:169], v[182:185], v[120:123]
	v_mfma_f32_16x16x32_bf16 v[116:119], v[170:173], v[178:181], v[116:119]
	v_mfma_f32_16x16x32_bf16 v[116:119], v[174:177], v[182:185], v[116:119]
	v_mfma_f32_16x16x32_bf16 v[100:103], v[170:173], v[186:189], v[100:103]
	v_mfma_f32_16x16x32_bf16 v[100:103], v[174:177], v[190:193], v[100:103]
	v_mfma_f32_16x16x32_bf16 v[104:107], v[162:165], v[186:189], v[104:107]
	v_mfma_f32_16x16x32_bf16 v[104:107], v[166:169], v[190:193], v[104:107]
	v_mfma_f32_16x16x32_bf16 v[88:91], v[162:165], v[194:197], v[88:91]
	v_mfma_f32_16x16x32_bf16 v[88:91], v[166:169], v[198:201], v[88:91]
	v_mfma_f32_16x16x32_bf16 v[84:87], v[170:173], v[194:197], v[84:87]
	v_mfma_f32_16x16x32_bf16 v[84:87], v[174:177], v[198:201], v[84:87]
	v_mfma_f32_16x16x32_bf16 v[68:71], v[170:173], v[202:205], v[68:71]
	v_mfma_f32_16x16x32_bf16 v[68:71], v[174:177], v[206:209], v[68:71]
	v_mfma_f32_16x16x32_bf16 v[72:75], v[162:165], v[202:205], v[72:75]
	v_mfma_f32_16x16x32_bf16 v[72:75], v[166:169], v[206:209], v[72:75]
	s_barrier
	ds_read_b128 v[178:181], v149 offset:16384
	ds_read_b128 v[182:185], v149 offset:17408
	ds_read_b128 v[186:189], v149 offset:18432
	ds_read_b128 v[190:193], v149 offset:19456
	ds_read_b128 v[194:197], v149 offset:20480
	ds_read_b128 v[198:201], v149 offset:21504
	ds_read_b128 v[202:205], v149 offset:22528
	ds_read_b128 v[206:209], v149 offset:23552
	s_setprio 0
	s_add_i32 s63, s63, s9
	s_mov_b32 m0, s63
	s_nop 0
	global_load_lds_dwordx4 v2, s[0:1]
	s_add_i32 m0, s63, 0x2000
	s_add_u32 s64, s0, 0x20000
	s_addc_u32 s65, s1, 0
	s_add_i32 s63, s66, s9
	global_load_lds_dwordx4 v136, s[0:1]
	s_mov_b32 m0, s63
	s_nop 0
	global_load_lds_dwordx4 v2, s[64:65]
	s_add_i32 m0, s63, 0x2000
	s_nop 0
	global_load_lds_dwordx4 v136, s[64:65]
	s_mov_b32 m0, s10
	s_nop 0
	global_load_lds_dwordx4 v132, s[26:27]
	s_mov_b32 m0, s11
	s_nop 0
	global_load_lds_dwordx4 v134, s[26:27]
	s_nop 0
	s_add_u32 s100, s26, 0x80
	s_addc_u32 s101, s27, 0
	s_setprio 1
	s_waitcnt vmcnt(8)
	s_waitcnt lgkmcnt(0)
	s_barrier
	v_mfma_f32_16x16x32_bf16 v[64:67], v[142:145], v[178:181], v[64:67]
	v_mfma_f32_16x16x32_bf16 v[64:67], v[150:153], v[182:185], v[64:67]
	v_mfma_f32_16x16x32_bf16 v[60:63], v[154:157], v[178:181], v[60:63]
	v_mfma_f32_16x16x32_bf16 v[60:63], v[158:161], v[182:185], v[60:63]
	v_mfma_f32_16x16x32_bf16 v[44:47], v[154:157], v[186:189], v[44:47]
	v_mfma_f32_16x16x32_bf16 v[44:47], v[158:161], v[190:193], v[44:47]
	v_mfma_f32_16x16x32_bf16 v[48:51], v[142:145], v[186:189], v[48:51]
	v_mfma_f32_16x16x32_bf16 v[48:51], v[150:153], v[190:193], v[48:51]
	v_mfma_f32_16x16x32_bf16 v[32:35], v[142:145], v[194:197], v[32:35]
	v_mfma_f32_16x16x32_bf16 v[32:35], v[150:153], v[198:201], v[32:35]
	v_mfma_f32_16x16x32_bf16 v[28:31], v[154:157], v[194:197], v[28:31]
	v_mfma_f32_16x16x32_bf16 v[28:31], v[158:161], v[198:201], v[28:31]
	v_mfma_f32_16x16x32_bf16 v[12:15], v[154:157], v[202:205], v[12:15]
	v_mfma_f32_16x16x32_bf16 v[12:15], v[158:161], v[206:209], v[12:15]
	v_mfma_f32_16x16x32_bf16 v[16:19], v[142:145], v[202:205], v[16:19]
	v_mfma_f32_16x16x32_bf16 v[16:19], v[150:153], v[206:209], v[16:19]
	s_setprio 0
	s_setprio 1
	v_mfma_f32_16x16x32_bf16 v[56:59], v[162:165], v[178:181], v[56:59]
	v_mfma_f32_16x16x32_bf16 v[56:59], v[166:169], v[182:185], v[56:59]
	v_mfma_f32_16x16x32_bf16 v[52:55], v[170:173], v[178:181], v[52:55]
	v_mfma_f32_16x16x32_bf16 v[52:55], v[174:177], v[182:185], v[52:55]
	v_mfma_f32_16x16x32_bf16 v[36:39], v[170:173], v[186:189], v[36:39]
	v_mfma_f32_16x16x32_bf16 v[36:39], v[174:177], v[190:193], v[36:39]
	v_mfma_f32_16x16x32_bf16 v[40:43], v[162:165], v[186:189], v[40:43]
	v_mfma_f32_16x16x32_bf16 v[40:43], v[166:169], v[190:193], v[40:43]
	v_mfma_f32_16x16x32_bf16 v[24:27], v[162:165], v[194:197], v[24:27]
	v_mfma_f32_16x16x32_bf16 v[24:27], v[166:169], v[198:201], v[24:27]
	v_mfma_f32_16x16x32_bf16 v[20:23], v[170:173], v[194:197], v[20:23]
	v_mfma_f32_16x16x32_bf16 v[20:23], v[174:177], v[198:201], v[20:23]
	v_mfma_f32_16x16x32_bf16 v[4:7], v[170:173], v[202:205], v[4:7]
	v_mfma_f32_16x16x32_bf16 v[4:7], v[174:177], v[206:209], v[4:7]
	v_mfma_f32_16x16x32_bf16 v[8:11], v[162:165], v[202:205], v[8:11]
	v_mfma_f32_16x16x32_bf16 v[8:11], v[166:169], v[206:209], v[8:11]
	s_barrier
; #define PG8_STAGE(bufoff, gbase, voff) do { _Pragma("unroll") for (int _i = 0; _i < 2; ++_i) \
;         __builtin_amdgcn_global_load_lds((const unsigned*)((const char*)(gbase) + (voff)[_i]), (PG8_LAS unsigned*)(lds + (bufoff) + ldsw + _i * 8192), 16, 0, 0); } while (0)
; #define PG8_LDA(dst, b, h) do { _Pragma("unroll") for (int m = 0; m < 4; ++m) _Pragma("unroll") for (int k = 0; k < 2; ++k) dst[m][k] = *(const PG8_LAS bf16x8*)(lds + PG8_SA(b, h) + aoff + m * 2048 + k * 1024); } while (0)
; #define PG8_LDB(dst, b, h) do { _Pragma("unroll") for (int n = 0; n < 2; ++n) _Pragma("unroll") for (int k = 0; k < 2; ++k) dst[n][k] = *(const PG8_LAS bf16x8*)(lds + PG8_SB(b, h) + boff + n * 2048 + k * 1024); } while (0)
; #define PG8_MMA(ai, bj, At, Bt) do { __builtin_amdgcn_s_setprio(1); _Pragma("unroll") for (int m = 0; m < 4; ++m) _Pragma("unroll") for (int n = 0; n < 2; ++n) _Pragma("unroll") for (int k = 0; k < 2; ++k) \
;         acc[ai][bj][m][n] = __builtin_amdgcn_mfma_f32_16x16x32_bf16(Bt[n][k], At[m][k], acc[ai][bj][m][n], 0, 0, 0); __builtin_amdgcn_s_setprio(0); } while (0)
; #define PG8_WAIT_V(n) asm volatile("s_waitcnt vmcnt(" #n ")" ::: "memory")
; #define PG8_WAIT_L(n) asm volatile("s_waitcnt lgkmcnt(" #n ")" ::: "memory")
; #define PG8_BAR __builtin_amdgcn_s_barrier()
; #define PG8_SCHED __builtin_amdgcn_sched_barrier(0)
; template <class Epi, class Sched, bool ALIGN_EPI = false, bool SP2 = false>
; __device__ __forceinline__ void gemm_phase(PG8_LAS unsigned char* lds, const Gemm g, const Sched& S, const Epi& E) {
;     ...
;         for (int t = 0; t < nt; t += 2) {
;             const bool last = (t == nt - 2);
;             const char* a1 = cA + (size_t)(t + 1) * kstep;
;             const char* a2 = last ? nA : cA + (size_t)(t + 2) * kstep; const char* b2 = last ? nB : cB + (size_t)(t + 2) * kstep;
;     ...
;             PG8_LDB(B0, 1, 0); PG8_LDB(B1, 1, 1); PG8_SCHED; PG8_LDA(At, 1, 0); PG8_STAGE(PG8_SA(0, 1), a2 + hstep, voffA);
;             PG8_WAIT_V(8); PG8_WAIT_L(0); PG8_BAR; PG8_MMA(0, 0, At, B0); PG8_MMA(0, 1, At, B1); PG8_BAR; PG8_SCHED;
;             PG8_LDA(At, 1, 1); PG8_STAGE(PG8_SB(1, 0), b3, voffB); PG8_STAGE(PG8_SB(1, 1), b3 + hstep, voffB); PG8_STAGE(PG8_SA(1, 0), a3, voffA);
;             PG8_WAIT_V(8); PG8_WAIT_L(0); PG8_BAR; PG8_MMA(1, 0, At, B0); PG8_MMA(1, 1, At, B1); PG8_BAR; PG8_SCHED;
	ds_read_b128 v[142:145], v210 offset:32768
	ds_read_b128 v[150:153], v210 offset:33792
	ds_read_b128 v[154:157], v210 offset:34816
	ds_read_b128 v[158:161], v210 offset:35840
	ds_read_b128 v[162:165], v210 offset:49152
	ds_read_b128 v[166:169], v210 offset:50176
	ds_read_b128 v[170:173], v210 offset:51200
	ds_read_b128 v[174:177], v210 offset:52224
	s_add_u32 s26, s26, 0x20000
	s_addc_u32 s27, s27, 0
	s_mov_b32 m0, s25
	ds_read_b128 v[178:181], v149 offset:32768
	ds_read_b128 v[182:185], v149 offset:33792
	ds_read_b128 v[186:189], v149 offset:34816
	ds_read_b128 v[190:193], v149 offset:35840
	ds_read_b128 v[194:197], v149 offset:36864
	ds_read_b128 v[198:201], v149 offset:37888
	ds_read_b128 v[202:205], v149 offset:38912
	ds_read_b128 v[206:209], v149 offset:39936
	s_setprio 0
	s_add_i32 s63, 0, 0x18000
	s_add_i32 s64, 0, 0x1c000
	global_load_lds_dwordx4 v132, s[26:27]
	s_mov_b32 m0, s55
	s_nop 0
	global_load_lds_dwordx4 v134, s[26:27]
	s_setprio 1
	s_waitcnt vmcnt(8)
	s_waitcnt lgkmcnt(0)
	s_barrier
	v_mfma_f32_16x16x32_bf16 v[128:131], v[142:145], v[178:181], v[128:131]
	v_mfma_f32_16x16x32_bf16 v[128:131], v[150:153], v[182:185], v[128:131]
	v_mfma_f32_16x16x32_bf16 v[124:127], v[154:157], v[178:181], v[124:127]
	v_mfma_f32_16x16x32_bf16 v[124:127], v[158:161], v[182:185], v[124:127]
	v_mfma_f32_16x16x32_bf16 v[108:111], v[154:157], v[186:189], v[108:111]
	v_mfma_f32_16x16x32_bf16 v[108:111], v[158:161], v[190:193], v[108:111]
	v_mfma_f32_16x16x32_bf16 v[112:115], v[142:145], v[186:189], v[112:115]
	v_mfma_f32_16x16x32_bf16 v[112:115], v[150:153], v[190:193], v[112:115]
	v_mfma_f32_16x16x32_bf16 v[96:99], v[142:145], v[194:197], v[96:99]
	v_mfma_f32_16x16x32_bf16 v[96:99], v[150:153], v[198:201], v[96:99]
	v_mfma_f32_16x16x32_bf16 v[92:95], v[154:157], v[194:197], v[92:95]
	v_mfma_f32_16x16x32_bf16 v[92:95], v[158:161], v[198:201], v[92:95]
	v_mfma_f32_16x16x32_bf16 v[76:79], v[154:157], v[202:205], v[76:79]
	v_mfma_f32_16x16x32_bf16 v[76:79], v[158:161], v[206:209], v[76:79]
	v_mfma_f32_16x16x32_bf16 v[80:83], v[142:145], v[202:205], v[80:83]
	v_mfma_f32_16x16x32_bf16 v[80:83], v[150:153], v[206:209], v[80:83]
	s_setprio 0
	s_setprio 1
	v_mfma_f32_16x16x32_bf16 v[120:123], v[162:165], v[178:181], v[120:123]
	v_mfma_f32_16x16x32_bf16 v[120:123], v[166:169], v[182:185], v[120:123]
	v_mfma_f32_16x16x32_bf16 v[116:119], v[170:173], v[178:181], v[116:119]
	v_mfma_f32_16x16x32_bf16 v[116:119], v[174:177], v[182:185], v[116:119]
	v_mfma_f32_16x16x32_bf16 v[100:103], v[170:173], v[186:189], v[100:103]
	v_mfma_f32_16x16x32_bf16 v[100:103], v[174:177], v[190:193], v[100:103]
	v_mfma_f32_16x16x32_bf16 v[104:107], v[162:165], v[186:189], v[104:107]
	v_mfma_f32_16x16x32_bf16 v[104:107], v[166:169], v[190:193], v[104:107]
	v_mfma_f32_16x16x32_bf16 v[88:91], v[162:165], v[194:197], v[88:91]
	v_mfma_f32_16x16x32_bf16 v[88:91], v[166:169], v[198:201], v[88:91]
	v_mfma_f32_16x16x32_bf16 v[84:87], v[170:173], v[194:197], v[84:87]
	v_mfma_f32_16x16x32_bf16 v[84:87], v[174:177], v[198:201], v[84:87]
	v_mfma_f32_16x16x32_bf16 v[68:71], v[170:173], v[202:205], v[68:71]
	v_mfma_f32_16x16x32_bf16 v[68:71], v[174:177], v[206:209], v[68:71]
	v_mfma_f32_16x16x32_bf16 v[72:75], v[162:165], v[202:205], v[72:75]
	v_mfma_f32_16x16x32_bf16 v[72:75], v[166:169], v[206:209], v[72:75]
	s_barrier
	ds_read_b128 v[178:181], v149 offset:49152
	ds_read_b128 v[182:185], v149 offset:50176
	ds_read_b128 v[186:189], v149 offset:51200
	ds_read_b128 v[190:193], v149 offset:52224
	ds_read_b128 v[194:197], v149 offset:53248
	ds_read_b128 v[198:201], v149 offset:54272
	ds_read_b128 v[202:205], v149 offset:55296
	ds_read_b128 v[206:209], v149 offset:56320
	s_setprio 0
	s_add_i32 s26, s63, s9
	s_mov_b32 m0, s26
	s_add_u32 s0, s0, 0x80
	s_addc_u32 s1, s1, 0
	global_load_lds_dwordx4 v2, s[0:1]
	s_add_i32 m0, s26, 0x2000
	s_add_i32 s26, s64, s9
	global_load_lds_dwordx4 v136, s[0:1]
	s_add_u32 s0, s0, 0x20000
	s_addc_u32 s1, s1, 0
	s_mov_b32 m0, s26
	s_nop 0
	global_load_lds_dwordx4 v2, s[0:1]
	s_add_i32 m0, s26, 0x2000
	s_nop 0
	global_load_lds_dwordx4 v136, s[0:1]
	s_mov_b32 m0, s58
	s_nop 0
	global_load_lds_dwordx4 v132, s[100:101]
	s_mov_b32 m0, s59
	s_nop 0
	global_load_lds_dwordx4 v134, s[100:101]
	s_setprio 1
	s_waitcnt vmcnt(8)
	s_waitcnt lgkmcnt(0)
	s_barrier
	v_mfma_f32_16x16x32_bf16 v[64:67], v[142:145], v[178:181], v[64:67]
	v_mfma_f32_16x16x32_bf16 v[64:67], v[150:153], v[182:185], v[64:67]
	v_mfma_f32_16x16x32_bf16 v[60:63], v[154:157], v[178:181], v[60:63]
	v_mfma_f32_16x16x32_bf16 v[60:63], v[158:161], v[182:185], v[60:63]
	v_mfma_f32_16x16x32_bf16 v[44:47], v[154:157], v[186:189], v[44:47]
	v_mfma_f32_16x16x32_bf16 v[44:47], v[158:161], v[190:193], v[44:47]
	v_mfma_f32_16x16x32_bf16 v[48:51], v[142:145], v[186:189], v[48:51]
	v_mfma_f32_16x16x32_bf16 v[48:51], v[150:153], v[190:193], v[48:51]
	v_mfma_f32_16x16x32_bf16 v[32:35], v[142:145], v[194:197], v[32:35]
	v_mfma_f32_16x16x32_bf16 v[32:35], v[150:153], v[198:201], v[32:35]
	v_mfma_f32_16x16x32_bf16 v[28:31], v[154:157], v[194:197], v[28:31]
	v_mfma_f32_16x16x32_bf16 v[28:31], v[158:161], v[198:201], v[28:31]
	v_mfma_f32_16x16x32_bf16 v[12:15], v[154:157], v[202:205], v[12:15]
	v_mfma_f32_16x16x32_bf16 v[12:15], v[158:161], v[206:209], v[12:15]
	v_mfma_f32_16x16x32_bf16 v[16:19], v[142:145], v[202:205], v[16:19]
	v_mfma_f32_16x16x32_bf16 v[16:19], v[150:153], v[206:209], v[16:19]
	s_setprio 0
	s_setprio 1
	s_add_i32 s62, s62, 2
	s_add_u32 s56, s56, 0x100
	s_addc_u32 s57, s57, 0
	s_add_u32 s47, s47, 0x100
	s_addc_u32 s49, s49, 0
	s_nop 0
	v_mfma_f32_16x16x32_bf16 v[56:59], v[162:165], v[178:181], v[56:59]
	v_mfma_f32_16x16x32_bf16 v[56:59], v[166:169], v[182:185], v[56:59]
	v_mfma_f32_16x16x32_bf16 v[52:55], v[170:173], v[178:181], v[52:55]
	v_mfma_f32_16x16x32_bf16 v[52:55], v[174:177], v[182:185], v[52:55]
	v_mfma_f32_16x16x32_bf16 v[36:39], v[170:173], v[186:189], v[36:39]
	v_mfma_f32_16x16x32_bf16 v[36:39], v[174:177], v[190:193], v[36:39]
	v_mfma_f32_16x16x32_bf16 v[40:43], v[162:165], v[186:189], v[40:43]
	v_mfma_f32_16x16x32_bf16 v[40:43], v[166:169], v[190:193], v[40:43]
	v_mfma_f32_16x16x32_bf16 v[24:27], v[162:165], v[194:197], v[24:27]
	v_mfma_f32_16x16x32_bf16 v[24:27], v[166:169], v[198:201], v[24:27]
	v_mfma_f32_16x16x32_bf16 v[20:23], v[170:173], v[194:197], v[20:23]
	v_mfma_f32_16x16x32_bf16 v[20:23], v[174:177], v[198:201], v[20:23]
	v_mfma_f32_16x16x32_bf16 v[4:7], v[170:173], v[202:205], v[4:7]
	v_mfma_f32_16x16x32_bf16 v[4:7], v[174:177], v[206:209], v[4:7]
	v_mfma_f32_16x16x32_bf16 v[8:11], v[162:165], v[202:205], v[8:11]
	v_mfma_f32_16x16x32_bf16 v[8:11], v[166:169], v[206:209], v[8:11]
	s_barrier
	s_cmp_gt_u32 s62, 5
	s_cbranch_scc0 .LBB0_2692
	s_setprio 0
	s_and_b64 vcc, exec, s[44:45]
	s_cbranch_vccz .LBB0_2695
	s_barrier

; #define PG8_STAGE(bufoff, gbase, voff) do { _Pragma("unroll") for (int _i = 0; _i < 2; ++_i) \
;         __builtin_amdgcn_global_load_lds((const unsigned*)((const char*)(gbase) + (voff)[_i]), (PG8_LAS unsigned*)(lds + (bufoff) + ldsw + _i * 8192), 16, 0, 0); } while (0)
; #define PG8_LDA(dst, b, h) do { _Pragma("unroll") for (int m = 0; m < 4; ++m) _Pragma("unroll") for (int k = 0; k < 2; ++k) dst[m][k] = *(const PG8_LAS bf16x8*)(lds + PG8_SA(b, h) + aoff + m * 2048 + k * 1024); } while (0)
; #define PG8_LDB(dst, b, h) do { _Pragma("unroll") for (int n = 0; n < 2; ++n) _Pragma("unroll") for (int k = 0; k < 2; ++k) dst[n][k] = *(const PG8_LAS bf16x8*)(lds + PG8_SB(b, h) + boff + n * 2048 + k * 1024); } while (0)
; #define PG8_MMA(ai, bj, At, Bt) do { __builtin_amdgcn_s_setprio(1); _Pragma("unroll") for (int m = 0; m < 4; ++m) _Pragma("unroll") for (int n = 0; n < 2; ++n) _Pragma("unroll") for (int k = 0; k < 2; ++k) \
;         acc[ai][bj][m][n] = __builtin_amdgcn_mfma_f32_16x16x32_bf16(Bt[n][k], At[m][k], acc[ai][bj][m][n], 0, 0, 0); __builtin_amdgcn_s_setprio(0); } while (0)
; #define PG8_WAIT_V(n) asm volatile("s_waitcnt vmcnt(" #n ")" ::: "memory")
; #define PG8_BAR __builtin_amdgcn_s_barrier()
; template <class Epi, class Sched, bool ALIGN_EPI = false, bool SP2 = false>
; __device__ __forceinline__ void gemm_phase(PG8_LAS unsigned char* lds, const Gemm g, const Sched& S, const Epi& E) {
;     ...
;         for (int t = 0; t < nt; t += 2) {
;             const bool last = (t == nt - 2);
;             const char* a1 = cA + (size_t)(t + 1) * kstep;
;             const char* a2 = last ? nA : cA + (size_t)(t + 2) * kstep; const char* b2 = last ? nB : cB + (size_t)(t + 2) * kstep;
;             const char* a3 = a2 + kstep; const char* b3 = b2 + kstep;
;             if (last && has_next) S.a_ready(nxt);
;             if constexpr (SP2) {
;             PG8_LDB(B0, 0, 0); PG8_LDB(B1, 0, 1); PG8_SCHED; PG8_LDA(At, 0, 0); PG8_STAGE(PG8_SA(1, 1), a1 + hstep, voffA);
;             PG8_WAIT_V(8); PG8_WAIT_L(0); PG8_BAR; PG8_MMA(0, 0, At, B0); PG8_MMA(0, 1, At, B1); PG8_BAR; PG8_SCHED;
;             PG8_LDA(At, 0, 1); PG8_STAGE(PG8_SB(0, 0), b2, voffB); PG8_STAGE(PG8_SB(0, 1), b2 + hstep, voffB); PG8_STAGE(PG8_SA(0, 0), a2, voffA);
;             PG8_WAIT_V(8); PG8_WAIT_L(0); PG8_BAR; PG8_MMA(1, 0, At, B0); PG8_MMA(1, 1, At, B1); PG8_BAR; PG8_SCHED;
.LBB0_3159:
	ds_read_b128 v[142:145], v146
	ds_read_b128 v[152:155], v146 offset:1024
	ds_read_b128 v[156:159], v146 offset:2048
	ds_read_b128 v[160:163], v146 offset:3072
	ds_read_b128 v[164:167], v146 offset:16384
	ds_read_b128 v[168:171], v146 offset:17408
	ds_read_b128 v[172:175], v146 offset:18432
	ds_read_b128 v[176:179], v146 offset:19456
	s_add_i32 m0, s34, 0xc000
	ds_read_b128 v[180:183], v151
	ds_read_b128 v[184:187], v151 offset:1024
	ds_read_b128 v[188:191], v151 offset:2048
	ds_read_b128 v[192:195], v151 offset:3072
	ds_read_b128 v[196:199], v151 offset:4096
	ds_read_b128 v[200:203], v151 offset:5120
	ds_read_b128 v[204:207], v151 offset:6144
	ds_read_b128 v[208:211], v151 offset:7168
	s_setprio 0
	s_add_u32 s0, s24, 0xfff00080
	s_addc_u32 s1, s25, -1
	s_add_i32 s65, 0, 0x10000
	s_cmp_eq_u32 s64, 60
	s_cselect_b32 s27, s51, s1
	s_cselect_b32 s26, s60, s0
	s_cselect_b32 s1, s49, s63
	s_cselect_b32 s0, s61, s62
	s_add_i32 s70, 0, 0x14000
	global_load_lds_dwordx4 v138, s[24:25]
	s_add_i32 m0, s34, 0xe000
	s_nop 0
	global_load_lds_dwordx4 v140, s[24:25]
	s_nop 0
	s_setprio 1
	s_waitcnt vmcnt(8)
	s_waitcnt lgkmcnt(0)
	s_barrier
	v_mfma_f32_16x16x32_bf16 v[128:131], v[142:145], v[180:183], v[128:131]
	v_mfma_f32_16x16x32_bf16 v[128:131], v[152:155], v[184:187], v[128:131]
	v_mfma_f32_16x16x32_bf16 v[124:127], v[156:159], v[180:183], v[124:127]
	v_mfma_f32_16x16x32_bf16 v[124:127], v[160:163], v[184:187], v[124:127]
	v_mfma_f32_16x16x32_bf16 v[108:111], v[156:159], v[188:191], v[108:111]
	v_mfma_f32_16x16x32_bf16 v[108:111], v[160:163], v[192:195], v[108:111]
	v_mfma_f32_16x16x32_bf16 v[112:115], v[142:145], v[188:191], v[112:115]
	v_mfma_f32_16x16x32_bf16 v[112:115], v[152:155], v[192:195], v[112:115]
	v_mfma_f32_16x16x32_bf16 v[96:99], v[142:145], v[196:199], v[96:99]
	v_mfma_f32_16x16x32_bf16 v[96:99], v[152:155], v[200:203], v[96:99]
	v_mfma_f32_16x16x32_bf16 v[92:95], v[156:159], v[196:199], v[92:95]
	v_mfma_f32_16x16x32_bf16 v[92:95], v[160:163], v[200:203], v[92:95]
	v_mfma_f32_16x16x32_bf16 v[76:79], v[156:159], v[204:207], v[76:79]
	v_mfma_f32_16x16x32_bf16 v[76:79], v[160:163], v[208:211], v[76:79]
	v_mfma_f32_16x16x32_bf16 v[80:83], v[142:145], v[204:207], v[80:83]
	v_mfma_f32_16x16x32_bf16 v[80:83], v[152:155], v[208:211], v[80:83]
	s_setprio 0
	s_setprio 1
	v_mfma_f32_16x16x32_bf16 v[120:123], v[164:167], v[180:183], v[120:123]
	v_mfma_f32_16x16x32_bf16 v[120:123], v[168:171], v[184:187], v[120:123]
	v_mfma_f32_16x16x32_bf16 v[116:119], v[172:175], v[180:183], v[116:119]
	v_mfma_f32_16x16x32_bf16 v[116:119], v[176:179], v[184:187], v[116:119]
	v_mfma_f32_16x16x32_bf16 v[100:103], v[172:175], v[188:191], v[100:103]
	v_mfma_f32_16x16x32_bf16 v[100:103], v[176:179], v[192:195], v[100:103]
	v_mfma_f32_16x16x32_bf16 v[104:107], v[164:167], v[188:191], v[104:107]
	v_mfma_f32_16x16x32_bf16 v[104:107], v[168:171], v[192:195], v[104:107]
	v_mfma_f32_16x16x32_bf16 v[88:91], v[164:167], v[196:199], v[88:91]
	v_mfma_f32_16x16x32_bf16 v[88:91], v[168:171], v[200:203], v[88:91]
	v_mfma_f32_16x16x32_bf16 v[84:87], v[172:175], v[196:199], v[84:87]
	v_mfma_f32_16x16x32_bf16 v[84:87], v[176:179], v[200:203], v[84:87]
	v_mfma_f32_16x16x32_bf16 v[68:71], v[172:175], v[204:207], v[68:71]
	v_mfma_f32_16x16x32_bf16 v[68:71], v[176:179], v[208:211], v[68:71]
	v_mfma_f32_16x16x32_bf16 v[72:75], v[164:167], v[204:207], v[72:75]
	v_mfma_f32_16x16x32_bf16 v[72:75], v[168:171], v[208:211], v[72:75]
	s_barrier
	ds_read_b128 v[180:183], v151 offset:16384
	ds_read_b128 v[184:187], v151 offset:17408
	ds_read_b128 v[188:191], v151 offset:18432
	ds_read_b128 v[192:195], v151 offset:19456
	ds_read_b128 v[196:199], v151 offset:20480
	ds_read_b128 v[200:203], v151 offset:21504
	ds_read_b128 v[204:207], v151 offset:22528
	ds_read_b128 v[208:211], v151 offset:23552
	s_setprio 0
	s_add_i32 s65, s65, s9
	s_mov_b32 m0, s65
	s_nop 0
	global_load_lds_dwordx4 v2, s[0:1]
	s_add_i32 m0, s65, 0x2000
	s_add_u32 s66, s0, 0x100000
	s_addc_u32 s67, s1, 0
	s_add_i32 s65, s70, s9
	global_load_lds_dwordx4 v132, s[0:1]
	s_mov_b32 m0, s65
	s_nop 0
	global_load_lds_dwordx4 v2, s[66:67]
	s_add_i32 m0, s65, 0x2000
	s_nop 0
	global_load_lds_dwordx4 v132, s[66:67]
	s_mov_b32 m0, s34
	s_nop 0
	global_load_lds_dwordx4 v136, s[26:27]
	s_mov_b32 m0, s35
	s_nop 0
	global_load_lds_dwordx4 v134, s[26:27]
	s_nop 0
	s_add_u32 s100, s26, 0x80
	s_addc_u32 s101, s27, 0
	s_setprio 1
	s_waitcnt vmcnt(8)
	s_waitcnt lgkmcnt(0)
	s_barrier
	v_mfma_f32_16x16x32_bf16 v[64:67], v[142:145], v[180:183], v[64:67]
	v_mfma_f32_16x16x32_bf16 v[64:67], v[152:155], v[184:187], v[64:67]
	v_mfma_f32_16x16x32_bf16 v[60:63], v[156:159], v[180:183], v[60:63]
	v_mfma_f32_16x16x32_bf16 v[60:63], v[160:163], v[184:187], v[60:63]
	v_mfma_f32_16x16x32_bf16 v[44:47], v[156:159], v[188:191], v[44:47]
	v_mfma_f32_16x16x32_bf16 v[44:47], v[160:163], v[192:195], v[44:47]
	v_mfma_f32_16x16x32_bf16 v[48:51], v[142:145], v[188:191], v[48:51]
	v_mfma_f32_16x16x32_bf16 v[48:51], v[152:155], v[192:195], v[48:51]
	v_mfma_f32_16x16x32_bf16 v[32:35], v[142:145], v[196:199], v[32:35]
	v_mfma_f32_16x16x32_bf16 v[32:35], v[152:155], v[200:203], v[32:35]
	v_mfma_f32_16x16x32_bf16 v[28:31], v[156:159], v[196:199], v[28:31]
	v_mfma_f32_16x16x32_bf16 v[28:31], v[160:163], v[200:203], v[28:31]
	v_mfma_f32_16x16x32_bf16 v[12:15], v[156:159], v[204:207], v[12:15]
	v_mfma_f32_16x16x32_bf16 v[12:15], v[160:163], v[208:211], v[12:15]
	v_mfma_f32_16x16x32_bf16 v[16:19], v[142:145], v[204:207], v[16:19]
	v_mfma_f32_16x16x32_bf16 v[16:19], v[152:155], v[208:211], v[16:19]
	s_setprio 0
	s_setprio 1
	v_mfma_f32_16x16x32_bf16 v[56:59], v[164:167], v[180:183], v[56:59]
	v_mfma_f32_16x16x32_bf16 v[56:59], v[168:171], v[184:187], v[56:59]
	v_mfma_f32_16x16x32_bf16 v[52:55], v[172:175], v[180:183], v[52:55]
	v_mfma_f32_16x16x32_bf16 v[52:55], v[176:179], v[184:187], v[52:55]
	v_mfma_f32_16x16x32_bf16 v[36:39], v[172:175], v[188:191], v[36:39]
	v_mfma_f32_16x16x32_bf16 v[36:39], v[176:179], v[192:195], v[36:39]
	v_mfma_f32_16x16x32_bf16 v[40:43], v[164:167], v[188:191], v[40:43]
	v_mfma_f32_16x16x32_bf16 v[40:43], v[168:171], v[192:195], v[40:43]
	v_mfma_f32_16x16x32_bf16 v[24:27], v[164:167], v[196:199], v[24:27]
	v_mfma_f32_16x16x32_bf16 v[24:27], v[168:171], v[200:203], v[24:27]
	v_mfma_f32_16x16x32_bf16 v[20:23], v[172:175], v[196:199], v[20:23]
	v_mfma_f32_16x16x32_bf16 v[20:23], v[176:179], v[200:203], v[20:23]
	v_mfma_f32_16x16x32_bf16 v[4:7], v[172:175], v[204:207], v[4:7]
	v_mfma_f32_16x16x32_bf16 v[4:7], v[176:179], v[208:211], v[4:7]
	v_mfma_f32_16x16x32_bf16 v[8:11], v[164:167], v[204:207], v[8:11]
	v_mfma_f32_16x16x32_bf16 v[8:11], v[168:171], v[208:211], v[8:11]
	s_barrier
; #define PG8_STAGE(bufoff, gbase, voff) do { _Pragma("unroll") for (int _i = 0; _i < 2; ++_i) \
;         __builtin_amdgcn_global_load_lds((const unsigned*)((const char*)(gbase) + (voff)[_i]), (PG8_LAS unsigned*)(lds + (bufoff) + ldsw + _i * 8192), 16, 0, 0); } while (0)
; #define PG8_LDA(dst, b, h) do { _Pragma("unroll") for (int m = 0; m < 4; ++m) _Pragma("unroll") for (int k = 0; k < 2; ++k) dst[m][k] = *(const PG8_LAS bf16x8*)(lds + PG8_SA(b, h) + aoff + m * 2048 + k * 1024); } while (0)
; #define PG8_LDB(dst, b, h) do { _Pragma("unroll") for (int n = 0; n < 2; ++n) _Pragma("unroll") for (int k = 0; k < 2; ++k) dst[n][k] = *(const PG8_LAS bf16x8*)(lds + PG8_SB(b, h) + boff + n * 2048 + k * 1024); } while (0)
; #define PG8_MMA(ai, bj, At, Bt) do { __builtin_amdgcn_s_setprio(1); _Pragma("unroll") for (int m = 0; m < 4; ++m) _Pragma("unroll") for (int n = 0; n < 2; ++n) _Pragma("unroll") for (int k = 0; k < 2; ++k) \
;         acc[ai][bj][m][n] = __builtin_amdgcn_mfma_f32_16x16x32_bf16(Bt[n][k], At[m][k], acc[ai][bj][m][n], 0, 0, 0); __builtin_amdgcn_s_setprio(0); } while (0)
; #define PG8_WAIT_V(n) asm volatile("s_waitcnt vmcnt(" #n ")" ::: "memory")
; #define PG8_WAIT_L(n) asm volatile("s_waitcnt lgkmcnt(" #n ")" ::: "memory")
; #define PG8_BAR __builtin_amdgcn_s_barrier()
; #define PG8_SCHED __builtin_amdgcn_sched_barrier(0)
; template <class Epi, class Sched, bool ALIGN_EPI = false, bool SP2 = false>
; __device__ __forceinline__ void gemm_phase(PG8_LAS unsigned char* lds, const Gemm g, const Sched& S, const Epi& E) {
;     ...
;         for (int t = 0; t < nt; t += 2) {
;             const bool last = (t == nt - 2);
;             const char* a1 = cA + (size_t)(t + 1) * kstep;
;             const char* a2 = last ? nA : cA + (size_t)(t + 2) * kstep; const char* b2 = last ? nB : cB + (size_t)(t + 2) * kstep;
;     ...
;             PG8_LDB(B0, 1, 0); PG8_LDB(B1, 1, 1); PG8_SCHED; PG8_LDA(At, 1, 0); PG8_STAGE(PG8_SA(0, 1), a2 + hstep, voffA);
;             PG8_WAIT_V(8); PG8_WAIT_L(0); PG8_BAR; PG8_MMA(0, 0, At, B0); PG8_MMA(0, 1, At, B1); PG8_BAR; PG8_SCHED;
;             PG8_LDA(At, 1, 1); PG8_STAGE(PG8_SB(1, 0), b3, voffB); PG8_STAGE(PG8_SB(1, 1), b3 + hstep, voffB); PG8_STAGE(PG8_SA(1, 0), a3, voffA);
;             PG8_WAIT_V(8); PG8_WAIT_L(0); PG8_BAR; PG8_MMA(1, 0, At, B0); PG8_MMA(1, 1, At, B1); PG8_BAR; PG8_SCHED;
	ds_read_b128 v[142:145], v146 offset:32768
	ds_read_b128 v[152:155], v146 offset:33792
	ds_read_b128 v[156:159], v146 offset:34816
	ds_read_b128 v[160:163], v146 offset:35840
	ds_read_b128 v[164:167], v146 offset:49152
	ds_read_b128 v[168:171], v146 offset:50176
	ds_read_b128 v[172:175], v146 offset:51200
	ds_read_b128 v[176:179], v146 offset:52224
	s_add_u32 s26, s26, 0x100000
	s_addc_u32 s27, s27, 0
	s_mov_b32 m0, s54
	ds_read_b128 v[180:183], v151 offset:32768
	ds_read_b128 v[184:187], v151 offset:33792
	ds_read_b128 v[188:191], v151 offset:34816
	ds_read_b128 v[192:195], v151 offset:35840
	ds_read_b128 v[196:199], v151 offset:36864
	ds_read_b128 v[200:203], v151 offset:37888
	ds_read_b128 v[204:207], v151 offset:38912
	ds_read_b128 v[208:211], v151 offset:39936
	s_setprio 0
	s_add_i32 s65, 0, 0x18000
	s_add_i32 s66, 0, 0x1c000
	global_load_lds_dwordx4 v136, s[26:27]
	s_mov_b32 m0, s55
	s_nop 0
	global_load_lds_dwordx4 v134, s[26:27]
	s_setprio 1
	s_waitcnt vmcnt(8)
	s_waitcnt lgkmcnt(0)
	s_barrier
	v_mfma_f32_16x16x32_bf16 v[128:131], v[142:145], v[180:183], v[128:131]
	v_mfma_f32_16x16x32_bf16 v[128:131], v[152:155], v[184:187], v[128:131]
	v_mfma_f32_16x16x32_bf16 v[124:127], v[156:159], v[180:183], v[124:127]
	v_mfma_f32_16x16x32_bf16 v[124:127], v[160:163], v[184:187], v[124:127]
	v_mfma_f32_16x16x32_bf16 v[108:111], v[156:159], v[188:191], v[108:111]
	v_mfma_f32_16x16x32_bf16 v[108:111], v[160:163], v[192:195], v[108:111]
	v_mfma_f32_16x16x32_bf16 v[112:115], v[142:145], v[188:191], v[112:115]
	v_mfma_f32_16x16x32_bf16 v[112:115], v[152:155], v[192:195], v[112:115]
	v_mfma_f32_16x16x32_bf16 v[96:99], v[142:145], v[196:199], v[96:99]
	v_mfma_f32_16x16x32_bf16 v[96:99], v[152:155], v[200:203], v[96:99]
	v_mfma_f32_16x16x32_bf16 v[92:95], v[156:159], v[196:199], v[92:95]
	v_mfma_f32_16x16x32_bf16 v[92:95], v[160:163], v[200:203], v[92:95]
	v_mfma_f32_16x16x32_bf16 v[76:79], v[156:159], v[204:207], v[76:79]
	v_mfma_f32_16x16x32_bf16 v[76:79], v[160:163], v[208:211], v[76:79]
	v_mfma_f32_16x16x32_bf16 v[80:83], v[142:145], v[204:207], v[80:83]
	v_mfma_f32_16x16x32_bf16 v[80:83], v[152:155], v[208:211], v[80:83]
	s_setprio 0
	s_setprio 1
	v_mfma_f32_16x16x32_bf16 v[120:123], v[164:167], v[180:183], v[120:123]
	v_mfma_f32_16x16x32_bf16 v[120:123], v[168:171], v[184:187], v[120:123]
	v_mfma_f32_16x16x32_bf16 v[116:119], v[172:175], v[180:183], v[116:119]
	v_mfma_f32_16x16x32_bf16 v[116:119], v[176:179], v[184:187], v[116:119]
	v_mfma_f32_16x16x32_bf16 v[100:103], v[172:175], v[188:191], v[100:103]
	v_mfma_f32_16x16x32_bf16 v[100:103], v[176:179], v[192:195], v[100:103]
	v_mfma_f32_16x16x32_bf16 v[104:107], v[164:167], v[188:191], v[104:107]
	v_mfma_f32_16x16x32_bf16 v[104:107], v[168:171], v[192:195], v[104:107]
	v_mfma_f32_16x16x32_bf16 v[88:91], v[164:167], v[196:199], v[88:91]
	v_mfma_f32_16x16x32_bf16 v[88:91], v[168:171], v[200:203], v[88:91]
	v_mfma_f32_16x16x32_bf16 v[84:87], v[172:175], v[196:199], v[84:87]
	v_mfma_f32_16x16x32_bf16 v[84:87], v[176:179], v[200:203], v[84:87]
	v_mfma_f32_16x16x32_bf16 v[68:71], v[172:175], v[204:207], v[68:71]
	v_mfma_f32_16x16x32_bf16 v[68:71], v[176:179], v[208:211], v[68:71]
	v_mfma_f32_16x16x32_bf16 v[72:75], v[164:167], v[204:207], v[72:75]
	v_mfma_f32_16x16x32_bf16 v[72:75], v[168:171], v[208:211], v[72:75]
	s_barrier
	ds_read_b128 v[180:183], v151 offset:49152
	ds_read_b128 v[184:187], v151 offset:50176
	ds_read_b128 v[188:191], v151 offset:51200
	ds_read_b128 v[192:195], v151 offset:52224
	ds_read_b128 v[196:199], v151 offset:53248
	ds_read_b128 v[200:203], v151 offset:54272
	ds_read_b128 v[204:207], v151 offset:55296
	ds_read_b128 v[208:211], v151 offset:56320
	s_setprio 0
	s_add_i32 s26, s65, s9
	s_mov_b32 m0, s26
	s_add_u32 s0, s0, 0x80
	s_addc_u32 s1, s1, 0
	global_load_lds_dwordx4 v2, s[0:1]
	s_add_i32 m0, s26, 0x2000
	s_add_i32 s26, s66, s9
	global_load_lds_dwordx4 v132, s[0:1]
	s_add_u32 s0, s0, 0x100000
	s_addc_u32 s1, s1, 0
	s_mov_b32 m0, s26
	s_nop 0
	global_load_lds_dwordx4 v2, s[0:1]
	s_add_i32 m0, s26, 0x2000
	s_nop 0
	global_load_lds_dwordx4 v132, s[0:1]
	s_mov_b32 m0, s56
	s_nop 0
	global_load_lds_dwordx4 v136, s[100:101]
	s_mov_b32 m0, s57
	s_nop 0
	global_load_lds_dwordx4 v134, s[100:101]
	s_setprio 1
	s_waitcnt vmcnt(8)
	s_waitcnt lgkmcnt(0)
	s_barrier
	v_mfma_f32_16x16x32_bf16 v[64:67], v[142:145], v[180:183], v[64:67]
	v_mfma_f32_16x16x32_bf16 v[64:67], v[152:155], v[184:187], v[64:67]
	v_mfma_f32_16x16x32_bf16 v[60:63], v[156:159], v[180:183], v[60:63]
	v_mfma_f32_16x16x32_bf16 v[60:63], v[160:163], v[184:187], v[60:63]
	v_mfma_f32_16x16x32_bf16 v[44:47], v[156:159], v[188:191], v[44:47]
	v_mfma_f32_16x16x32_bf16 v[44:47], v[160:163], v[192:195], v[44:47]
	v_mfma_f32_16x16x32_bf16 v[48:51], v[142:145], v[188:191], v[48:51]
	v_mfma_f32_16x16x32_bf16 v[48:51], v[152:155], v[192:195], v[48:51]
	v_mfma_f32_16x16x32_bf16 v[32:35], v[142:145], v[196:199], v[32:35]
	v_mfma_f32_16x16x32_bf16 v[32:35], v[152:155], v[200:203], v[32:35]
	v_mfma_f32_16x16x32_bf16 v[28:31], v[156:159], v[196:199], v[28:31]
	v_mfma_f32_16x16x32_bf16 v[28:31], v[160:163], v[200:203], v[28:31]
	v_mfma_f32_16x16x32_bf16 v[12:15], v[156:159], v[204:207], v[12:15]
	v_mfma_f32_16x16x32_bf16 v[12:15], v[160:163], v[208:211], v[12:15]
	v_mfma_f32_16x16x32_bf16 v[16:19], v[142:145], v[204:207], v[16:19]
	v_mfma_f32_16x16x32_bf16 v[16:19], v[152:155], v[208:211], v[16:19]
	s_setprio 0
	s_setprio 1
	s_add_i32 s64, s64, 2
	s_add_u32 s24, s24, 0x100
	s_addc_u32 s25, s25, 0
	s_add_u32 s62, s62, 0x100
	s_addc_u32 s63, s63, 0
	s_nop 0
	v_mfma_f32_16x16x32_bf16 v[56:59], v[164:167], v[180:183], v[56:59]
	v_mfma_f32_16x16x32_bf16 v[56:59], v[168:171], v[184:187], v[56:59]
	v_mfma_f32_16x16x32_bf16 v[52:55], v[172:175], v[180:183], v[52:55]
	v_mfma_f32_16x16x32_bf16 v[52:55], v[176:179], v[184:187], v[52:55]
	v_mfma_f32_16x16x32_bf16 v[36:39], v[172:175], v[188:191], v[36:39]
	v_mfma_f32_16x16x32_bf16 v[36:39], v[176:179], v[192:195], v[36:39]
	v_mfma_f32_16x16x32_bf16 v[40:43], v[164:167], v[188:191], v[40:43]
	v_mfma_f32_16x16x32_bf16 v[40:43], v[168:171], v[192:195], v[40:43]
	v_mfma_f32_16x16x32_bf16 v[24:27], v[164:167], v[196:199], v[24:27]
	v_mfma_f32_16x16x32_bf16 v[24:27], v[168:171], v[200:203], v[24:27]
	v_mfma_f32_16x16x32_bf16 v[20:23], v[172:175], v[196:199], v[20:23]
	v_mfma_f32_16x16x32_bf16 v[20:23], v[176:179], v[200:203], v[20:23]
	v_mfma_f32_16x16x32_bf16 v[4:7], v[172:175], v[204:207], v[4:7]
	v_mfma_f32_16x16x32_bf16 v[4:7], v[176:179], v[208:211], v[4:7]
	v_mfma_f32_16x16x32_bf16 v[8:11], v[164:167], v[204:207], v[8:11]
	v_mfma_f32_16x16x32_bf16 v[8:11], v[168:171], v[208:211], v[8:11]
	s_barrier
	s_cmp_gt_u32 s64, 61
	s_cbranch_scc0 .LBB0_3159
	s_setprio 0
	s_and_b64 vcc, exec, s[46:47]
	s_cbranch_vccz .LBB0_3162
	s_barrier

; #define PG8_STAGE(bufoff, gbase, voff) do { _Pragma("unroll") for (int _i = 0; _i < 2; ++_i) \
;         __builtin_amdgcn_global_load_lds((const unsigned*)((const char*)(gbase) + (voff)[_i]), (PG8_LAS unsigned*)(lds + (bufoff) + ldsw + _i * 8192), 16, 0, 0); } while (0)
; #define PG8_LDA(dst, b, h) do { _Pragma("unroll") for (int m = 0; m < 4; ++m) _Pragma("unroll") for (int k = 0; k < 2; ++k) dst[m][k] = *(const PG8_LAS bf16x8*)(lds + PG8_SA(b, h) + aoff + m * 2048 + k * 1024); } while (0)
; #define PG8_LDB(dst, b, h) do { _Pragma("unroll") for (int n = 0; n < 2; ++n) _Pragma("unroll") for (int k = 0; k < 2; ++k) dst[n][k] = *(const PG8_LAS bf16x8*)(lds + PG8_SB(b, h) + boff + n * 2048 + k * 1024); } while (0)
; #define PG8_MMA(ai, bj, At, Bt) do { __builtin_amdgcn_s_setprio(1); _Pragma("unroll") for (int m = 0; m < 4; ++m) _Pragma("unroll") for (int n = 0; n < 2; ++n) _Pragma("unroll") for (int k = 0; k < 2; ++k) \
;         acc[ai][bj][m][n] = __builtin_amdgcn_mfma_f32_16x16x32_bf16(Bt[n][k], At[m][k], acc[ai][bj][m][n], 0, 0, 0); __builtin_amdgcn_s_setprio(0); } while (0)
; #define PG8_WAIT_V(n) asm volatile("s_waitcnt vmcnt(" #n ")" ::: "memory")
; #define PG8_BAR __builtin_amdgcn_s_barrier()
; template <class Epi, class Sched, bool ALIGN_EPI = false, bool SP2 = false>
; __device__ __forceinline__ void gemm_phase(PG8_LAS unsigned char* lds, const Gemm g, const Sched& S, const Epi& E) {
;     ...
;         for (int t = 0; t < nt; t += 2) {
;             const bool last = (t == nt - 2);
;             const char* a1 = cA + (size_t)(t + 1) * kstep;
;             const char* a2 = last ? nA : cA + (size_t)(t + 2) * kstep; const char* b2 = last ? nB : cB + (size_t)(t + 2) * kstep;
;             const char* a3 = a2 + kstep; const char* b3 = b2 + kstep;
;             if (last && has_next) S.a_ready(nxt);
;             if constexpr (SP2) {
;             PG8_LDB(B0, 0, 0); PG8_LDB(B1, 0, 1); PG8_SCHED; PG8_LDA(At, 0, 0); PG8_STAGE(PG8_SA(1, 1), a1 + hstep, voffA);
;             PG8_WAIT_V(8); PG8_WAIT_L(0); PG8_BAR; PG8_MMA(0, 0, At, B0); PG8_MMA(0, 1, At, B1); PG8_BAR; PG8_SCHED;
;             PG8_LDA(At, 0, 1); PG8_STAGE(PG8_SB(0, 0), b2, voffB); PG8_STAGE(PG8_SB(0, 1), b2 + hstep, voffB); PG8_STAGE(PG8_SA(0, 0), a2, voffA);
;             PG8_WAIT_V(8); PG8_WAIT_L(0); PG8_BAR; PG8_MMA(1, 0, At, B0); PG8_MMA(1, 1, At, B1); PG8_BAR; PG8_SCHED;
.LBB0_3627:
	s_waitcnt lgkmcnt(0)
	ds_read_b128 v[132:135], v162
	ds_read_b128 v[136:139], v162 offset:1024
	ds_read_b128 v[140:143], v162 offset:2048
	ds_read_b128 v[154:157], v162 offset:3072
	ds_read_b128 v[158:161], v162 offset:16384
	ds_read_b128 v[170:173], v162 offset:17408
	ds_read_b128 v[174:177], v162 offset:18432
	ds_read_b128 v[178:181], v162 offset:19456
	s_add_i32 m0, s92, 0xc000
	ds_read_b128 v[182:185], v169
	ds_read_b128 v[186:189], v169 offset:1024
	ds_read_b128 v[190:193], v169 offset:2048
	ds_read_b128 v[194:197], v169 offset:3072
	ds_read_b128 v[198:201], v169 offset:4096
	ds_read_b128 v[202:205], v169 offset:5120
	ds_read_b128 v[206:209], v169 offset:6144
	ds_read_b128 v[210:213], v169 offset:7168
	s_setprio 0
	s_add_i32 s72, s26, 2
	s_add_u32 s0, s24, 0x100
	s_addc_u32 s1, s25, 0
	s_add_i32 s73, 0, 0x10000
	s_cmp_eq_u32 s44, s26
	s_cselect_b32 s35, s79, s1
	s_cselect_b32 s34, s78, s0
	s_cselect_b32 s27, s81, s47
	s_cselect_b32 s26, s80, s45
	s_add_i32 vcc_lo, 0, 0x14000
	global_load_lds_dwordx4 v150, s[24:25]
	s_add_i32 m0, s92, 0xe000
	s_nop 0
	global_load_lds_dwordx4 v152, s[24:25]
	s_setprio 1
	s_waitcnt vmcnt(8)
	s_waitcnt lgkmcnt(0)
	s_barrier
	v_mfma_f32_16x16x32_bf16 v[128:131], v[132:135], v[182:185], v[128:131]
	v_mfma_f32_16x16x32_bf16 v[128:131], v[136:139], v[186:189], v[128:131]
	v_mfma_f32_16x16x32_bf16 v[124:127], v[140:143], v[182:185], v[124:127]
	v_mfma_f32_16x16x32_bf16 v[124:127], v[154:157], v[186:189], v[124:127]
	v_mfma_f32_16x16x32_bf16 v[116:119], v[140:143], v[190:193], v[116:119]
	v_mfma_f32_16x16x32_bf16 v[116:119], v[154:157], v[194:197], v[116:119]
	v_mfma_f32_16x16x32_bf16 v[120:123], v[132:135], v[190:193], v[120:123]
	v_mfma_f32_16x16x32_bf16 v[120:123], v[136:139], v[194:197], v[120:123]
	v_mfma_f32_16x16x32_bf16 v[112:115], v[132:135], v[198:201], v[112:115]
	v_mfma_f32_16x16x32_bf16 v[112:115], v[136:139], v[202:205], v[112:115]
	v_mfma_f32_16x16x32_bf16 v[108:111], v[140:143], v[198:201], v[108:111]
	v_mfma_f32_16x16x32_bf16 v[108:111], v[154:157], v[202:205], v[108:111]
	v_mfma_f32_16x16x32_bf16 v[100:103], v[140:143], v[206:209], v[100:103]
	v_mfma_f32_16x16x32_bf16 v[100:103], v[154:157], v[210:213], v[100:103]
	v_mfma_f32_16x16x32_bf16 v[104:107], v[132:135], v[206:209], v[104:107]
	v_mfma_f32_16x16x32_bf16 v[104:107], v[136:139], v[210:213], v[104:107]
	s_setprio 0
	s_setprio 1
	v_mfma_f32_16x16x32_bf16 v[96:99], v[158:161], v[182:185], v[96:99]
	v_mfma_f32_16x16x32_bf16 v[96:99], v[170:173], v[186:189], v[96:99]
	v_mfma_f32_16x16x32_bf16 v[92:95], v[174:177], v[182:185], v[92:95]
	v_mfma_f32_16x16x32_bf16 v[92:95], v[178:181], v[186:189], v[92:95]
	v_mfma_f32_16x16x32_bf16 v[84:87], v[174:177], v[190:193], v[84:87]
	v_mfma_f32_16x16x32_bf16 v[84:87], v[178:181], v[194:197], v[84:87]
	v_mfma_f32_16x16x32_bf16 v[88:91], v[158:161], v[190:193], v[88:91]
	v_mfma_f32_16x16x32_bf16 v[88:91], v[170:173], v[194:197], v[88:91]
	v_mfma_f32_16x16x32_bf16 v[80:83], v[158:161], v[198:201], v[80:83]
	v_mfma_f32_16x16x32_bf16 v[80:83], v[170:173], v[202:205], v[80:83]
	v_mfma_f32_16x16x32_bf16 v[76:79], v[174:177], v[198:201], v[76:79]
	v_mfma_f32_16x16x32_bf16 v[76:79], v[178:181], v[202:205], v[76:79]
	v_mfma_f32_16x16x32_bf16 v[68:71], v[174:177], v[206:209], v[68:71]
	v_mfma_f32_16x16x32_bf16 v[68:71], v[178:181], v[210:213], v[68:71]
	v_mfma_f32_16x16x32_bf16 v[72:75], v[158:161], v[206:209], v[72:75]
	v_mfma_f32_16x16x32_bf16 v[72:75], v[170:173], v[210:213], v[72:75]
	s_barrier
	ds_read_b128 v[182:185], v169 offset:16384
	ds_read_b128 v[186:189], v169 offset:17408
	ds_read_b128 v[190:193], v169 offset:18432
	ds_read_b128 v[194:197], v169 offset:19456
	ds_read_b128 v[198:201], v169 offset:20480
	ds_read_b128 v[202:205], v169 offset:21504
	ds_read_b128 v[206:209], v169 offset:22528
	ds_read_b128 v[210:213], v169 offset:23552
	s_setprio 0
	s_add_i32 s24, s73, s83
	s_mov_b32 m0, s24
	s_nop 0
	global_load_lds_dwordx4 v2, s[26:27]
	s_add_i32 m0, s24, 0x2000
	s_add_u32 s24, s26, 0x2b0000
	s_addc_u32 s25, s27, 0
	s_add_i32 s73, vcc_lo, s83
	global_load_lds_dwordx4 v148, s[26:27]
	s_mov_b32 m0, s73
	s_nop 0
	global_load_lds_dwordx4 v2, s[24:25]
	s_add_i32 m0, s73, 0x2000
	s_nop 0
	global_load_lds_dwordx4 v148, s[24:25]
	s_mov_b32 m0, s92
	s_nop 0
	global_load_lds_dwordx4 v144, s[34:35]
	s_mov_b32 m0, s93
	s_nop 0
	global_load_lds_dwordx4 v146, s[34:35]
	s_nop 0
	s_nop 0
	s_setprio 1
	s_waitcnt vmcnt(8)
	s_waitcnt lgkmcnt(0)
	s_barrier
	v_mfma_f32_16x16x32_bf16 v[64:67], v[132:135], v[182:185], v[64:67]
	v_mfma_f32_16x16x32_bf16 v[64:67], v[136:139], v[186:189], v[64:67]
	v_mfma_f32_16x16x32_bf16 v[60:63], v[140:143], v[182:185], v[60:63]
	v_mfma_f32_16x16x32_bf16 v[60:63], v[154:157], v[186:189], v[60:63]
	v_mfma_f32_16x16x32_bf16 v[52:55], v[140:143], v[190:193], v[52:55]
	v_mfma_f32_16x16x32_bf16 v[52:55], v[154:157], v[194:197], v[52:55]
	v_mfma_f32_16x16x32_bf16 v[56:59], v[132:135], v[190:193], v[56:59]
	v_mfma_f32_16x16x32_bf16 v[56:59], v[136:139], v[194:197], v[56:59]
	v_mfma_f32_16x16x32_bf16 v[48:51], v[132:135], v[198:201], v[48:51]
	v_mfma_f32_16x16x32_bf16 v[48:51], v[136:139], v[202:205], v[48:51]
	v_mfma_f32_16x16x32_bf16 v[44:47], v[140:143], v[198:201], v[44:47]
	v_mfma_f32_16x16x32_bf16 v[44:47], v[154:157], v[202:205], v[44:47]
	v_mfma_f32_16x16x32_bf16 v[36:39], v[140:143], v[206:209], v[36:39]
	v_mfma_f32_16x16x32_bf16 v[36:39], v[154:157], v[210:213], v[36:39]
	v_mfma_f32_16x16x32_bf16 v[40:43], v[132:135], v[206:209], v[40:43]
	v_mfma_f32_16x16x32_bf16 v[40:43], v[136:139], v[210:213], v[40:43]
	s_setprio 0
	s_setprio 1
	v_mfma_f32_16x16x32_bf16 v[32:35], v[158:161], v[182:185], v[32:35]
	v_mfma_f32_16x16x32_bf16 v[32:35], v[170:173], v[186:189], v[32:35]
	v_mfma_f32_16x16x32_bf16 v[28:31], v[174:177], v[182:185], v[28:31]
	v_mfma_f32_16x16x32_bf16 v[28:31], v[178:181], v[186:189], v[28:31]
	v_mfma_f32_16x16x32_bf16 v[20:23], v[174:177], v[190:193], v[20:23]
	v_mfma_f32_16x16x32_bf16 v[20:23], v[178:181], v[194:197], v[20:23]
	v_mfma_f32_16x16x32_bf16 v[24:27], v[158:161], v[190:193], v[24:27]
	v_mfma_f32_16x16x32_bf16 v[24:27], v[170:173], v[194:197], v[24:27]
	v_mfma_f32_16x16x32_bf16 v[16:19], v[158:161], v[198:201], v[16:19]
	v_mfma_f32_16x16x32_bf16 v[16:19], v[170:173], v[202:205], v[16:19]
	v_mfma_f32_16x16x32_bf16 v[12:15], v[174:177], v[198:201], v[12:15]
	v_mfma_f32_16x16x32_bf16 v[12:15], v[178:181], v[202:205], v[12:15]
	v_mfma_f32_16x16x32_bf16 v[4:7], v[174:177], v[206:209], v[4:7]
	v_mfma_f32_16x16x32_bf16 v[4:7], v[178:181], v[210:213], v[4:7]
	v_mfma_f32_16x16x32_bf16 v[8:11], v[158:161], v[206:209], v[8:11]
	v_mfma_f32_16x16x32_bf16 v[8:11], v[170:173], v[210:213], v[8:11]
	s_barrier
; #define PG8_STAGE(bufoff, gbase, voff) do { _Pragma("unroll") for (int _i = 0; _i < 2; ++_i) \
;         __builtin_amdgcn_global_load_lds((const unsigned*)((const char*)(gbase) + (voff)[_i]), (PG8_LAS unsigned*)(lds + (bufoff) + ldsw + _i * 8192), 16, 0, 0); } while (0)
; #define PG8_LDA(dst, b, h) do { _Pragma("unroll") for (int m = 0; m < 4; ++m) _Pragma("unroll") for (int k = 0; k < 2; ++k) dst[m][k] = *(const PG8_LAS bf16x8*)(lds + PG8_SA(b, h) + aoff + m * 2048 + k * 1024); } while (0)
; #define PG8_LDB(dst, b, h) do { _Pragma("unroll") for (int n = 0; n < 2; ++n) _Pragma("unroll") for (int k = 0; k < 2; ++k) dst[n][k] = *(const PG8_LAS bf16x8*)(lds + PG8_SB(b, h) + boff + n * 2048 + k * 1024); } while (0)
; #define PG8_MMA(ai, bj, At, Bt) do { __builtin_amdgcn_s_setprio(1); _Pragma("unroll") for (int m = 0; m < 4; ++m) _Pragma("unroll") for (int n = 0; n < 2; ++n) _Pragma("unroll") for (int k = 0; k < 2; ++k) \
;         acc[ai][bj][m][n] = __builtin_amdgcn_mfma_f32_16x16x32_bf16(Bt[n][k], At[m][k], acc[ai][bj][m][n], 0, 0, 0); __builtin_amdgcn_s_setprio(0); } while (0)
; #define PG8_WAIT_V(n) asm volatile("s_waitcnt vmcnt(" #n ")" ::: "memory")
; #define PG8_WAIT_L(n) asm volatile("s_waitcnt lgkmcnt(" #n ")" ::: "memory")
; #define PG8_BAR __builtin_amdgcn_s_barrier()
; #define PG8_SCHED __builtin_amdgcn_sched_barrier(0)
; template <class Epi, class Sched, bool ALIGN_EPI = false, bool SP2 = false>
; __device__ __forceinline__ void gemm_phase(PG8_LAS unsigned char* lds, const Gemm g, const Sched& S, const Epi& E) {
;     ...
;         for (int t = 0; t < nt; t += 2) {
;             const bool last = (t == nt - 2);
;             const char* a1 = cA + (size_t)(t + 1) * kstep;
;             const char* a2 = last ? nA : cA + (size_t)(t + 2) * kstep; const char* b2 = last ? nB : cB + (size_t)(t + 2) * kstep;
;     ...
;             PG8_LDB(B0, 1, 0); PG8_LDB(B1, 1, 1); PG8_SCHED; PG8_LDA(At, 1, 0); PG8_STAGE(PG8_SA(0, 1), a2 + hstep, voffA);
;             PG8_WAIT_V(8); PG8_WAIT_L(0); PG8_BAR; PG8_MMA(0, 0, At, B0); PG8_MMA(0, 1, At, B1); PG8_BAR; PG8_SCHED;
;             PG8_LDA(At, 1, 1); PG8_STAGE(PG8_SB(1, 0), b3, voffB); PG8_STAGE(PG8_SB(1, 1), b3 + hstep, voffB); PG8_STAGE(PG8_SA(1, 0), a3, voffA);
;             PG8_WAIT_V(8); PG8_WAIT_L(0); PG8_BAR; PG8_MMA(1, 0, At, B0); PG8_MMA(1, 1, At, B1); PG8_BAR; PG8_SCHED;
	ds_read_b128 v[132:135], v162 offset:32768
	ds_read_b128 v[136:139], v162 offset:33792
	ds_read_b128 v[140:143], v162 offset:34816
	ds_read_b128 v[154:157], v162 offset:35840
	ds_read_b128 v[158:161], v162 offset:49152
	ds_read_b128 v[170:173], v162 offset:50176
	ds_read_b128 v[174:177], v162 offset:51200
	ds_read_b128 v[178:181], v162 offset:52224
	s_add_u32 s24, s34, 0x2b0000
	s_addc_u32 s25, s35, 0
	s_mov_b32 m0, s94
	ds_read_b128 v[182:185], v169 offset:32768
	ds_read_b128 v[186:189], v169 offset:33792
	ds_read_b128 v[190:193], v169 offset:34816
	ds_read_b128 v[194:197], v169 offset:35840
	ds_read_b128 v[198:201], v169 offset:36864
	ds_read_b128 v[202:205], v169 offset:37888
	ds_read_b128 v[206:209], v169 offset:38912
	ds_read_b128 v[210:213], v169 offset:39936
	s_setprio 0
	s_add_i32 s73, 0, 0x18000
	s_add_i32 vcc_lo, 0, 0x1c000
	global_load_lds_dwordx4 v144, s[24:25]
	s_mov_b32 m0, s95
	s_nop 0
	global_load_lds_dwordx4 v146, s[24:25]
	s_setprio 1
	s_waitcnt vmcnt(8)
	s_waitcnt lgkmcnt(0)
	s_barrier
	v_mfma_f32_16x16x32_bf16 v[128:131], v[132:135], v[182:185], v[128:131]
	v_mfma_f32_16x16x32_bf16 v[128:131], v[136:139], v[186:189], v[128:131]
	v_mfma_f32_16x16x32_bf16 v[124:127], v[140:143], v[182:185], v[124:127]
	v_mfma_f32_16x16x32_bf16 v[124:127], v[154:157], v[186:189], v[124:127]
	v_mfma_f32_16x16x32_bf16 v[116:119], v[140:143], v[190:193], v[116:119]
	v_mfma_f32_16x16x32_bf16 v[116:119], v[154:157], v[194:197], v[116:119]
	v_mfma_f32_16x16x32_bf16 v[120:123], v[132:135], v[190:193], v[120:123]
	v_mfma_f32_16x16x32_bf16 v[120:123], v[136:139], v[194:197], v[120:123]
	v_mfma_f32_16x16x32_bf16 v[112:115], v[132:135], v[198:201], v[112:115]
	v_mfma_f32_16x16x32_bf16 v[112:115], v[136:139], v[202:205], v[112:115]
	v_mfma_f32_16x16x32_bf16 v[108:111], v[140:143], v[198:201], v[108:111]
	v_mfma_f32_16x16x32_bf16 v[108:111], v[154:157], v[202:205], v[108:111]
	v_mfma_f32_16x16x32_bf16 v[100:103], v[140:143], v[206:209], v[100:103]
	v_mfma_f32_16x16x32_bf16 v[100:103], v[154:157], v[210:213], v[100:103]
	v_mfma_f32_16x16x32_bf16 v[104:107], v[132:135], v[206:209], v[104:107]
	v_mfma_f32_16x16x32_bf16 v[104:107], v[136:139], v[210:213], v[104:107]
	s_setprio 0
	s_setprio 1
	v_mfma_f32_16x16x32_bf16 v[96:99], v[158:161], v[182:185], v[96:99]
	v_mfma_f32_16x16x32_bf16 v[96:99], v[170:173], v[186:189], v[96:99]
	v_mfma_f32_16x16x32_bf16 v[92:95], v[174:177], v[182:185], v[92:95]
	v_mfma_f32_16x16x32_bf16 v[92:95], v[178:181], v[186:189], v[92:95]
	v_mfma_f32_16x16x32_bf16 v[84:87], v[174:177], v[190:193], v[84:87]
	v_mfma_f32_16x16x32_bf16 v[84:87], v[178:181], v[194:197], v[84:87]
	v_mfma_f32_16x16x32_bf16 v[88:91], v[158:161], v[190:193], v[88:91]
	v_mfma_f32_16x16x32_bf16 v[88:91], v[170:173], v[194:197], v[88:91]
	v_mfma_f32_16x16x32_bf16 v[80:83], v[158:161], v[198:201], v[80:83]
	v_mfma_f32_16x16x32_bf16 v[80:83], v[170:173], v[202:205], v[80:83]
	v_mfma_f32_16x16x32_bf16 v[76:79], v[174:177], v[198:201], v[76:79]
	v_mfma_f32_16x16x32_bf16 v[76:79], v[178:181], v[202:205], v[76:79]
	v_mfma_f32_16x16x32_bf16 v[68:71], v[174:177], v[206:209], v[68:71]
	v_mfma_f32_16x16x32_bf16 v[68:71], v[178:181], v[210:213], v[68:71]
	v_mfma_f32_16x16x32_bf16 v[72:75], v[158:161], v[206:209], v[72:75]
	v_mfma_f32_16x16x32_bf16 v[72:75], v[170:173], v[210:213], v[72:75]
	s_barrier
	ds_read_b128 v[182:185], v169 offset:49152
	ds_read_b128 v[186:189], v169 offset:50176
	ds_read_b128 v[190:193], v169 offset:51200
	ds_read_b128 v[194:197], v169 offset:52224
	ds_read_b128 v[198:201], v169 offset:53248
	ds_read_b128 v[202:205], v169 offset:54272
	ds_read_b128 v[206:209], v169 offset:55296
	ds_read_b128 v[210:213], v169 offset:56320
	s_setprio 0
	s_add_i32 s24, s73, s83
	s_add_u32 s100, s26, 0x80
	s_addc_u32 s101, s27, 0
	s_mov_b32 m0, s24
	s_nop 0
	global_load_lds_dwordx4 v2, s[100:101]
	s_add_i32 m0, s24, 0x2000
	s_add_u32 s24, s26, 0x2b0080
	s_addc_u32 s25, s27, 0
	s_add_i32 s26, vcc_lo, s83
	global_load_lds_dwordx4 v148, s[100:101]
	s_mov_b32 m0, s26
	s_nop 0
	global_load_lds_dwordx4 v2, s[24:25]
	s_add_i32 m0, s26, 0x2000
	s_nop 0
	global_load_lds_dwordx4 v148, s[24:25]
	s_add_u32 s100, s34, 0x80
	s_addc_u32 s101, s35, 0
	s_mov_b32 m0, s65
	s_nop 0
	global_load_lds_dwordx4 v144, s[100:101]
	s_mov_b32 m0, s4
	s_nop 0
	global_load_lds_dwordx4 v146, s[100:101]
	s_nop 0
	s_nop 0
	s_setprio 1
	s_waitcnt vmcnt(8)
	s_waitcnt lgkmcnt(0)
	s_barrier
	v_mfma_f32_16x16x32_bf16 v[64:67], v[132:135], v[182:185], v[64:67]
	v_mfma_f32_16x16x32_bf16 v[64:67], v[136:139], v[186:189], v[64:67]
	v_mfma_f32_16x16x32_bf16 v[60:63], v[140:143], v[182:185], v[60:63]
	v_mfma_f32_16x16x32_bf16 v[60:63], v[154:157], v[186:189], v[60:63]
	v_mfma_f32_16x16x32_bf16 v[52:55], v[140:143], v[190:193], v[52:55]
	v_mfma_f32_16x16x32_bf16 v[52:55], v[154:157], v[194:197], v[52:55]
	v_mfma_f32_16x16x32_bf16 v[56:59], v[132:135], v[190:193], v[56:59]
	v_mfma_f32_16x16x32_bf16 v[56:59], v[136:139], v[194:197], v[56:59]
	v_mfma_f32_16x16x32_bf16 v[48:51], v[132:135], v[198:201], v[48:51]
	v_mfma_f32_16x16x32_bf16 v[48:51], v[136:139], v[202:205], v[48:51]
	v_mfma_f32_16x16x32_bf16 v[44:47], v[140:143], v[198:201], v[44:47]
	v_mfma_f32_16x16x32_bf16 v[44:47], v[154:157], v[202:205], v[44:47]
	v_mfma_f32_16x16x32_bf16 v[36:39], v[140:143], v[206:209], v[36:39]
	v_mfma_f32_16x16x32_bf16 v[36:39], v[154:157], v[210:213], v[36:39]
	v_mfma_f32_16x16x32_bf16 v[40:43], v[132:135], v[206:209], v[40:43]
	v_mfma_f32_16x16x32_bf16 v[40:43], v[136:139], v[210:213], v[40:43]
	s_setprio 0
	s_setprio 1
	s_add_u32 s45, s45, 0x100
	s_addc_u32 s47, s47, 0
	s_mov_b64 s[24:25], s[0:1]
	s_mov_b32 s26, s72
	s_nop 0
	v_mfma_f32_16x16x32_bf16 v[32:35], v[158:161], v[182:185], v[32:35]
	v_mfma_f32_16x16x32_bf16 v[32:35], v[170:173], v[186:189], v[32:35]
	v_mfma_f32_16x16x32_bf16 v[28:31], v[174:177], v[182:185], v[28:31]
	v_mfma_f32_16x16x32_bf16 v[28:31], v[178:181], v[186:189], v[28:31]
	v_mfma_f32_16x16x32_bf16 v[20:23], v[174:177], v[190:193], v[20:23]
	v_mfma_f32_16x16x32_bf16 v[20:23], v[178:181], v[194:197], v[20:23]
	v_mfma_f32_16x16x32_bf16 v[24:27], v[158:161], v[190:193], v[24:27]
	v_mfma_f32_16x16x32_bf16 v[24:27], v[170:173], v[194:197], v[24:27]
	v_mfma_f32_16x16x32_bf16 v[16:19], v[158:161], v[198:201], v[16:19]
	v_mfma_f32_16x16x32_bf16 v[16:19], v[170:173], v[202:205], v[16:19]
	v_mfma_f32_16x16x32_bf16 v[12:15], v[174:177], v[198:201], v[12:15]
	v_mfma_f32_16x16x32_bf16 v[12:15], v[178:181], v[202:205], v[12:15]
	v_mfma_f32_16x16x32_bf16 v[4:7], v[174:177], v[206:209], v[4:7]
	v_mfma_f32_16x16x32_bf16 v[4:7], v[178:181], v[210:213], v[4:7]
	v_mfma_f32_16x16x32_bf16 v[8:11], v[158:161], v[206:209], v[8:11]
	v_mfma_f32_16x16x32_bf16 v[8:11], v[170:173], v[210:213], v[8:11]
	s_barrier
	s_cmp_ge_i32 s72, s46
	s_cbranch_scc0 .LBB0_3627
	s_setprio 0
	s_and_b64 vcc, exec, s[50:51]
	s_cbranch_vccz .LBB0_3630
	s_barrier
